# plus: removed dead zero-initialisations before full-lane DPP moves (FFN-up conv epilogue, prep transposes), hazard nops re-derived
# speedup vs baseline: 1.0070x; 1.0038x over previous
; __device__ __forceinline__ void phase_wconv_rest(const Params& p, LAS unsigned char* lds, int gw, int NGW) {
;     ...
;     for (int it = gw; it < NITEMS; it += NGW) {
;         int r = it;
;         if (r < I_A) { transpose_item<false, false>(p.w_a, WA, D_MODEL, (bf16*)(ws + WS_WAT), 0, scr, r, lane); continue; } r -= I_A;
;         if (r < I_A) { transpose_item<false, false>(p.w_b, WA, D_MODEL, (bf16*)(ws + WS_WBT), 0, scr, r, lane); continue; } r -= I_A;
;         if (r < I_O) { transpose_item<false, false>(p.w_o, D_MODEL, D_MODEL, (bf16*)(ws + WS_WOT), 0, scr, r, lane); continue; } r -= I_O;
;         if (r < I_1) { transpose_item<false, true>(p.w1, D_MODEL, FFN, (bf16*)(ws + WS_W13T), 0, scr, r, lane, sh2, b2); continue; } r -= I_1;
;         if (r < I_1) { transpose_item<false, true>(p.w3, D_MODEL, FFN, (bf16*)(ws + WS_W13T), 128, scr, r, lane, sh2, b2); continue; } r -= I_1;
;         transpose_item<false, false>(p.w2, FFN, D_MODEL, (bf16*)(ws + WS_W2T), 0, scr, r, lane);
; __global__ void __launch_bounds__(NTHREADS, 2) mega_fwd(Params p_in) {
;     ...
;       const int nfree = nb - CTX_UNITS;
;       if (nfree >= 64) { if (bx >= CTX_UNITS) phase_wconv_rest(p, lds, (bx - CTX_UNITS) * 8 + wave_id, nfree * 8); }
.LBB0_240:
	s_cmpk_lt_i32 s2, 0x50
	s_cbranch_scc1 .LBB0_268
	s_lshl_b32 s4, s2, 3
	s_add_i32 s4, s4, s3
	s_add_i32 s20, s4, 0xfffffd80
	s_movk_i32 s98, 0x51ff
	s_cmpk_lg_i32 s33, 0x100
	s_cselect_b32 s98, s98, 0x3fff
	s_cmp_gt_i32 s20, s98
	v_mbcnt_lo_u32_b32 v0, -1, 0
	v_mbcnt_hi_u32_b32 v0, -1, v0
	s_cbranch_scc1 .LBB0_268
	s_add_i32 s21, s46, 0xfffffd80
	s_waitcnt lgkmcnt(0)
	s_add_u32 s6, s22, 0x106000
	s_addc_u32 s7, s23, 0
	s_add_u32 s16, s22, 0x18000
	s_addc_u32 s17, s23, 0
	s_lshl_b32 s3, s3, 14
	v_ashrrev_i32_e32 v34, 5, v0
	v_lshlrev_b32_e32 v1, 2, v0
	s_movk_i32 s4, 0x84
	s_add_i32 s3, s3, 0
	v_and_b32_e32 v22, 0x7c, v1
	v_mul_lo_u32 v1, v34, s4
	v_add3_u32 v26, s3, v22, v1
	v_lshlrev_b32_e32 v1, 3, v0
	v_and_b32_e32 v1, 56, v1
	v_ashrrev_i32_e32 v35, 3, v0
	v_lshlrev_b32_e32 v12, 1, v1
	v_mov_b32_e32 v13, 0
	v_mul_u32_u24_e32 v4, 0x84, v1
	v_lshl_add_u64 v[10:11], s[22:23], 0, v[12:13]
	v_lshlrev_b32_e32 v1, 2, v35
	s_mov_b64 s[22:23], 0x142000
	v_add3_u32 v27, s3, v4, v1
	v_lshl_add_u64 v[4:5], v[10:11], 0, s[22:23]
	s_mov_b64 s[22:23], 0x4b42000
	v_lshl_add_u64 v[6:7], v[10:11], 0, s[22:23]
	s_mov_b64 s[22:23], 0x4742000
	s_mov_b64 s[4:5], 0x2d42000
	v_ashrrev_i32_e32 v1, 31, v0
	v_lshl_add_u64 v[8:9], v[10:11], 0, s[22:23]
	s_mov_b64 s[22:23], 0x4342000
	v_mov_b32_e32 v23, v13
	s_mov_b32 s19, 0
	v_lshl_add_u64 v[2:3], v[10:11], 0, s[4:5]
	v_add_u32_e32 v36, 8, v35
	v_add_u32_e32 v37, 16, v35
	v_add_u32_e32 v38, 24, v35
	v_cmp_gt_i32_e64 s[4:5], 32, v0
	v_lshl_add_u64 v[10:11], v[10:11], 0, s[22:23]
	v_lshl_add_u64 v[12:13], s[42:43], 0, v[22:23]
	v_lshl_add_u64 v[14:15], s[40:41], 0, v[22:23]
	v_lshl_add_u64 v[16:17], s[14:15], 0, v[22:23]
	v_lshl_add_u64 v[18:19], s[12:13], 0, v[22:23]
	v_lshl_add_u64 v[20:21], s[10:11], 0, v[22:23]
	v_lshl_add_u64 v[22:23], s[8:9], 0, v[22:23]
	v_lshl_add_u64 v[24:25], v[0:1], 2, s[16:17]
	s_lshl_b32 s3, s20, 5
	s_lshl_b32 s12, s21, 5
	s_mov_b32 s13, 0xc000
	s_mov_b32 s14, 0x18000
	s_mov_b32 s15, 0x24000
	s_movk_i32 s22, 0x2c00
	s_movk_i32 s23, 0x5800
	v_add_u32_e32 v39, 0x4000, v26
	v_add_u32_e32 v40, 0x4400, v26
	v_add_u32_e32 v41, 0x4800, v26
	v_add_u32_e32 v42, 0x4c00, v26
	v_add_u32_e32 v43, 0x5000, v26
	v_add_u32_e32 v44, 0x5400, v26
	v_add_u32_e32 v45, 0x5800, v26
	v_add_u32_e32 v46, 0x5c00, v26
	v_add_u32_e32 v47, 0x4000, v27
	s_branch .LBB0_244
.LBB0_243:
	s_add_i32 s20, s20, s21
	s_add_i32 s3, s3, s12
	s_cmp_gt_i32 s20, s98
	s_cbranch_scc1 .LBB0_268

; __device__ __forceinline__ void quad_transpose4(unsigned (&a)[4], const int r) {
;     const bool o1 = (r & 1) != 0, o2 = (r & 2) != 0;
;     const unsigned sl = o1 ? a[0] : a[1], sh = o1 ? a[2] : a[3];
;     const unsigned rl = (unsigned)__builtin_amdgcn_update_dpp(0, (int)sl, 0xB1, 0xf, 0xf, false), rh = (unsigned)__builtin_amdgcn_update_dpp(0, (int)sh, 0xB1, 0xf, 0xf, false);
;     const unsigned c0 = o1 ? rl : a[0], c1 = o1 ? a[1] : rl, c2 = o1 ? rh : a[2], c3 = o1 ? a[3] : rh;
;     const unsigned tl = o2 ? c0 : c2, th = o2 ? c1 : c3;
;     const unsigned vl = (unsigned)__builtin_amdgcn_update_dpp(0, (int)tl, 0x4E, 0xf, 0xf, false), vh = (unsigned)__builtin_amdgcn_update_dpp(0, (int)th, 0x4E, 0xf, 0xf, false);
;     a[0] = o2 ? vl : c0; a[1] = o2 ? vh : c1; a[2] = o2 ? c2 : vl; a[3] = o2 ? c3 : vh;
.LBB0_339:
	v_and_b32_e32 v26, 1, v30
	v_cmp_eq_u32_e32 vcc, 0, v26
	v_cmp_gt_u32_e64 s[4:5], 2, v17
	s_waitcnt vmcnt(3)
	v_cndmask_b32_e32 v26, v0, v1, vcc
	v_cndmask_b32_e32 v27, v2, v3, vcc
	s_nop 0
	v_mov_b32_dpp v28, v26 quad_perm:[1,0,3,2] row_mask:0xf bank_mask:0xf
	v_mov_b32_e32 v36, 0
	v_mov_b32_dpp v26, v27 quad_perm:[1,0,3,2] row_mask:0xf bank_mask:0xf
	v_cndmask_b32_e32 v27, v28, v0, vcc
	v_cndmask_b32_e32 v29, v26, v2, vcc
	v_cndmask_b32_e32 v28, v1, v28, vcc
	v_cndmask_b32_e32 v26, v3, v26, vcc
	v_cndmask_b32_e64 v32, v27, v29, s[4:5]
	v_cndmask_b32_e64 v33, v28, v26, s[4:5]
	v_mov_b32_e32 v37, 0
	v_mov_b32_dpp v34, v32 quad_perm:[2,3,0,1] row_mask:0xf bank_mask:0xf
	v_cndmask_b32_e64 v47, v29, v34, s[4:5]
	v_and_b32_e32 v29, 0xffff, v19
	v_mov_b32_dpp v32, v33 quad_perm:[2,3,0,1] row_mask:0xf bank_mask:0xf
	v_cndmask_b32_e64 v46, v32, v28, s[4:5]
	v_cndmask_b32_e64 v48, v26, v32, s[4:5]
	v_and_b32_e32 v26, 0xffff, v18
	v_lshrrev_b32_e32 v28, 16, v18
	v_lshrrev_b32_e32 v32, 16, v19
	v_cndmask_b32_e32 v33, v26, v28, vcc
	v_cndmask_b32_e64 v27, v34, v27, s[4:5]
	v_cndmask_b32_e32 v34, v29, v32, vcc
	v_mov_b32_dpp v35, v33 quad_perm:[1,0,3,2] row_mask:0xf bank_mask:0xf
	v_cndmask_b32_e32 v26, v35, v26, vcc
	v_cndmask_b32_e32 v28, v28, v35, vcc
	v_mov_b32_dpp v33, v34 quad_perm:[1,0,3,2] row_mask:0xf bank_mask:0xf
	v_cndmask_b32_e32 v29, v33, v29, vcc
	v_cndmask_b32_e32 v32, v32, v33, vcc
	v_cndmask_b32_e64 v33, v26, v29, s[4:5]
	v_cndmask_b32_e64 v34, v28, v32, s[4:5]
	s_nop 0
	v_mov_b32_dpp v35, v33 quad_perm:[2,3,0,1] row_mask:0xf bank_mask:0xf
	v_cndmask_b32_e64 v49, v35, v26, s[4:5]
	v_cndmask_b32_e64 v51, v29, v35, s[4:5]
	v_mov_b32_dpp v33, v34 quad_perm:[2,3,0,1] row_mask:0xf bank_mask:0xf
	s_waitcnt vmcnt(2)
	v_cndmask_b32_e32 v26, v4, v5, vcc
	v_cndmask_b32_e64 v50, v33, v28, s[4:5]
	v_cndmask_b32_e32 v28, v6, v7, vcc
	v_mov_b32_dpp v29, v26 quad_perm:[1,0,3,2] row_mask:0xf bank_mask:0xf
	v_cndmask_b32_e64 v52, v32, v33, s[4:5]
	v_mov_b32_dpp v26, v28 quad_perm:[1,0,3,2] row_mask:0xf bank_mask:0xf
	v_cndmask_b32_e32 v28, v29, v4, vcc
	v_cndmask_b32_e32 v32, v26, v6, vcc
	v_cndmask_b32_e32 v29, v5, v29, vcc
	v_cndmask_b32_e32 v26, v7, v26, vcc
	v_cndmask_b32_e64 v33, v28, v32, s[4:5]
	v_cndmask_b32_e64 v34, v29, v26, s[4:5]
	s_nop 0
	v_mov_b32_dpp v35, v33 quad_perm:[2,3,0,1] row_mask:0xf bank_mask:0xf
	v_cndmask_b32_e64 v53, v35, v28, s[4:5]
	v_lshrrev_b32_e32 v28, 16, v20
	v_mov_b32_dpp v33, v34 quad_perm:[2,3,0,1] row_mask:0xf bank_mask:0xf
	v_cndmask_b32_e64 v56, v26, v33, s[4:5]
	v_and_b32_e32 v26, 0xffff, v20
	v_cndmask_b32_e64 v54, v33, v29, s[4:5]
	v_cndmask_b32_e64 v55, v32, v35, s[4:5]
	v_and_b32_e32 v29, 0xffff, v21
	v_lshrrev_b32_e32 v32, 16, v21
	v_cndmask_b32_e32 v33, v26, v28, vcc
	v_cndmask_b32_e32 v34, v29, v32, vcc
	s_nop 0
	v_mov_b32_dpp v35, v33 quad_perm:[1,0,3,2] row_mask:0xf bank_mask:0xf
	v_cndmask_b32_e32 v26, v35, v26, vcc
	v_cndmask_b32_e32 v28, v28, v35, vcc
	v_mov_b32_dpp v33, v34 quad_perm:[1,0,3,2] row_mask:0xf bank_mask:0xf
	v_cndmask_b32_e32 v29, v33, v29, vcc
	v_cndmask_b32_e32 v32, v32, v33, vcc
	v_cndmask_b32_e64 v33, v26, v29, s[4:5]
	v_cndmask_b32_e64 v34, v28, v32, s[4:5]
	s_nop 0
	v_mov_b32_dpp v35, v33 quad_perm:[2,3,0,1] row_mask:0xf bank_mask:0xf
	v_cndmask_b32_e64 v57, v35, v26, s[4:5]
	v_cndmask_b32_e64 v59, v29, v35, s[4:5]
	v_mov_b32_dpp v33, v34 quad_perm:[2,3,0,1] row_mask:0xf bank_mask:0xf
	s_waitcnt vmcnt(1)
	v_cndmask_b32_e32 v26, v8, v9, vcc
	v_cndmask_b32_e64 v58, v33, v28, s[4:5]
	v_cndmask_b32_e32 v28, v10, v11, vcc
	v_mov_b32_dpp v29, v26 quad_perm:[1,0,3,2] row_mask:0xf bank_mask:0xf
	v_cndmask_b32_e64 v60, v32, v33, s[4:5]
	v_mov_b32_dpp v26, v28 quad_perm:[1,0,3,2] row_mask:0xf bank_mask:0xf
	v_cndmask_b32_e32 v28, v29, v8, vcc
	v_cndmask_b32_e32 v32, v26, v10, vcc
	v_cndmask_b32_e32 v29, v9, v29, vcc
	v_cndmask_b32_e32 v26, v11, v26, vcc
	v_cndmask_b32_e64 v33, v28, v32, s[4:5]
	v_cndmask_b32_e64 v34, v29, v26, s[4:5]
	s_nop 0
	v_mov_b32_dpp v35, v33 quad_perm:[2,3,0,1] row_mask:0xf bank_mask:0xf
	v_cndmask_b32_e64 v61, v35, v28, s[4:5]
	v_lshrrev_b32_e32 v28, 16, v22
	v_mov_b32_dpp v33, v34 quad_perm:[2,3,0,1] row_mask:0xf bank_mask:0xf
	v_cndmask_b32_e64 v64, v26, v33, s[4:5]
	v_and_b32_e32 v26, 0xffff, v22
	v_cndmask_b32_e64 v62, v33, v29, s[4:5]
	v_cndmask_b32_e64 v63, v32, v35, s[4:5]
	v_and_b32_e32 v29, 0xffff, v23
	v_lshrrev_b32_e32 v32, 16, v23
	v_cndmask_b32_e32 v33, v26, v28, vcc
	v_cndmask_b32_e32 v34, v29, v32, vcc
	s_nop 0
	v_mov_b32_dpp v35, v33 quad_perm:[1,0,3,2] row_mask:0xf bank_mask:0xf
	v_cndmask_b32_e32 v26, v35, v26, vcc
	v_cndmask_b32_e32 v28, v28, v35, vcc
	v_mov_b32_dpp v33, v34 quad_perm:[1,0,3,2] row_mask:0xf bank_mask:0xf
	v_cndmask_b32_e32 v29, v33, v29, vcc
	v_cndmask_b32_e32 v32, v32, v33, vcc
	v_cndmask_b32_e64 v33, v26, v29, s[4:5]
	v_cndmask_b32_e64 v34, v28, v32, s[4:5]
	s_nop 0
	v_mov_b32_dpp v35, v33 quad_perm:[2,3,0,1] row_mask:0xf bank_mask:0xf
	v_cndmask_b32_e64 v65, v35, v26, s[4:5]
	v_cndmask_b32_e64 v67, v29, v35, s[4:5]
	v_mov_b32_dpp v33, v34 quad_perm:[2,3,0,1] row_mask:0xf bank_mask:0xf
	s_waitcnt vmcnt(0)
	v_cndmask_b32_e32 v26, v12, v13, vcc
	v_cndmask_b32_e64 v66, v33, v28, s[4:5]
	v_cndmask_b32_e32 v28, v14, v15, vcc
	v_mov_b32_dpp v29, v26 quad_perm:[1,0,3,2] row_mask:0xf bank_mask:0xf
	v_cndmask_b32_e64 v68, v32, v33, s[4:5]
	v_mov_b32_dpp v26, v28 quad_perm:[1,0,3,2] row_mask:0xf bank_mask:0xf
	v_cndmask_b32_e32 v28, v29, v12, vcc
	v_cndmask_b32_e32 v29, v13, v29, vcc
	v_cndmask_b32_e32 v32, v26, v14, vcc
	v_cndmask_b32_e32 v33, v15, v26, vcc
	v_cndmask_b32_e64 v26, v28, v32, s[4:5]
	v_cndmask_b32_e64 v34, v29, v33, s[4:5]
	s_nop 0
	v_mov_b32_dpp v35, v26 quad_perm:[2,3,0,1] row_mask:0xf bank_mask:0xf
	v_mov_b32_dpp v36, v34 quad_perm:[2,3,0,1] row_mask:0xf bank_mask:0xf
	v_cndmask_b32_e64 v70, v36, v29, s[4:5]
	v_cndmask_b32_e64 v26, v32, v35, s[4:5]
	v_and_b32_e32 v29, 0xffff, v24
	v_lshrrev_b32_e32 v32, 16, v24
	v_cndmask_b32_e64 v69, v35, v28, s[4:5]
	v_cndmask_b32_e64 v28, v33, v36, s[4:5]
	v_and_b32_e32 v33, 0xffff, v25
	v_lshrrev_b32_e32 v34, 16, v25
	v_cndmask_b32_e32 v35, v29, v32, vcc
	v_cndmask_b32_e32 v36, v33, v34, vcc
	s_nop 0
	v_mov_b32_dpp v37, v35 quad_perm:[1,0,3,2] row_mask:0xf bank_mask:0xf
	v_cndmask_b32_e32 v29, v37, v29, vcc
	v_cndmask_b32_e32 v32, v32, v37, vcc
	v_mov_b32_dpp v35, v36 quad_perm:[1,0,3,2] row_mask:0xf bank_mask:0xf
	v_cndmask_b32_e32 v33, v35, v33, vcc
	v_cndmask_b32_e32 v34, v34, v35, vcc
	v_cndmask_b32_e64 v35, v29, v33, s[4:5]
	v_cndmask_b32_e64 v36, v32, v34, s[4:5]
	s_nop 0
	s_nop 0
	v_mov_b32_dpp v31, v36 quad_perm:[2,3,0,1] row_mask:0xf bank_mask:0xf
	v_mov_b32_dpp v37, v35 quad_perm:[2,3,0,1] row_mask:0xf bank_mask:0xf
	v_cndmask_b32_e64 v81, v37, v29, s[4:5]
	v_cndmask_b32_e64 v82, v31, v32, s[4:5]
	v_cndmask_b32_e64 v84, v33, v37, s[4:5]
	v_cndmask_b32_e64 v87, v34, v31, s[4:5]
	s_andn2_b64 vcc, exec, s[6:7]
	s_cbranch_vccnz .LBB0_382

; #define ATT_BAR() do { asm volatile("s_waitcnt lgkmcnt(0)" ::: "memory"); __builtin_amdgcn_s_barrier(); asm volatile("" ::: "memory"); } while (0)
; __device__ __forceinline__ void hgrn_prep(const Params& p, LAS unsigned char* lds, int vb, int nb) {
;     ...
;         float ecum[16]; float e1r = 1.0f;
; #pragma unroll
;         for (int i = 0; i < 16; ++i) { e1r *= lf[i]; ecum[i] = e1r; }
;         const float run = __logf(e1r);
;         Tl[J * 128 + k] = run;
;         ATT_BAR();
;         const float T0 = Tl[k], T1 = Tl[128 + k], T2 = Tl[256 + k], T3 = Tl[384 + k];
;         const float bJ = (J > 0 ? T0 : 0.f) + (J > 1 ? T1 : 0.f) + (J > 2 ? T2 : 0.f);
;         const float tail = (J < 1 ? T1 : 0.f) + (J < 2 ? T2 : 0.f) + (J < 3 ? T3 : 0.f);
;         const float eb = __expf(bJ), et = __expf(tail), eT = e1r;
;         const float x2 = (J == 3) ? __expf(T2) : __expf(T1);
;         float qh[16], kh[16];
; #pragma unroll
;         for (int i = 0; i < 16; ++i) { const float e1 = ecum[i]; const float r1 = __builtin_amdgcn_rcpf(e1); const float kk = 1.0f - lf[i];
;             qh[i] = __builtin_bit_cast(float, qv[i] << 16) * e1; kh[i] = kk * r1; }
.LBB0_342:
	v_rcp_f32_e32 v30, v27
	v_mul_f32_e32 v29, v27, v46
	v_sub_f32_e32 v106, 1.0, v27
	v_mul_f32_e32 v38, v29, v47
	v_mul_f32_e32 v30, v30, v106
	v_rcp_f32_e32 v106, v29
	v_lshlrev_b32_e32 v108, 16, v50
	v_mul_f32_e32 v118, v29, v108
	v_rcp_f32_e32 v29, v38
	v_lshlrev_b32_e32 v107, 16, v49
	v_mul_f32_e32 v117, v27, v107
	v_sub_f32_e32 v107, 1.0, v46
	v_mul_f32_e32 v39, v38, v48
	v_mul_f32_e32 v106, v107, v106
	v_sub_f32_e32 v107, 1.0, v47
	v_mul_f32_e32 v107, v107, v29
	v_rcp_f32_e32 v29, v39
	v_lshlrev_b32_e32 v108, 16, v51
	v_mul_f32_e32 v40, v39, v53
	v_mul_f32_e32 v119, v38, v108
	v_sub_f32_e32 v38, 1.0, v48
	v_lshlrev_b32_e32 v108, 16, v52
	v_mul_f32_e32 v120, v39, v108
	v_mul_f32_e32 v108, v38, v29
	v_rcp_f32_e32 v29, v40
	v_mul_f32_e32 v41, v40, v54
	v_sub_f32_e32 v38, 1.0, v53
	v_mul_f32_e32 v42, v41, v55
	v_mul_f32_e32 v109, v38, v29
	v_rcp_f32_e32 v29, v41
	v_sub_f32_e32 v38, 1.0, v54
	v_mul_f32_e32 v43, v42, v56
	v_mul_f32_e32 v44, v43, v61
	v_mul_f32_e32 v110, v38, v29
	v_rcp_f32_e32 v29, v42
	v_sub_f32_e32 v38, 1.0, v55
	v_mul_f32_e32 v45, v44, v62
	v_lshlrev_b32_e32 v39, 16, v57
	v_mul_f32_e32 v111, v38, v29
	v_rcp_f32_e32 v29, v43
	v_sub_f32_e32 v38, 1.0, v56
	v_mul_f32_e32 v121, v40, v39
	v_lshlrev_b32_e32 v39, 16, v58
	v_mul_f32_e32 v113, v38, v29
	v_rcp_f32_e32 v29, v44
	v_sub_f32_e32 v38, 1.0, v61
	v_mul_f32_e32 v115, v45, v63
	v_mul_f32_e32 v123, v41, v39
	v_mul_f32_e32 v112, v38, v29
	v_rcp_f32_e32 v29, v45
	v_lshlrev_b32_e32 v39, 16, v59
	v_sub_f32_e32 v38, 1.0, v62
	v_mul_f32_e32 v124, v42, v39
	v_lshlrev_b32_e32 v39, 16, v60
	v_mul_f32_e32 v114, v38, v29
	v_rcp_f32_e32 v29, v115
	v_mul_f32_e32 v126, v43, v39
	v_lshlrev_b32_e32 v39, 16, v65
	v_mul_f32_e32 v125, v44, v39
	v_lshlrev_b32_e32 v39, 16, v66
	v_mul_f32_e32 v116, v115, v64
	v_mul_f32_e32 v127, v45, v39
	v_sub_f32_e32 v38, 1.0, v63
	v_lshlrev_b32_e32 v39, 16, v67
	v_mul_f32_e32 v128, v115, v39
	v_mul_f32_e32 v115, v38, v29
	v_rcp_f32_e32 v29, v116
	v_mul_f32_e32 v122, v116, v69
	v_mul_f32_e32 v36, v122, v70
	v_sub_f32_e32 v38, 1.0, v64
	v_lshlrev_b32_e32 v39, 16, v68
	v_pk_mul_f32 v[40:41], v[36:37], v[26:27] op_sel_hi:[1,0]
	v_mul_f32_e32 v129, v116, v39
	v_mul_f32_e32 v116, v38, v29
	v_rcp_f32_e32 v29, v40
	v_lshlrev_b32_e32 v38, 16, v81
	v_mul_f32_e32 v130, v122, v38
	v_pk_add_f32 v[38:39], v[26:27], s[2:3] op_sel_hi:[0,1] neg_lo:[1,0] neg_hi:[1,0]
	s_nop 0
	v_mov_b32_e32 v41, v39
	v_pk_mul_f32 v[38:39], v[40:41], v[28:29]
	v_rcp_f32_e32 v42, v122
	v_cmp_gt_f32_e32 vcc, s83, v38
	v_sub_f32_e32 v43, 1.0, v69
	v_rcp_f32_e32 v44, v36
	v_cndmask_b32_e64 v29, 0, 32, vcc
	v_ldexp_f32 v29, v38, v29
	v_log_f32_e32 v29, v29
	v_mul_f32_e32 v122, v43, v42
	v_cvt_pk_bf16_f32 v135, v119, v120
	v_cvt_pk_bf16_f32 v136, v121, v123
	v_mul_f32_e32 v41, 0x3f317217, v29
	v_fma_f32 v41, v29, s84, -v41
	v_fmac_f32_e32 v41, 0x3377d1cf, v29
	v_fmac_f32_e32 v41, 0x3f317217, v29
	v_cmp_lt_f32_e64 s[36:37], |v29|, s85
	v_cvt_pk_bf16_f32 v137, v124, v126
	v_cvt_pk_bf16_f32 v138, v125, v127
	v_cndmask_b32_e64 v29, v29, v41, s[36:37]
	v_cndmask_b32_e32 v41, 0, v97, vcc
	v_sub_f32_e32 v29, v29, v41
	ds_write_b32 v72, v29
	s_waitcnt lgkmcnt(0)
	s_barrier
; #define LAS __attribute__((address_space(3)))
; __device__ __forceinline__ void hgrn_prep(const Params& p, LAS unsigned char* lds, int vb, int nb) {
;     ...
;         const float T0 = Tl[k], T1 = Tl[128 + k], T2 = Tl[256 + k], T3 = Tl[384 + k];
;         const float bJ = (J > 0 ? T0 : 0.f) + (J > 1 ? T1 : 0.f) + (J > 2 ? T2 : 0.f);
;         const float tail = (J < 1 ? T1 : 0.f) + (J < 2 ? T2 : 0.f) + (J < 3 ? T3 : 0.f);
;         const float eb = __expf(bJ), et = __expf(tail), eT = e1r;
;         const float x2 = (J == 3) ? __expf(T2) : __expf(T1);
;         float qh[16], kh[16];
; #pragma unroll
;         for (int i = 0; i < 16; ++i) { const float e1 = ecum[i]; const float r1 = __builtin_amdgcn_rcpf(e1); const float kk = 1.0f - lf[i];
;             qh[i] = __builtin_bit_cast(float, qv[i] << 16) * e1; kh[i] = kk * r1; }
;         {
;             LAS unsigned char* rowp = lds + k * HP + 32 * J;
;             u32x4 w0, w1;
;     ...
;             HG_WRITE(rowp + H_QH, qh[i]);
;             HG_WRITE(rowp + H_KH, kh[i]);
;             HG_WRITE(rowp + H_KE, kh[i] * eT);
;             HG_WRITE(rowp + H_QD, qh[i] * eb);
;             HG_WRITE(rowp + H_KD, kh[i] * (eT * et));
;             if (J == 3) { HG_WRITE(lds + H_Q2 + k * HP2, qh[i] * x2); }
;             if (J == 0) { HG_WRITE(lds + H_K2 + k * HP2, kh[i] * (eT * x2)); }
	ds_read2st64_b32 v[42:43], v71 offset1:2
	ds_read2st64_b32 v[132:133], v71 offset0:4 offset1:6
	v_lshlrev_b32_e32 v41, 16, v82
	v_mul_f32_e32 v131, v36, v41
	v_lshlrev_b32_e32 v41, 16, v84
	s_waitcnt lgkmcnt(1)
	v_cndmask_b32_e64 v36, 0, v42, s[4:5]
	v_cndmask_b32_e64 v42, 0, v43, s[6:7]
	v_add_f32_e32 v36, v36, v42
	s_waitcnt lgkmcnt(0)
	v_cndmask_b32_e64 v42, 0, v132, s[8:9]
	v_add_f32_e32 v36, v36, v42
	v_cndmask_b32_e64 v42, 0, v43, s[10:11]
	v_cndmask_b32_e64 v45, 0, v132, s[12:13]
	v_add_f32_e32 v42, v42, v45
	v_cndmask_b32_e64 v45, 0, v133, s[14:15]
	v_add_f32_e32 v42, v42, v45
	v_mul_f32_e32 v134, 0x3fb8aa3b, v132
	v_mul_f32_e32 v132, v40, v41
	v_rcp_f32_e32 v40, v38
	v_mul_f32_e32 v45, 0x3fb8aa3b, v36
	v_mul_f32_e32 v42, 0x3fb8aa3b, v42
	v_lshlrev_b32_e32 v133, 16, v87
	v_mul_f32_e32 v133, v38, v133
	v_exp_f32_e32 v144, v45
	v_exp_f32_e32 v45, v42
	v_exp_f32_e32 v42, v134
	v_cvt_pk_bf16_f32 v134, v117, v118
	v_sub_f32_e32 v41, 1.0, v28
	v_cvt_pk_bf16_f32 v139, v128, v129
	v_cvt_pk_bf16_f32 v140, v130, v131
	v_cvt_pk_bf16_f32 v141, v132, v133
	ds_write_b128 v73, v[134:137]
	ds_write_b128 v73, v[138:141] offset:16
	v_cvt_pk_bf16_f32 v134, v30, v106
	v_cvt_pk_bf16_f32 v135, v107, v108
	v_cvt_pk_bf16_f32 v136, v109, v110
	v_cvt_pk_bf16_f32 v137, v111, v113
	v_mul_f32_e32 v41, v41, v40
	ds_write_b128 v73, v[134:137] offset:20480
	v_mul_f32_e32 v40, v30, v38
	v_mul_f32_e32 v134, v106, v38
	v_cvt_pk_bf16_f32 v134, v40, v134
	v_mul_f32_e32 v40, v107, v38
	v_mul_f32_e32 v135, v108, v38
	v_cvt_pk_bf16_f32 v135, v40, v135
	v_mul_f32_e32 v40, v109, v38
	v_mul_f32_e32 v136, v110, v38
	v_cvt_pk_bf16_f32 v136, v40, v136
	v_mul_f32_e32 v40, v111, v38
	v_mul_f32_e32 v137, v113, v38
	v_cvt_pk_bf16_f32 v137, v40, v137
	v_mul_f32_e32 v40, v112, v38
	v_mul_f32_e32 v140, v114, v38
	v_cvt_pk_bf16_f32 v142, v40, v140
	v_mul_f32_e32 v40, v115, v38
	v_mul_f32_e32 v140, v116, v38
	v_cvt_pk_bf16_f32 v143, v40, v140
	v_mov_b32_e32 v40, v39
	v_pk_mul_f32 v[140:141], v[38:39], v[40:41] op_sel_hi:[0,1]
	ds_write_b128 v73, v[134:137] offset:40960
	v_mul_f32_e32 v40, v117, v144
	v_mul_f32_e32 v134, v118, v144
	v_cvt_pk_bf16_f32 v134, v40, v134
	v_mul_f32_e32 v40, v119, v144
	v_mul_f32_e32 v135, v120, v144
	v_cvt_pk_bf16_f32 v135, v40, v135
	v_mul_f32_e32 v40, v121, v144
	v_mul_f32_e32 v136, v123, v144
	v_cvt_pk_bf16_f32 v136, v40, v136
	v_mul_f32_e32 v40, v124, v144
	v_mul_f32_e32 v137, v126, v144
	v_cvt_pk_bf16_f32 v145, v140, v141
	v_cvt_pk_bf16_f32 v137, v40, v137
	v_mul_f32_e32 v40, v125, v144
	v_mul_f32_e32 v140, v127, v144
	v_cvt_pk_bf16_f32 v146, v40, v140
	v_mul_f32_e32 v40, v128, v144
	v_mul_f32_e32 v140, v129, v144
	v_cvt_pk_bf16_f32 v147, v40, v140
	v_mul_f32_e32 v40, v130, v144
	v_mul_f32_e32 v140, v131, v144
	v_cvt_pk_bf16_f32 v148, v40, v140
	v_mul_f32_e32 v40, v132, v144
	v_mul_f32_e32 v140, v133, v144
	v_cvt_pk_bf16_f32 v149, v40, v140
	ds_write_b128 v73, v[134:137] offset:61440
	ds_write_b128 v73, v[146:149] offset:61456
	v_pk_mov_b32 v[146:147], v[38:39], v[38:39] op_sel:[1,0]
	v_sub_f32_e32 v150, 1.0, v70
	v_mov_b32_e32 v151, v147
	v_pk_mul_f32 v[44:45], v[150:151], v[44:45]
	v_mul_f32_e32 v152, v122, v38
	v_pk_mul_f32 v[134:135], v[38:39], v[44:45]
	v_mul_f32_e32 v40, v30, v45
	v_cvt_pk_bf16_f32 v144, v152, v134
	v_mul_f32_e32 v134, v106, v45
	v_cvt_pk_bf16_f32 v134, v40, v134
	v_mul_f32_e32 v40, v107, v45
	v_mul_f32_e32 v135, v108, v45
	v_cvt_pk_bf16_f32 v135, v40, v135
	v_mul_f32_e32 v40, v109, v45
	v_mul_f32_e32 v136, v110, v45
	v_cvt_pk_bf16_f32 v138, v112, v114
	v_cvt_pk_bf16_f32 v139, v115, v116
	v_cvt_pk_bf16_f32 v140, v122, v44
	v_cvt_pk_bf16_f32 v141, v39, v41
	v_cvt_pk_bf16_f32 v136, v40, v136
	v_mul_f32_e32 v40, v111, v45
	v_mul_f32_e32 v137, v113, v45
	ds_write_b128 v73, v[138:141] offset:20496
	v_cvt_pk_bf16_f32 v137, v40, v137
	v_mul_f32_e32 v40, v112, v45
	v_mul_f32_e32 v138, v114, v45
	v_cvt_pk_bf16_f32 v138, v40, v138
	v_mul_f32_e32 v40, v115, v45
	v_mul_f32_e32 v139, v116, v45
	v_mov_b32_e32 v147, v41
	ds_write_b128 v73, v[142:145] offset:40976
	v_cvt_pk_bf16_f32 v139, v40, v139
	v_mul_f32_e32 v40, v122, v45
	v_pk_mul_f32 v[140:141], v[44:45], v[44:45] op_sel_hi:[0,1]
	v_pk_mul_f32 v[142:143], v[146:147], v[44:45] op_sel:[0,1]
	v_cvt_pk_bf16_f32 v140, v40, v141
	v_cvt_pk_bf16_f32 v141, v142, v143
	v_cmp_ne_u32_e64 s[36:37], 1, v98
	s_andn2_b64 vcc, exec, s[16:17]
	ds_write_b128 v74, v[134:137]
	ds_write_b128 v75, v[138:141]
	s_cbranch_vccz .LBB0_353
	s_andn2_b64 vcc, exec, s[54:55]
	s_cbranch_vccz .LBB0_354

; __device__ __forceinline__ int lane_id() { int l; asm volatile("v_mbcnt_lo_u32_b32 %0, -1, 0\n\tv_mbcnt_hi_u32_b32 %0, -1, %0" : "=v"(l)); return l; }
; #define LOAD_P() Params p; { const __attribute__((address_space(4))) Params* q_ = (const __attribute__((address_space(4))) Params*)__builtin_amdgcn_kernarg_segment_ptr(); asm volatile("" : "+s"(q_)); \
;     p = *q_; p.wave_id = wave_id; } unsigned char* ws = p.ws; (void)ws
; __device__ __forceinline__ void phase_wconv_rest(const Params& p, LAS unsigned char* lds, int gw, int NGW) {
;     ...
;     for (int it = gw; it < NITEMS; it += NGW) {
;         int r = it;
;         if (r < I_A) { transpose_item<false, false>(p.w_a, WA, D_MODEL, (bf16*)(ws + WS_WAT), 0, scr, r, lane); continue; } r -= I_A;
;         if (r < I_A) { transpose_item<false, false>(p.w_b, WA, D_MODEL, (bf16*)(ws + WS_WBT), 0, scr, r, lane); continue; } r -= I_A;
;         if (r < I_O) { transpose_item<false, false>(p.w_o, D_MODEL, D_MODEL, (bf16*)(ws + WS_WOT), 0, scr, r, lane); continue; } r -= I_O;
;         if (r < I_1) { transpose_item<false, true>(p.w1, D_MODEL, FFN, (bf16*)(ws + WS_W13T), 0, scr, r, lane, sh2, b2); continue; } r -= I_1;
;         if (r < I_1) { transpose_item<false, true>(p.w3, D_MODEL, FFN, (bf16*)(ws + WS_W13T), 128, scr, r, lane, sh2, b2); continue; } r -= I_1;
;         transpose_item<false, false>(p.w2, FFN, D_MODEL, (bf16*)(ws + WS_W2T), 0, scr, r, lane);
; __global__ void __launch_bounds__(NTHREADS, 2) mega_fwd(Params p_in) {
;     ...
;     { LOAD_P();
;       if (bx < 2 * BATCH * NHEAD) {
;         if (wave_id == 0 && lane_id() == 0) { unsigned* pc = (unsigned*)(ws + WS_PREPCTR); while (__hip_atomic_load(pc, __ATOMIC_RELAXED, __HIP_MEMORY_SCOPE_AGENT) < (unsigned)nb) __builtin_amdgcn_s_sleep(2); }
;         asm volatile("" ::: "memory"); __syncthreads();
;         hgrn_scan(p, lds, bx); }
;       __syncthreads();
;       phase_attn(p, lds); }
.LBB0_505:
	s_cmpk_lg_i32 s33, 0x100
	s_cbranch_scc1 .Lw2_skip
	s_cmpk_lt_i32 s2, 0x40
	s_cbranch_scc1 .Lw2_skip
	v_writelane_b32 v250, s3, 40
	v_writelane_b32 v250, s12, 41
	v_writelane_b32 v250, s18, 42
	v_writelane_b32 v250, s19, 43
	v_writelane_b32 v250, s20, 44
	v_writelane_b32 v250, s21, 45
	v_writelane_b32 v250, s22, 46
	v_writelane_b32 v250, s23, 47
	v_writelane_b32 v250, s24, 48
	v_writelane_b32 v250, s25, 49
	v_writelane_b32 v250, s26, 50
	v_writelane_b32 v250, s27, 51
	s_lshr_b32 s3, s76, 6
	s_load_dwordx8 s[8:15], s[0:1], 0x70
	s_load_dwordx2 s[40:41], s[0:1], 0x90
	s_load_dwordx2 s[42:43], s[0:1], 0xa8
	s_load_dwordx2 s[22:23], s[0:1], 0xb8
	s_waitcnt vmcnt(0) lgkmcnt(0)
	s_barrier
	s_lshl_b32 s4, s2, 3
	s_add_i32 s4, s4, s3
	s_add_i32 s20, s4, 0x3e00
	s_cmpk_gt_i32 s20, 0x51ff
	v_mbcnt_lo_u32_b32 v0, -1, 0
	v_mbcnt_hi_u32_b32 v0, -1, v0
	s_cbranch_scc1 .Lw2_done
	s_movk_i32 s21, 0x600
	s_waitcnt lgkmcnt(0)
	s_add_u32 s6, s22, 0x106000
	s_addc_u32 s7, s23, 0
	s_add_u32 s16, s22, 0x18000
	s_addc_u32 s17, s23, 0
	s_lshl_b32 s3, s3, 14
	v_ashrrev_i32_e32 v34, 5, v0
	v_lshlrev_b32_e32 v1, 2, v0
	s_movk_i32 s4, 0x84
	s_add_i32 s3, s3, 0
	v_and_b32_e32 v22, 0x7c, v1
	v_mul_lo_u32 v1, v34, s4
	v_add3_u32 v26, s3, v22, v1
	v_lshlrev_b32_e32 v1, 3, v0
	v_and_b32_e32 v1, 56, v1
	v_ashrrev_i32_e32 v35, 3, v0
	v_lshlrev_b32_e32 v12, 1, v1
	v_mov_b32_e32 v13, 0
	v_mul_u32_u24_e32 v4, 0x84, v1
	v_lshl_add_u64 v[10:11], s[22:23], 0, v[12:13]
	v_lshlrev_b32_e32 v1, 2, v35
	s_mov_b64 s[22:23], 0x142000
	v_add3_u32 v27, s3, v4, v1
	v_lshl_add_u64 v[4:5], v[10:11], 0, s[22:23]
	s_mov_b64 s[22:23], 0x4b42000
	v_lshl_add_u64 v[6:7], v[10:11], 0, s[22:23]
	s_mov_b64 s[22:23], 0x4742000
	s_mov_b64 s[4:5], 0x2d42000
	v_ashrrev_i32_e32 v1, 31, v0
	v_lshl_add_u64 v[8:9], v[10:11], 0, s[22:23]
	s_mov_b64 s[22:23], 0x4342000
	v_mov_b32_e32 v23, v13
	s_mov_b32 s19, 0
	v_lshl_add_u64 v[2:3], v[10:11], 0, s[4:5]
	v_add_u32_e32 v36, 8, v35
	v_add_u32_e32 v37, 16, v35
	v_add_u32_e32 v38, 24, v35
	v_cmp_gt_i32_e64 s[4:5], 32, v0
	v_lshl_add_u64 v[10:11], v[10:11], 0, s[22:23]
	v_lshl_add_u64 v[12:13], s[42:43], 0, v[22:23]
	v_lshl_add_u64 v[14:15], s[40:41], 0, v[22:23]
	v_lshl_add_u64 v[16:17], s[14:15], 0, v[22:23]
	v_lshl_add_u64 v[18:19], s[12:13], 0, v[22:23]
	v_lshl_add_u64 v[20:21], s[10:11], 0, v[22:23]
	v_lshl_add_u64 v[22:23], s[8:9], 0, v[22:23]
	v_lshl_add_u64 v[24:25], v[0:1], 2, s[16:17]
	s_lshl_b32 s3, s20, 5
	s_lshl_b32 s12, s21, 5
	s_mov_b32 s13, 0xc000
	s_mov_b32 s14, 0x18000
	s_mov_b32 s15, 0x24000
	s_movk_i32 s22, 0x2c00
	s_movk_i32 s23, 0x5800
	v_add_u32_e32 v39, 0x4000, v26
	v_add_u32_e32 v40, 0x4400, v26
	v_add_u32_e32 v41, 0x4800, v26
	v_add_u32_e32 v42, 0x4c00, v26
	v_add_u32_e32 v43, 0x5000, v26
	v_add_u32_e32 v44, 0x5400, v26
	v_add_u32_e32 v45, 0x5800, v26
	v_add_u32_e32 v46, 0x5c00, v26
	v_add_u32_e32 v47, 0x4000, v27
	s_branch .Lw2c_244

;     __device__ __forceinline__ void operator()(const f32x4 (&acc_c)[2][2][4][2], const pg8::Unit& u, int wr, int wc, int fr, int fq) const {
;     ...
; #pragma unroll
;         for (int m = 0; m < 4; ++m) { const int rl = half * 128 + wr * 64 + m * 16 + fr;
;             const float rstd = __builtin_amdgcn_rsqf(rsq[rl] * (1.0f / D_MODEL) + EPS);
; #pragma unroll
;             for (int bj = 0; bj < 2; ++bj)
; #pragma unroll
;                 for (int n = 0; n < 2; ++n) acc[0][bj][m][n] = acc[0][bj][m][n] * rstd + *(const LAS f32x4*)(bias2 + bj * 128 + cl + 4 * n); }
;         f32x4 w0[2], w1[2], w2[2], cbv[2];
; #pragma unroll
;         for (int n = 0; n < 2; ++n) { w0[n] = *(const f32x4*)(cw + ch0 + 4 * n); w1[n] = *(const f32x4*)(cw + FFN + ch0 + 4 * n); w2[n] = *(const f32x4*)(cw + 2 * FFN + ch0 + 4 * n); cbv[n] = *(const f32x4*)(cb + ch0 + 4 * n); }
;         { const int bi = wr;
;             if (fr == 0) {
; #pragma unroll
;                 for (int n = 0; n < 2; ++n) *(LAS f32x4*)(X + (bi * 2 + 0) * 128 + cl + 4 * n) = acc[0][0][0][n]; }
;             if (fr == 15) {
; #pragma unroll
;                 for (int n = 0; n < 2; ++n) *(LAS f32x4*)(X + (bi * 2 + 1) * 128 + cl + 4 * n) = acc[0][0][3][n]; } }
;         asm volatile("s_waitcnt lgkmcnt(0)" ::: "memory"); __builtin_amdgcn_s_barrier(); asm volatile("" ::: "memory");
;         { const int bi = wr;
; #pragma unroll
;             for (int m = 0; m < 4; ++m) { u32x4 o;
; #pragma unroll
;                 for (int n = 0; n < 2; ++n) { const f32x4 cur = acc[0][0][m][n];
;                     f32x4 pu, nd;
;                     if (m > 0) pu = ror1_4(acc[0][0][m > 0 ? m - 1 : 0][n]); else pu = (bi > 0) ? *(const LAS f32x4*)(X + ((bi - 1) * 2 + 1) * 128 + cl + 4 * n) : (f32x4){0.f, 0.f, 0.f, 0.f};
;                     if (m < 3) nd = rol1_4(acc[0][0][m < 3 ? m + 1 : 3][n]); else nd = (bi < 1) ? *(const LAS f32x4*)(X + ((bi + 1) * 2 + 0) * 128 + cl + 4 * n) : (f32x4){0.f, 0.f, 0.f, 0.f};
;                     const f32x4 ps = ror1_4(cur), ns = rol1_4(cur);
;                     const f32x4 prev = (fr > 0) ? ps : pu, next = (fr < 15) ? ns : nd;
;                     const f32x4 uu = w0[n] * prev + w1[n] * cur + w2[n] * next + cbv[n]; const f32x4 gt = acc[0][1][m][n];
;                     f32x4 r; r.x = siluf_(uu.x) * gt.x; r.y = siluf_(uu.y) * gt.y; r.z = siluf_(uu.z) * gt.z; r.w = siluf_(uu.w) * gt.w;
.LBB0_778:
	v_mov_b32_e32 v114, 0x358637bd
	v_fmac_f32_e32 v114, 0x3a000000, v113
	v_rsq_f32_e32 v130, v114
	s_nop 0
	v_mov_b32_e32 v131, v130
	v_pk_fma_f32 v[102:103], v[102:103], v[130:131], v[110:111] op_sel_hi:[1,0,1]
	v_pk_fma_f32 v[124:125], v[100:101], v[130:131], v[108:109] op_sel_hi:[1,0,1]
	v_mov_b32_e32 v129, v128
	s_nop 0
	v_mov_b32_dpp v134, v124 row_ror:15 row_mask:0xf bank_mask:0xf
	v_mov_b32_dpp v136, v125 row_ror:15 row_mask:0xf bank_mask:0xf
	v_mov_b32_dpp v135, v102 row_ror:15 row_mask:0xf bank_mask:0xf
	v_mov_b32_dpp v137, v103 row_ror:15 row_mask:0xf bank_mask:0xf
	v_mov_b32_dpp v142, v20 row_ror:1 row_mask:0xf bank_mask:0xf
	v_mov_b32_dpp v144, v21 row_ror:1 row_mask:0xf bank_mask:0xf
	v_mov_b32_dpp v143, v22 row_ror:1 row_mask:0xf bank_mask:0xf
	v_mov_b32_dpp v145, v23 row_ror:1 row_mask:0xf bank_mask:0xf
	v_mov_b32_dpp v138, v20 row_ror:15 row_mask:0xf bank_mask:0xf
	v_mov_b32_dpp v140, v21 row_ror:15 row_mask:0xf bank_mask:0xf
	v_mov_b32_dpp v139, v22 row_ror:15 row_mask:0xf bank_mask:0xf
	v_mov_b32_dpp v141, v23 row_ror:15 row_mask:0xf bank_mask:0xf
	s_andn2_b64 vcc, exec, s[10:11]
	v_mov_b32_e32 v113, 0
	v_mov_b32_e32 v114, 0
	v_mov_b32_e32 v115, 0
	s_cbranch_vccnz .LBB0_780
	ds_read_b128 v[112:115], v127 offset:16
.LBB0_780:
	v_mov_b32_e32 v146, v128
	v_mov_b32_e32 v147, v128
	v_pk_fma_f32 v[40:41], v[40:41], v[128:129], v[92:93]
	v_pk_fma_f32 v[48:49], v[48:49], v[128:129], v[88:89]
	v_mov_b32_e32 v128, v130
	v_mov_b32_e32 v129, v130
	v_pk_fma_f32 v[42:43], v[42:43], v[146:147], v[94:95]
	v_or_b32_e32 v127, s25, v132
	v_lshl_add_u64 v[100:101], v[120:121], 1, s[14:15]
	s_mov_b64 s[10:11], 0x14342000
	v_pk_fma_f32 v[50:51], v[50:51], v[146:147], v[90:91]
	v_pk_fma_f32 v[98:99], v[98:99], v[128:129], v[106:107]
	v_pk_fma_f32 v[128:129], v[96:97], v[130:131], v[104:105]
	s_lshl_b32 s25, s4, 7
	v_lshl_add_u64 v[100:101], v[100:101], 0, s[10:11]
	v_mov_b32_dpp v96, v128 row_ror:15 row_mask:0xf bank_mask:0xf
	v_mov_b32_dpp v146, v129 row_ror:15 row_mask:0xf bank_mask:0xf
	v_mov_b32_dpp v147, v98 row_ror:15 row_mask:0xf bank_mask:0xf
	v_mov_b32_dpp v148, v99 row_ror:15 row_mask:0xf bank_mask:0xf
	v_mov_b32_dpp v152, v16 row_ror:1 row_mask:0xf bank_mask:0xf
	v_mov_b32_dpp v153, v17 row_ror:1 row_mask:0xf bank_mask:0xf
	v_mov_b32_dpp v154, v18 row_ror:1 row_mask:0xf bank_mask:0xf
	v_mov_b32_dpp v155, v19 row_ror:1 row_mask:0xf bank_mask:0xf
	v_mov_b32_dpp v149, v16 row_ror:15 row_mask:0xf bank_mask:0xf
	v_mov_b32_dpp v150, v17 row_ror:15 row_mask:0xf bank_mask:0xf
	v_mov_b32_dpp v151, v18 row_ror:15 row_mask:0xf bank_mask:0xf
	v_mov_b32_dpp v97, v19 row_ror:15 row_mask:0xf bank_mask:0xf
	v_cmp_ne_u32_e32 vcc, 0, v127
	s_and_saveexec_b64 s[10:11], vcc
	s_xor_b64 s[10:11], exec, s[10:11]
	s_cbranch_execz .LBB0_782
	s_waitcnt lgkmcnt(0)
	v_cndmask_b32_e64 v119, v145, v119, s[8:9]
	v_cndmask_b32_e64 v118, v143, v118, s[8:9]
	s_waitcnt vmcnt(0)
	v_pk_mul_f32 v[118:119], v[58:59], v[118:119]
	v_cndmask_b32_e64 v143, v140, v136, s[6:7]
	v_pk_fma_f32 v[118:119], v[22:23], v[66:67], v[118:119]
	v_cndmask_b32_e64 v137, v141, v137, s[6:7]
	v_cndmask_b32_e64 v136, v139, v135, s[6:7]
	v_pk_fma_f32 v[118:119], v[54:55], v[136:137], v[118:119]
	v_cndmask_b32_e64 v116, v142, v116, s[8:9]
	v_pk_add_f32 v[118:119], v[46:47], v[118:119]
	v_cndmask_b32_e64 v142, v138, v134, s[6:7]
	v_mul_f32_e32 v134, 0xbfb8aa3b, v119
	v_cndmask_b32_e64 v117, v144, v117, s[8:9]
	v_exp_f32_e32 v134, v134
	v_mul_f32_e32 v135, 0xbfb8aa3b, v118
	v_pk_mul_f32 v[116:117], v[56:57], v[116:117]
	v_exp_f32_e32 v136, v135
	v_pk_fma_f32 v[116:117], v[20:21], v[64:65], v[116:117]
	v_add_f32_e32 v134, 1.0, v134
	v_pk_fma_f32 v[116:117], v[52:53], v[142:143], v[116:117]
	v_rcp_f32_e32 v135, v134
	v_pk_add_f32 v[116:117], v[44:45], v[116:117]
	v_add_f32_e32 v134, 1.0, v136
	v_mul_f32_e32 v136, 0xbfb8aa3b, v117
	v_exp_f32_e32 v136, v136
	v_mul_f32_e32 v137, 0xbfb8aa3b, v116
	v_exp_f32_e32 v138, v137
	v_rcp_f32_e32 v134, v134
	v_add_f32_e32 v136, 1.0, v136
	v_rcp_f32_e32 v137, v136
	v_add_f32_e32 v136, 1.0, v138
	v_rcp_f32_e32 v136, v136
	v_pk_mul_f32 v[118:119], v[118:119], v[134:135]
	v_cndmask_b32_e64 v113, v153, v113, s[8:9]
	v_cndmask_b32_e64 v112, v152, v112, s[8:9]
	v_pk_mul_f32 v[116:117], v[116:117], v[136:137]
	v_pk_mul_f32 v[118:119], v[42:43], v[118:119]
	v_pk_mul_f32 v[116:117], v[40:41], v[116:117]
	v_cndmask_b32_e64 v115, v155, v115, s[8:9]
	v_cndmask_b32_e64 v114, v154, v114, s[8:9]
	v_pk_mul_f32 v[112:113], v[32:33], v[112:113]
	v_cvt_pk_bf16_f32 v116, v116, v117
	v_cvt_pk_bf16_f32 v117, v118, v119
	v_pk_mul_f32 v[114:115], v[34:35], v[114:115]
	v_pk_fma_f32 v[112:113], v[16:17], v[36:37], v[112:113]
	v_cndmask_b32_e64 v119, v97, v148, s[6:7]
	v_cndmask_b32_e64 v97, v150, v146, s[6:7]
	v_cndmask_b32_e64 v96, v149, v96, s[6:7]
	v_pk_fma_f32 v[114:115], v[18:19], v[38:39], v[114:115]
	v_cndmask_b32_e64 v118, v151, v147, s[6:7]
	v_pk_fma_f32 v[96:97], v[28:29], v[96:97], v[112:113]
	v_pk_fma_f32 v[112:113], v[30:31], v[118:119], v[114:115]
	v_pk_add_f32 v[96:97], v[24:25], v[96:97]
	v_pk_add_f32 v[112:113], v[26:27], v[112:113]
	v_mul_f32_e32 v114, 0xbfb8aa3b, v96
	v_mul_f32_e32 v115, 0xbfb8aa3b, v97
	v_exp_f32_e32 v114, v114
	v_exp_f32_e32 v115, v115
	v_mul_f32_e32 v118, 0xbfb8aa3b, v112
	v_exp_f32_e32 v118, v118
	v_mul_f32_e32 v119, 0xbfb8aa3b, v113
	v_exp_f32_e32 v119, v119
	v_add_f32_e32 v114, 1.0, v114
	v_add_f32_e32 v115, 1.0, v115
	v_rcp_f32_e32 v114, v114
	v_rcp_f32_e32 v115, v115
	v_add_f32_e32 v118, 1.0, v118
	v_rcp_f32_e32 v134, v118
	v_add_f32_e32 v118, 1.0, v119
	v_rcp_f32_e32 v135, v118
	v_pk_mul_f32 v[96:97], v[96:97], v[114:115]
	s_lshl_b32 s31, s12, 8
	v_pk_mul_f32 v[96:97], v[48:49], v[96:97]
	s_or_b32 s31, s31, s25
	v_cvt_pk_bf16_f32 v118, v96, v97
	v_pk_mul_f32 v[96:97], v[112:113], v[134:135]
	s_movk_i32 s34, 0x2c00
	v_pk_mul_f32 v[96:97], v[50:51], v[96:97]
	s_nop 0
	v_cvt_pk_bf16_f32 v119, v96, v97
	v_add_u32_e32 v96, s31, v127
	v_mad_i64_i32 v[96:97], s[34:35], v96, s34, v[100:101]
	global_store_dwordx4 v[96:97], v[116:119], off
;     __host__ __device__ bool next(int i, Unit& u) const { const long L = (long)i * G + c; if (L >= maxL) return false; return unit_of(L, u); }
; #define LAS __attribute__((address_space(3)))
; __device__ __forceinline__ unsigned pk2(float lo, float hi) { const f32x2_t v = {lo, hi}; const bf16x2_t b = __builtin_convertvector(v, bf16x2_t); return __builtin_bit_cast(unsigned, b); }
; __device__ __forceinline__ float siluf_(float x) { return x * __builtin_amdgcn_rcpf(1.0f + __expf(-x)); }
;     __device__ bool next(int i, pg8::Unit& u) const { if (!pg8::StaticOrder::next(i >> 1, u)) return false; u.br = i & 1; return true; }
; __device__ __forceinline__ f32x4 ror1_4(const f32x4 v) { return (f32x4){dpp_ror1(v.x), dpp_ror1(v.y), dpp_ror1(v.z), dpp_ror1(v.w)}; }
; __device__ __forceinline__ f32x4 rol1_4(const f32x4 v) { return (f32x4){dpp_rol1(v.x), dpp_rol1(v.y), dpp_rol1(v.z), dpp_rol1(v.w)}; }
;     __device__ __forceinline__ void operator()(const f32x4 (&acc_c)[2][2][4][2], const pg8::Unit& u, int wr, int wc, int fr, int fq) const {
;     ...
;             for (int m = 0; m < 4; ++m) { u32x4 o;
; #pragma unroll
;                 for (int n = 0; n < 2; ++n) { const f32x4 cur = acc[0][0][m][n];
;                     f32x4 pu, nd;
;                     if (m > 0) pu = ror1_4(acc[0][0][m > 0 ? m - 1 : 0][n]); else pu = (bi > 0) ? *(const LAS f32x4*)(X + ((bi - 1) * 2 + 1) * 128 + cl + 4 * n) : (f32x4){0.f, 0.f, 0.f, 0.f};
;                     if (m < 3) nd = rol1_4(acc[0][0][m < 3 ? m + 1 : 3][n]); else nd = (bi < 1) ? *(const LAS f32x4*)(X + ((bi + 1) * 2 + 0) * 128 + cl + 4 * n) : (f32x4){0.f, 0.f, 0.f, 0.f};
;                     const f32x4 ps = ror1_4(cur), ns = rol1_4(cur);
;                     const f32x4 prev = (fr > 0) ? ps : pu, next = (fr < 15) ? ns : nd;
;                     const f32x4 uu = w0[n] * prev + w1[n] * cur + w2[n] * next + cbv[n]; const f32x4 gt = acc[0][1][m][n];
;                     f32x4 r; r.x = siluf_(uu.x) * gt.x; r.y = siluf_(uu.y) * gt.y; r.z = siluf_(uu.z) * gt.z; r.w = siluf_(uu.w) * gt.w;
;                     if (n == 0) { o.x = pk2(r.x, r.y); o.y = pk2(r.z, r.w); } else { o.z = pk2(r.x, r.y); o.w = pk2(r.z, r.w); } }
;                 const int rh = wr * 64 + m * 16 + fr;
;                 if (rh != 0 && rh != 127) *(u32x4*)(ACT + (size_t)(u.pm * 256 + half * 128 + rh) * FFN + ch0) = o; } }
.LBB0_782:
	s_or_saveexec_b64 s[10:11], s[10:11]
	s_add_i32 s30, s30, 0x20000
	s_waitcnt lgkmcnt(0)
	v_mov_b32_e32 v112, s31
	s_xor_b64 exec, exec, s[10:11]
	s_lshl_b32 s31, s12, 8
	s_or_b32 s25, s25, s31
	v_mov_b32_e32 v112, s25
	s_or_b64 exec, exec, s[10:11]
	v_mov_b32_e32 v114, v130
	v_mov_b32_e32 v115, v130
	v_pk_fma_f32 v[116:117], v[78:79], v[114:115], v[94:95]
	v_mov_b32_e32 v78, 0x358637bd
	v_fmac_f32_e32 v78, 0x3a000000, v126
	v_rsq_f32_e32 v118, v78
	v_pk_fma_f32 v[134:135], v[76:77], v[130:131], v[92:93]
	v_pk_fma_f32 v[130:131], v[72:73], v[130:131], v[88:89]
	v_pk_fma_f32 v[114:115], v[74:75], v[114:115], v[90:91]
	v_pk_fma_f32 v[78:79], v[84:85], v[118:119], v[108:109] op_sel_hi:[1,0,1]
	v_pk_fma_f32 v[72:73], v[82:83], v[118:119], v[106:107] op_sel_hi:[1,0,1]
	v_mov_b32_dpp v82, v20 row_ror:1 row_mask:0xf bank_mask:0xf
	v_mov_b32_dpp v83, v21 row_ror:1 row_mask:0xf bank_mask:0xf
	v_mov_b32_dpp v107, v124 row_ror:1 row_mask:0xf bank_mask:0xf
	v_mov_b32_dpp v108, v125 row_ror:1 row_mask:0xf bank_mask:0xf
	v_pk_fma_f32 v[76:77], v[86:87], v[118:119], v[110:111] op_sel_hi:[1,0,1]
	v_pk_fma_f32 v[74:75], v[80:81], v[118:119], v[104:105] op_sel_hi:[1,0,1]
	v_cndmask_b32_e64 v83, v108, v83, s[8:9]
	v_cndmask_b32_e64 v82, v107, v82, s[8:9]
	v_mov_b32_dpp v80, v22 row_ror:1 row_mask:0xf bank_mask:0xf
	v_mov_b32_dpp v81, v23 row_ror:1 row_mask:0xf bank_mask:0xf
	v_mov_b32_dpp v97, v78 row_ror:15 row_mask:0xf bank_mask:0xf
	v_mov_b32_dpp v104, v79 row_ror:15 row_mask:0xf bank_mask:0xf
	v_mov_b32_dpp v109, v102 row_ror:1 row_mask:0xf bank_mask:0xf
	v_mov_b32_dpp v110, v103 row_ror:1 row_mask:0xf bank_mask:0xf
	v_mov_b32_dpp v86, v124 row_ror:15 row_mask:0xf bank_mask:0xf
	v_mov_b32_dpp v87, v125 row_ror:15 row_mask:0xf bank_mask:0xf
	s_waitcnt vmcnt(0)
	v_pk_mul_f32 v[82:83], v[56:57], v[82:83]
	v_cndmask_b32_e64 v81, v110, v81, s[8:9]
	v_cndmask_b32_e64 v80, v109, v80, s[8:9]
	v_pk_fma_f32 v[82:83], v[64:65], v[124:125], v[82:83]
	v_cndmask_b32_e64 v87, v87, v104, s[6:7]
	v_cndmask_b32_e64 v86, v86, v97, s[6:7]
	v_mov_b32_dpp v105, v76 row_ror:15 row_mask:0xf bank_mask:0xf
	v_mov_b32_dpp v106, v77 row_ror:15 row_mask:0xf bank_mask:0xf
	v_mov_b32_dpp v84, v102 row_ror:15 row_mask:0xf bank_mask:0xf
	v_mov_b32_dpp v85, v103 row_ror:15 row_mask:0xf bank_mask:0xf
	v_pk_mul_f32 v[80:81], v[58:59], v[80:81]
	v_pk_fma_f32 v[82:83], v[52:53], v[86:87], v[82:83]
	v_pk_fma_f32 v[80:81], v[66:67], v[102:103], v[80:81]
	v_cndmask_b32_e64 v85, v85, v106, s[6:7]
	v_cndmask_b32_e64 v84, v84, v105, s[6:7]
	v_pk_add_f32 v[82:83], v[44:45], v[82:83]
	v_pk_fma_f32 v[80:81], v[54:55], v[84:85], v[80:81]
	v_mul_f32_e32 v84, 0xbfb8aa3b, v82
	v_exp_f32_e32 v86, v84
	v_mul_f32_e32 v84, 0xbfb8aa3b, v83
	v_exp_f32_e32 v87, v84
	v_pk_add_f32 v[84:85], v[46:47], v[80:81]
	v_add_f32_e32 v80, 1.0, v86
	v_mul_f32_e32 v86, 0xbfb8aa3b, v84
	v_add_f32_e32 v81, 1.0, v87
	v_mul_f32_e32 v87, 0xbfb8aa3b, v85
	v_exp_f32_e32 v86, v86
	v_exp_f32_e32 v87, v87
	v_rcp_f32_e32 v80, v80
	v_rcp_f32_e32 v81, v81
	v_add_f32_e32 v86, 1.0, v86
	v_add_f32_e32 v87, 1.0, v87
	v_rcp_f32_e32 v86, v86
	v_rcp_f32_e32 v87, v87
	v_lshl_add_u32 v113, v123, 2, s30
	v_pk_fma_f32 v[70:71], v[70:71], v[118:119], v[94:95] op_sel_hi:[1,0,1]
	v_pk_fma_f32 v[68:69], v[68:69], v[118:119], v[92:93] op_sel_hi:[1,0,1]
	v_pk_fma_f32 v[62:63], v[62:63], v[118:119], v[90:91] op_sel_hi:[1,0,1]
	v_pk_fma_f32 v[60:61], v[60:61], v[118:119], v[88:89] op_sel_hi:[1,0,1]
	v_pk_mul_f32 v[80:81], v[82:83], v[80:81]
	v_pk_mul_f32 v[82:83], v[84:85], v[86:87]
	v_mov_b32_dpp v111, v16 row_ror:1 row_mask:0xf bank_mask:0xf
	v_mov_b32_dpp v118, v17 row_ror:1 row_mask:0xf bank_mask:0xf
	v_mov_b32_dpp v119, v18 row_ror:1 row_mask:0xf bank_mask:0xf
	v_mov_b32_dpp v123, v19 row_ror:1 row_mask:0xf bank_mask:0xf
	v_mov_b32_dpp v139, v128 row_ror:1 row_mask:0xf bank_mask:0xf
	v_mov_b32_dpp v140, v129 row_ror:1 row_mask:0xf bank_mask:0xf
	v_mov_b32_dpp v141, v98 row_ror:1 row_mask:0xf bank_mask:0xf
	v_mov_b32_dpp v142, v99 row_ror:1 row_mask:0xf bank_mask:0xf
	v_pk_mul_f32 v[80:81], v[134:135], v[80:81]
	v_pk_mul_f32 v[82:83], v[116:117], v[82:83]
	v_cvt_pk_bf16_f32 v80, v80, v81
	v_cvt_pk_bf16_f32 v81, v82, v83
	v_cndmask_b32_e64 v83, v142, v123, s[8:9]
	v_cndmask_b32_e64 v82, v141, v119, s[8:9]
	v_cndmask_b32_e64 v85, v140, v118, s[8:9]
	v_cndmask_b32_e64 v84, v139, v111, s[8:9]
	v_mov_b32_dpp v126, v74 row_ror:15 row_mask:0xf bank_mask:0xf
	v_mov_b32_dpp v136, v75 row_ror:15 row_mask:0xf bank_mask:0xf
	v_mov_b32_dpp v143, v128 row_ror:15 row_mask:0xf bank_mask:0xf
	v_mov_b32_dpp v144, v129 row_ror:15 row_mask:0xf bank_mask:0xf
	v_pk_mul_f32 v[84:85], v[32:33], v[84:85]
	v_pk_mul_f32 v[82:83], v[34:35], v[82:83]
	v_mov_b32_dpp v145, v98 row_ror:15 row_mask:0xf bank_mask:0xf
	v_mov_b32_dpp v146, v99 row_ror:15 row_mask:0xf bank_mask:0xf
	v_pk_fma_f32 v[82:83], v[98:99], v[38:39], v[82:83]
	v_pk_fma_f32 v[84:85], v[128:129], v[36:37], v[84:85]
	v_cndmask_b32_e64 v99, v144, v136, s[6:7]
	v_cndmask_b32_e64 v98, v143, v126, s[6:7]
	v_mov_b32_dpp v137, v72 row_ror:15 row_mask:0xf bank_mask:0xf
	v_mov_b32_dpp v138, v73 row_ror:15 row_mask:0xf bank_mask:0xf
	v_pk_fma_f32 v[84:85], v[28:29], v[98:99], v[84:85]
	v_cndmask_b32_e64 v87, v146, v138, s[6:7]
	v_cndmask_b32_e64 v86, v145, v137, s[6:7]
	v_pk_add_f32 v[84:85], v[24:25], v[84:85]
	v_pk_fma_f32 v[82:83], v[30:31], v[86:87], v[82:83]
	v_mul_f32_e32 v86, 0xbfb8aa3b, v84
	v_exp_f32_e32 v98, v86
	v_mul_f32_e32 v86, 0xbfb8aa3b, v85
	v_exp_f32_e32 v99, v86
	v_pk_add_f32 v[86:87], v[26:27], v[82:83]
	v_add_f32_e32 v82, 1.0, v98
	v_mul_f32_e32 v98, 0xbfb8aa3b, v86
	v_add_f32_e32 v83, 1.0, v99
;     __host__ __device__ bool next(int i, Unit& u) const { const long L = (long)i * G + c; if (L >= maxL) return false; return unit_of(L, u); }
; #define LAS __attribute__((address_space(3)))
; __device__ __forceinline__ unsigned pk2(float lo, float hi) { const f32x2_t v = {lo, hi}; const bf16x2_t b = __builtin_convertvector(v, bf16x2_t); return __builtin_bit_cast(unsigned, b); }
; __device__ __forceinline__ float siluf_(float x) { return x * __builtin_amdgcn_rcpf(1.0f + __expf(-x)); }
;     __device__ bool next(int i, pg8::Unit& u) const { if (!pg8::StaticOrder::next(i >> 1, u)) return false; u.br = i & 1; return true; }
; __device__ __forceinline__ f32x4 ror1_4(const f32x4 v) { return (f32x4){dpp_ror1(v.x), dpp_ror1(v.y), dpp_ror1(v.z), dpp_ror1(v.w)}; }
; __device__ __forceinline__ f32x4 rol1_4(const f32x4 v) { return (f32x4){dpp_rol1(v.x), dpp_rol1(v.y), dpp_rol1(v.z), dpp_rol1(v.w)}; }
;     __device__ __forceinline__ void operator()(const f32x4 (&acc_c)[2][2][4][2], const pg8::Unit& u, int wr, int wc, int fr, int fq) const {
;     ...
;             for (int m = 0; m < 4; ++m) { u32x4 o;
; #pragma unroll
;                 for (int n = 0; n < 2; ++n) { const f32x4 cur = acc[0][0][m][n];
;                     f32x4 pu, nd;
;                     if (m > 0) pu = ror1_4(acc[0][0][m > 0 ? m - 1 : 0][n]); else pu = (bi > 0) ? *(const LAS f32x4*)(X + ((bi - 1) * 2 + 1) * 128 + cl + 4 * n) : (f32x4){0.f, 0.f, 0.f, 0.f};
;                     if (m < 3) nd = rol1_4(acc[0][0][m < 3 ? m + 1 : 3][n]); else nd = (bi < 1) ? *(const LAS f32x4*)(X + ((bi + 1) * 2 + 0) * 128 + cl + 4 * n) : (f32x4){0.f, 0.f, 0.f, 0.f};
;                     const f32x4 ps = ror1_4(cur), ns = rol1_4(cur);
;                     const f32x4 prev = (fr > 0) ? ps : pu, next = (fr < 15) ? ns : nd;
;                     const f32x4 uu = w0[n] * prev + w1[n] * cur + w2[n] * next + cbv[n]; const f32x4 gt = acc[0][1][m][n];
;                     f32x4 r; r.x = siluf_(uu.x) * gt.x; r.y = siluf_(uu.y) * gt.y; r.z = siluf_(uu.z) * gt.z; r.w = siluf_(uu.w) * gt.w;
;                     if (n == 0) { o.x = pk2(r.x, r.y); o.y = pk2(r.z, r.w); } else { o.z = pk2(r.x, r.y); o.w = pk2(r.z, r.w); } }
;                 const int rh = wr * 64 + m * 16 + fr;
;                 if (rh != 0 && rh != 127) *(u32x4*)(ACT + (size_t)(u.pm * 256 + half * 128 + rh) * FFN + ch0) = o; } }
	v_mul_f32_e32 v99, 0xbfb8aa3b, v87
	v_exp_f32_e32 v98, v98
	v_exp_f32_e32 v99, v99
	v_rcp_f32_e32 v82, v82
	v_rcp_f32_e32 v83, v83
	v_add_f32_e32 v98, 1.0, v98
	v_add_f32_e32 v99, 1.0, v99
	v_rcp_f32_e32 v98, v98
	v_rcp_f32_e32 v99, v99
	v_pk_mul_f32 v[82:83], v[84:85], v[82:83]
	s_movk_i32 s25, 0x2c00
	v_pk_mul_f32 v[82:83], v[130:131], v[82:83]
	v_pk_mul_f32 v[84:85], v[86:87], v[98:99]
	v_add_u32_e32 v98, v112, v127
	v_pk_mul_f32 v[84:85], v[114:115], v[84:85]
	v_cvt_pk_bf16_f32 v82, v82, v83
	v_cvt_pk_bf16_f32 v83, v84, v85
	v_add_u32_e32 v84, 16, v98
	v_mad_i64_i32 v[84:85], s[30:31], v84, s25, v[100:101]
	global_store_dwordx4 v[84:85], v[80:83], off
	s_nop 1
	v_mov_b32_dpp v81, v76 row_ror:1 row_mask:0xf bank_mask:0xf
	v_mov_b32_dpp v83, v77 row_ror:1 row_mask:0xf bank_mask:0xf
	v_mov_b32_dpp v80, v78 row_ror:1 row_mask:0xf bank_mask:0xf
	v_mov_b32_dpp v82, v79 row_ror:1 row_mask:0xf bank_mask:0xf
	v_cndmask_b32_e64 v85, v83, v110, s[8:9]
	v_cndmask_b32_e64 v84, v81, v109, s[8:9]
	v_mov_b32_dpp v103, v14 row_ror:15 row_mask:0xf bank_mask:0xf
	v_mov_b32_dpp v111, v15 row_ror:15 row_mask:0xf bank_mask:0xf
	v_cndmask_b32_e64 v87, v82, v108, s[8:9]
	v_cndmask_b32_e64 v86, v80, v107, s[8:9]
	v_pk_mul_f32 v[84:85], v[58:59], v[84:85]
	v_mov_b32_dpp v99, v12 row_ror:15 row_mask:0xf bank_mask:0xf
	v_mov_b32_dpp v102, v13 row_ror:15 row_mask:0xf bank_mask:0xf
	v_pk_mul_f32 v[86:87], v[56:57], v[86:87]
	v_pk_fma_f32 v[76:77], v[66:67], v[76:77], v[84:85]
	v_cndmask_b32_e64 v85, v106, v111, s[6:7]
	v_cndmask_b32_e64 v84, v105, v103, s[6:7]
	v_pk_fma_f32 v[78:79], v[64:65], v[78:79], v[86:87]
	v_cndmask_b32_e64 v87, v104, v102, s[6:7]
	v_cndmask_b32_e64 v86, v97, v99, s[6:7]
	v_pk_fma_f32 v[76:77], v[54:55], v[84:85], v[76:77]
	v_pk_fma_f32 v[78:79], v[52:53], v[86:87], v[78:79]
	v_pk_add_f32 v[76:77], v[46:47], v[76:77]
	v_pk_add_f32 v[78:79], v[44:45], v[78:79]
	v_mul_f32_e32 v86, 0xbfb8aa3b, v76
	v_mul_f32_e32 v87, 0xbfb8aa3b, v77
	v_mul_f32_e32 v84, 0xbfb8aa3b, v78
	v_mul_f32_e32 v85, 0xbfb8aa3b, v79
	v_exp_f32_e32 v86, v86
	v_exp_f32_e32 v87, v87
	v_exp_f32_e32 v84, v84
	v_exp_f32_e32 v85, v85
	v_add_f32_e32 v86, 1.0, v86
	v_add_f32_e32 v87, 1.0, v87
	v_add_f32_e32 v84, 1.0, v84
	v_add_f32_e32 v85, 1.0, v85
	v_rcp_f32_e32 v86, v86
	v_rcp_f32_e32 v87, v87
	v_rcp_f32_e32 v84, v84
	v_rcp_f32_e32 v85, v85
	v_pk_mul_f32 v[76:77], v[76:77], v[86:87]
	v_mov_b32_dpp v118, v74 row_ror:1 row_mask:0xf bank_mask:0xf
	v_mov_b32_dpp v119, v75 row_ror:1 row_mask:0xf bank_mask:0xf
	v_pk_mul_f32 v[78:79], v[78:79], v[84:85]
	v_pk_mul_f32 v[70:71], v[70:71], v[76:77]
	v_cndmask_b32_e64 v77, v119, v140, s[8:9]
	v_cndmask_b32_e64 v76, v118, v139, s[8:9]
	v_mov_b32_dpp v114, v8 row_ror:15 row_mask:0xf bank_mask:0xf
	v_mov_b32_dpp v115, v9 row_ror:15 row_mask:0xf bank_mask:0xf
	v_mov_b32_dpp v123, v72 row_ror:1 row_mask:0xf bank_mask:0xf
	v_mov_b32_dpp v124, v73 row_ror:1 row_mask:0xf bank_mask:0xf
	v_pk_mul_f32 v[68:69], v[68:69], v[78:79]
	v_pk_mul_f32 v[76:77], v[32:33], v[76:77]
	v_cvt_pk_bf16_f32 v68, v68, v69
	v_cvt_pk_bf16_f32 v69, v70, v71
	v_cndmask_b32_e64 v71, v124, v142, s[8:9]
	v_cndmask_b32_e64 v70, v123, v141, s[8:9]
	v_pk_fma_f32 v[76:77], v[36:37], v[74:75], v[76:77]
	v_cndmask_b32_e64 v85, v136, v115, s[6:7]
	v_cndmask_b32_e64 v84, v126, v114, s[6:7]
	v_mov_b32_dpp v116, v10 row_ror:15 row_mask:0xf bank_mask:0xf
	v_mov_b32_dpp v117, v11 row_ror:15 row_mask:0xf bank_mask:0xf
	v_pk_mul_f32 v[70:71], v[34:35], v[70:71]
	v_pk_fma_f32 v[76:77], v[28:29], v[84:85], v[76:77]
	v_pk_fma_f32 v[70:71], v[38:39], v[72:73], v[70:71]
	v_cndmask_b32_e64 v79, v138, v117, s[6:7]
	v_cndmask_b32_e64 v78, v137, v116, s[6:7]
	v_pk_add_f32 v[76:77], v[24:25], v[76:77]
	v_pk_fma_f32 v[70:71], v[30:31], v[78:79], v[70:71]
	v_mul_f32_e32 v78, 0xbfb8aa3b, v76
	v_exp_f32_e32 v84, v78
	v_mul_f32_e32 v78, 0xbfb8aa3b, v77
	v_exp_f32_e32 v85, v78
	v_pk_add_f32 v[78:79], v[26:27], v[70:71]
	v_add_f32_e32 v70, 1.0, v84
	v_mul_f32_e32 v84, 0xbfb8aa3b, v78
	v_add_f32_e32 v71, 1.0, v85
	v_mul_f32_e32 v85, 0xbfb8aa3b, v79
	v_exp_f32_e32 v84, v84
	v_exp_f32_e32 v85, v85
	v_rcp_f32_e32 v70, v70
	v_rcp_f32_e32 v71, v71
	v_add_f32_e32 v84, 1.0, v84
	v_add_f32_e32 v85, 1.0, v85
	v_rcp_f32_e32 v84, v84
	v_rcp_f32_e32 v85, v85
	v_pk_mul_f32 v[70:71], v[76:77], v[70:71]
	s_cmp_lt_i32 s5, 1
	v_pk_mul_f32 v[60:61], v[60:61], v[70:71]
	s_cselect_b64 s[10:11], -1, 0
	v_cvt_pk_bf16_f32 v70, v60, v61
	v_pk_mul_f32 v[60:61], v[78:79], v[84:85]
	v_mov_b32_e32 v96, 0
	v_pk_mul_f32 v[60:61], v[62:63], v[60:61]
	s_cmp_gt_i32 s5, 0
	v_cvt_pk_bf16_f32 v71, v60, v61
	v_add_u32_e32 v60, 32, v98
	v_mad_i64_i32 v[60:61], s[30:31], v60, s25, v[100:101]
	global_store_dwordx4 v[60:61], v[68:71], off
	v_mov_b32_e32 v60, 0
	v_mov_b32_e32 v61, 0
	v_mov_b32_e32 v62, 0
	v_mov_b32_e32 v63, 0
	s_cbranch_scc1 .LBB0_786
	ds_read_b128 v[60:63], v113 offset:1024
;     __host__ __device__ bool next(int i, Unit& u) const { const long L = (long)i * G + c; if (L >= maxL) return false; return unit_of(L, u); }
; #define LAS __attribute__((address_space(3)))
; __device__ __forceinline__ unsigned pk2(float lo, float hi) { const f32x2_t v = {lo, hi}; const bf16x2_t b = __builtin_convertvector(v, bf16x2_t); return __builtin_bit_cast(unsigned, b); }
; __device__ __forceinline__ float siluf_(float x) { return x * __builtin_amdgcn_rcpf(1.0f + __expf(-x)); }
;     __device__ bool next(int i, pg8::Unit& u) const { if (!pg8::StaticOrder::next(i >> 1, u)) return false; u.br = i & 1; return true; }
; __device__ __forceinline__ f32x4 ror1_4(const f32x4 v) { return (f32x4){dpp_ror1(v.x), dpp_ror1(v.y), dpp_ror1(v.z), dpp_ror1(v.w)}; }
; __device__ __forceinline__ f32x4 rol1_4(const f32x4 v) { return (f32x4){dpp_rol1(v.x), dpp_rol1(v.y), dpp_rol1(v.z), dpp_rol1(v.w)}; }
;     __device__ __forceinline__ void operator()(const f32x4 (&acc_c)[2][2][4][2], const pg8::Unit& u, int wr, int wc, int fr, int fq) const {
;     ...
;             for (int m = 0; m < 4; ++m) { u32x4 o;
; #pragma unroll
;                 for (int n = 0; n < 2; ++n) { const f32x4 cur = acc[0][0][m][n];
;                     f32x4 pu, nd;
;                     if (m > 0) pu = ror1_4(acc[0][0][m > 0 ? m - 1 : 0][n]); else pu = (bi > 0) ? *(const LAS f32x4*)(X + ((bi - 1) * 2 + 1) * 128 + cl + 4 * n) : (f32x4){0.f, 0.f, 0.f, 0.f};
;                     if (m < 3) nd = rol1_4(acc[0][0][m < 3 ? m + 1 : 3][n]); else nd = (bi < 1) ? *(const LAS f32x4*)(X + ((bi + 1) * 2 + 0) * 128 + cl + 4 * n) : (f32x4){0.f, 0.f, 0.f, 0.f};
;                     const f32x4 ps = ror1_4(cur), ns = rol1_4(cur);
;                     const f32x4 prev = (fr > 0) ? ps : pu, next = (fr < 15) ? ns : nd;
;                     const f32x4 uu = w0[n] * prev + w1[n] * cur + w2[n] * next + cbv[n]; const f32x4 gt = acc[0][1][m][n];
;                     f32x4 r; r.x = siluf_(uu.x) * gt.x; r.y = siluf_(uu.y) * gt.y; r.z = siluf_(uu.z) * gt.z; r.w = siluf_(uu.w) * gt.w;
;                     if (n == 0) { o.x = pk2(r.x, r.y); o.y = pk2(r.z, r.w); } else { o.z = pk2(r.x, r.y); o.w = pk2(r.z, r.w); } }
;                 const int rh = wr * 64 + m * 16 + fr;
;                 if (rh != 0 && rh != 127) *(u32x4*)(ACT + (size_t)(u.pm * 256 + half * 128 + rh) * FFN + ch0) = o; } }
.LBB0_786:
	v_mov_b32_e32 v123, v122
	v_mov_b32_dpp v85, v12 row_ror:1 row_mask:0xf bank_mask:0xf
	v_mov_b32_dpp v102, v13 row_ror:1 row_mask:0xf bank_mask:0xf
	v_mov_b32_dpp v86, v14 row_ror:1 row_mask:0xf bank_mask:0xf
	v_mov_b32_dpp v103, v15 row_ror:1 row_mask:0xf bank_mask:0xf
	v_mov_b32_dpp v76, v12 row_ror:15 row_mask:0xf bank_mask:0xf
	v_mov_b32_dpp v78, v13 row_ror:15 row_mask:0xf bank_mask:0xf
	v_mov_b32_dpp v77, v14 row_ror:15 row_mask:0xf bank_mask:0xf
	v_mov_b32_dpp v79, v15 row_ror:15 row_mask:0xf bank_mask:0xf
	v_mov_b32_dpp v68, v74 row_ror:1 row_mask:0xf bank_mask:0xf
	v_mov_b32_dpp v69, v75 row_ror:1 row_mask:0xf bank_mask:0xf
	v_mov_b32_dpp v70, v72 row_ror:1 row_mask:0xf bank_mask:0xf
	v_mov_b32_dpp v71, v73 row_ror:1 row_mask:0xf bank_mask:0xf
	s_andn2_b64 vcc, exec, s[10:11]
	v_mov_b32_e32 v97, 0
	v_mov_b32_e32 v98, 0
	v_mov_b32_e32 v99, 0
	s_cbranch_vccnz .LBB0_788
	ds_read_b128 v[96:99], v113 offset:1040
.LBB0_788:
	v_mov_b32_e32 v72, v122
	v_mov_b32_e32 v73, v122
	v_pk_fma_f32 v[6:7], v[6:7], v[72:73], v[94:95]
	v_pk_fma_f32 v[2:3], v[2:3], v[72:73], v[90:91]
	v_pk_fma_f32 v[0:1], v[0:1], v[122:123], v[88:89]
	s_movk_i32 s10, 0x4f
	v_pk_fma_f32 v[4:5], v[4:5], v[122:123], v[92:93]
	v_mov_b32_dpp v84, v8 row_ror:1 row_mask:0xf bank_mask:0xf
	v_mov_b32_dpp v87, v9 row_ror:1 row_mask:0xf bank_mask:0xf
	v_mov_b32_dpp v88, v10 row_ror:1 row_mask:0xf bank_mask:0xf
	v_mov_b32_dpp v89, v11 row_ror:1 row_mask:0xf bank_mask:0xf
	v_mov_b32_dpp v73, v8 row_ror:15 row_mask:0xf bank_mask:0xf
	v_mov_b32_dpp v74, v9 row_ror:15 row_mask:0xf bank_mask:0xf
	v_mov_b32_dpp v75, v10 row_ror:15 row_mask:0xf bank_mask:0xf
	v_mov_b32_dpp v72, v11 row_ror:15 row_mask:0xf bank_mask:0xf
	v_cmp_ne_u32_e32 vcc, s10, v127
	s_and_saveexec_b64 s[10:11], vcc
	s_cbranch_execz .LBB0_790
	v_cndmask_b32_e64 v91, v102, v82, s[8:9]
	v_cndmask_b32_e64 v83, v103, v83, s[8:9]
	v_cndmask_b32_e64 v82, v86, v81, s[8:9]
	v_pk_mul_f32 v[58:59], v[58:59], v[82:83]
	s_waitcnt lgkmcnt(0)
	v_cndmask_b32_e64 v63, v79, v63, s[6:7]
	v_pk_fma_f32 v[58:59], v[66:67], v[14:15], v[58:59]
	v_cndmask_b32_e64 v62, v77, v62, s[6:7]
	v_pk_fma_f32 v[54:55], v[54:55], v[62:63], v[58:59]
	v_cndmask_b32_e64 v90, v85, v80, s[8:9]
	v_pk_add_f32 v[46:47], v[46:47], v[54:55]
	v_pk_mul_f32 v[56:57], v[56:57], v[90:91]
	v_mul_f32_e32 v54, 0xbfb8aa3b, v47
	v_exp_f32_e32 v54, v54
	v_mul_f32_e32 v55, 0xbfb8aa3b, v46
	v_pk_fma_f32 v[56:57], v[64:65], v[12:13], v[56:57]
	v_cndmask_b32_e64 v61, v78, v61, s[6:7]
	v_cndmask_b32_e64 v60, v76, v60, s[6:7]
	v_exp_f32_e32 v55, v55
	v_pk_fma_f32 v[52:53], v[52:53], v[60:61], v[56:57]
	s_nop 0
	v_pk_add_f32 v[44:45], v[44:45], v[52:53]
	v_add_f32_e32 v52, 1.0, v54
	v_mul_f32_e32 v54, 0xbfb8aa3b, v45
	v_rcp_f32_e32 v53, v52
	v_add_f32_e32 v52, 1.0, v55
	v_exp_f32_e32 v54, v54
	v_mul_f32_e32 v55, 0xbfb8aa3b, v44
	v_exp_f32_e32 v56, v55
	v_rcp_f32_e32 v52, v52
	v_add_f32_e32 v54, 1.0, v54
	v_rcp_f32_e32 v55, v54
	v_add_f32_e32 v54, 1.0, v56
	v_rcp_f32_e32 v54, v54
	v_pk_mul_f32 v[46:47], v[46:47], v[52:53]
	v_cndmask_b32_e64 v53, v87, v69, s[8:9]
	v_pk_mul_f32 v[46:47], v[6:7], v[46:47]
	v_pk_mul_f32 v[44:45], v[44:45], v[54:55]
	v_cndmask_b32_e64 v52, v84, v68, s[8:9]
	v_pk_mul_f32 v[44:45], v[4:5], v[44:45]
	v_pk_mul_f32 v[32:33], v[32:33], v[52:53]
	v_cvt_pk_bf16_f32 v44, v44, v45
	v_cvt_pk_bf16_f32 v45, v46, v47
	v_cndmask_b32_e64 v47, v89, v71, s[8:9]
	v_cndmask_b32_e64 v46, v88, v70, s[8:9]
	v_pk_mul_f32 v[34:35], v[34:35], v[46:47]
	v_pk_fma_f32 v[32:33], v[36:37], v[8:9], v[32:33]
	v_pk_fma_f32 v[34:35], v[38:39], v[10:11], v[34:35]
	v_cndmask_b32_e64 v39, v74, v97, s[6:7]
	v_cndmask_b32_e64 v38, v73, v96, s[6:7]
	v_pk_fma_f32 v[28:29], v[28:29], v[38:39], v[32:33]
	v_cndmask_b32_e64 v37, v72, v99, s[6:7]
	v_cndmask_b32_e64 v36, v75, v98, s[6:7]
	v_pk_add_f32 v[24:25], v[24:25], v[28:29]
	v_pk_fma_f32 v[30:31], v[30:31], v[36:37], v[34:35]
	v_mul_f32_e32 v28, 0xbfb8aa3b, v24
	v_mul_f32_e32 v29, 0xbfb8aa3b, v25
	v_exp_f32_e32 v28, v28
	v_exp_f32_e32 v29, v29
	v_pk_add_f32 v[26:27], v[26:27], v[30:31]
	v_add_f32_e32 v28, 1.0, v28
	v_mul_f32_e32 v30, 0xbfb8aa3b, v26
	v_mul_f32_e32 v31, 0xbfb8aa3b, v27
	v_exp_f32_e32 v30, v30
	v_exp_f32_e32 v31, v31
	v_add_f32_e32 v29, 1.0, v29
	v_rcp_f32_e32 v28, v28
	v_rcp_f32_e32 v29, v29
	v_add_f32_e32 v30, 1.0, v30
	v_add_f32_e32 v31, 1.0, v31
	v_rcp_f32_e32 v30, v30
	v_rcp_f32_e32 v31, v31
	v_pk_mul_f32 v[24:25], v[24:25], v[28:29]
	s_nop 0
	v_pk_mul_f32 v[24:25], v[0:1], v[24:25]
	s_nop 0
	v_cvt_pk_bf16_f32 v46, v24, v25
	v_pk_mul_f32 v[24:25], v[26:27], v[30:31]
	s_nop 0
	v_pk_mul_f32 v[24:25], v[2:3], v[24:25]
	s_nop 0
	v_cvt_pk_bf16_f32 v47, v24, v25
	v_add3_u32 v24, v112, v127, 48
	v_mad_i64_i32 v[24:25], s[30:31], v24, s25, v[100:101]
	global_store_dwordx4 v[24:25], v[44:47], off

; #define LAS __attribute__((address_space(3)))
;     __device__ __forceinline__ void operator()(const f32x4 (&acc_c)[2][2][4][2], const pg8::Unit& u, int wr, int wc, int fr, int fq) const {
;     ...
;         for (int ai = 0; ai < 2; ++ai)
; #pragma unroll
;             for (int m = 0; m < 4; ++m) { const int rl = ai * 128 + wr * 64 + m * 16 + fr;
;                 const float rstd = __builtin_amdgcn_rsqf(rsq[rl] * (1.0f / D_MODEL) + EPS);
; #pragma unroll
;                 for (int bj = 0; bj < 2; ++bj)
; #pragma unroll
;                     for (int n = 0; n < 2; ++n) acc[ai][bj][m][n] = acc[ai][bj][m][n] * rstd + *(const LAS f32x4*)(bias2 + bj * 128 + cl + 4 * n); }
;         f32x4 w0[2], w1[2], w2[2], cbv[2];
; #pragma unroll
;         for (int n = 0; n < 2; ++n) { w0[n] = *(const f32x4*)(cw + ch0 + 4 * n); w1[n] = *(const f32x4*)(cw + FFN + ch0 + 4 * n); w2[n] = *(const f32x4*)(cw + 2 * FFN + ch0 + 4 * n); cbv[n] = *(const f32x4*)(cb + ch0 + 4 * n); }
; #pragma unroll
;         for (int ai = 0; ai < 2; ++ai) { const int bi = 2 * ai + wr;
;             if (fr == 0) {
; #pragma unroll
;                 for (int n = 0; n < 2; ++n) *(LAS f32x4*)(X + (bi * 2 + 0) * 128 + cl + 4 * n) = acc[ai][0][0][n]; }
;             if (fr == 15) {
; #pragma unroll
;                 for (int n = 0; n < 2; ++n) *(LAS f32x4*)(X + (bi * 2 + 1) * 128 + cl + 4 * n) = acc[ai][0][3][n]; } }
;         asm volatile("s_waitcnt lgkmcnt(0)" ::: "memory"); __builtin_amdgcn_s_barrier(); asm volatile("" ::: "memory");
; #pragma unroll
;         for (int ai = 0; ai < 2; ++ai) { const int bi = 2 * ai + wr;
; #pragma unroll
;             for (int m = 0; m < 4; ++m) { u32x4 o;
; #pragma unroll
;                 for (int n = 0; n < 2; ++n) { const f32x4 cur = acc[ai][0][m][n];
;                     f32x4 pu, nd;
;                     if (m > 0) pu = ror1_4(acc[ai][0][m > 0 ? m - 1 : 0][n]); else pu = (bi > 0) ? *(const LAS f32x4*)(X + ((bi - 1) * 2 + 1) * 128 + cl + 4 * n) : (f32x4){0.f, 0.f, 0.f, 0.f};
;                     if (m < 3) nd = rol1_4(acc[ai][0][m < 3 ? m + 1 : 3][n]); else nd = (bi < 3) ? *(const LAS f32x4*)(X + ((bi + 1) * 2 + 0) * 128 + cl + 4 * n) : (f32x4){0.f, 0.f, 0.f, 0.f};
;                     const f32x4 ps = ror1_4(cur), ns = rol1_4(cur);
;                     const f32x4 prev = (fr > 0) ? ps : pu, next = (fr < 15) ? ns : nd;
.LBB0_839:
	v_fmamk_f32 v177, v215, 0x3a000000, v224
	v_rsq_f32_e32 v218, v177
	s_nop 0
	v_pk_fma_f32 v[174:175], v[174:175], v[218:219], v[126:127] op_sel_hi:[1,0,1]
	v_pk_fma_f32 v[214:215], v[172:173], v[218:219], v[124:125] op_sel_hi:[1,0,1]
	s_nop 1
	v_mov_b32_dpp v208, v214 row_ror:15 row_mask:0xf bank_mask:0xf
	v_mov_b32_dpp v227, v215 row_ror:15 row_mask:0xf bank_mask:0xf
	v_mov_b32_dpp v228, v174 row_ror:15 row_mask:0xf bank_mask:0xf
	v_mov_b32_dpp v229, v175 row_ror:15 row_mask:0xf bank_mask:0xf
	v_mov_b32_dpp v234, v40 row_ror:1 row_mask:0xf bank_mask:0xf
	v_mov_b32_dpp v236, v41 row_ror:1 row_mask:0xf bank_mask:0xf
	v_mov_b32_dpp v235, v42 row_ror:1 row_mask:0xf bank_mask:0xf
	v_mov_b32_dpp v238, v43 row_ror:1 row_mask:0xf bank_mask:0xf
	v_mov_b32_dpp v230, v40 row_ror:15 row_mask:0xf bank_mask:0xf
	v_mov_b32_dpp v232, v41 row_ror:15 row_mask:0xf bank_mask:0xf
	v_mov_b32_dpp v231, v42 row_ror:15 row_mask:0xf bank_mask:0xf
	v_mov_b32_dpp v233, v43 row_ror:15 row_mask:0xf bank_mask:0xf
	s_andn2_b64 vcc, exec, s[46:47]
	v_mov_b32_e32 v177, 0
	v_mov_b32_e32 v178, 0
	v_mov_b32_e32 v179, 0
	s_cbranch_vccnz .LBB0_841
	ds_read_b128 v[176:179], v192 offset:16
.LBB0_841:
	v_mov_b32_e32 v219, v218
	v_mov_b32_e32 v240, v216
	v_mov_b32_e32 v241, v216
	v_pk_fma_f32 v[104:105], v[104:105], v[216:217], v[96:97]
	v_pk_fma_f32 v[108:109], v[108:109], v[216:217], v[92:93]
	v_mov_b32_e32 v216, v218
	v_mov_b32_e32 v217, v218
	v_pk_fma_f32 v[106:107], v[106:107], v[240:241], v[98:99]
	v_or_b32_e32 v192, s85, v225
	s_lshl_b32 s27, s26, 8
	v_pk_fma_f32 v[110:111], v[110:111], v[240:241], v[94:95]
	v_pk_fma_f32 v[166:167], v[166:167], v[216:217], v[122:123]
	v_pk_fma_f32 v[164:165], v[164:165], v[218:219], v[120:121]
	v_cmp_eq_u32_e64 s[10:11], 0, v225
	v_cmp_eq_u32_e64 s[8:9], 15, v225
	v_lshl_add_u64 v[172:173], v[200:201], 1, s[56:57]
	v_mov_b32_dpp v237, v164 row_ror:15 row_mask:0xf bank_mask:0xf
	v_mov_b32_dpp v239, v165 row_ror:15 row_mask:0xf bank_mask:0xf
	v_mov_b32_dpp v240, v166 row_ror:15 row_mask:0xf bank_mask:0xf
	v_mov_b32_dpp v241, v167 row_ror:15 row_mask:0xf bank_mask:0xf
	v_mov_b32_dpp v246, v36 row_ror:1 row_mask:0xf bank_mask:0xf
	v_mov_b32_dpp v247, v37 row_ror:1 row_mask:0xf bank_mask:0xf
	v_mov_b32_dpp v248, v38 row_ror:1 row_mask:0xf bank_mask:0xf
	v_mov_b32_dpp v249, v39 row_ror:1 row_mask:0xf bank_mask:0xf
	v_mov_b32_dpp v242, v36 row_ror:15 row_mask:0xf bank_mask:0xf
	v_mov_b32_dpp v243, v37 row_ror:15 row_mask:0xf bank_mask:0xf
	v_mov_b32_dpp v244, v38 row_ror:15 row_mask:0xf bank_mask:0xf
	v_mov_b32_dpp v245, v39 row_ror:15 row_mask:0xf bank_mask:0xf
	v_cmp_ne_u32_e32 vcc, 0, v192
	v_mov_b32_e32 v205, s27
	s_and_saveexec_b64 s[12:13], vcc
	s_cbranch_execz .LBB0_843
	s_waitcnt lgkmcnt(0)
	v_cndmask_b32_e64 v183, v238, v183, s[10:11]
	v_cndmask_b32_e64 v182, v235, v182, s[10:11]
	s_waitcnt vmcnt(0)
	v_pk_mul_f32 v[182:183], v[86:87], v[182:183]
	v_cndmask_b32_e64 v229, v233, v229, s[8:9]
	v_pk_fma_f32 v[182:183], v[42:43], v[78:79], v[182:183]
	v_cndmask_b32_e64 v228, v231, v228, s[8:9]
	v_pk_fma_f32 v[182:183], v[74:75], v[228:229], v[182:183]
	v_cndmask_b32_e64 v181, v236, v181, s[10:11]
	v_pk_add_f32 v[182:183], v[70:71], v[182:183]
	v_cndmask_b32_e64 v180, v234, v180, s[10:11]
	v_mul_f32_e32 v205, 0xbfb8aa3b, v183
	v_cndmask_b32_e64 v234, v230, v208, s[8:9]
	v_exp_f32_e32 v205, v205
	v_mul_f32_e32 v208, 0xbfb8aa3b, v182
	v_pk_mul_f32 v[180:181], v[84:85], v[180:181]
	v_exp_f32_e32 v208, v208
	v_pk_fma_f32 v[180:181], v[40:41], v[76:77], v[180:181]
	v_cndmask_b32_e64 v235, v232, v227, s[8:9]
	v_pk_fma_f32 v[180:181], v[72:73], v[234:235], v[180:181]
	v_add_f32_e32 v205, 1.0, v205
	v_pk_add_f32 v[180:181], v[68:69], v[180:181]
	v_rcp_f32_e32 v229, v205
	v_add_f32_e32 v205, 1.0, v208
	v_mul_f32_e32 v208, 0xbfb8aa3b, v181
	v_exp_f32_e32 v208, v208
	v_mul_f32_e32 v227, 0xbfb8aa3b, v180
	v_exp_f32_e32 v227, v227
	v_rcp_f32_e32 v228, v205
	v_add_f32_e32 v205, 1.0, v208
	v_rcp_f32_e32 v231, v205
	v_add_f32_e32 v205, 1.0, v227
	v_rcp_f32_e32 v230, v205
	v_cndmask_b32_e64 v177, v247, v177, s[10:11]
	v_cndmask_b32_e64 v176, v246, v176, s[10:11]
	v_pk_mul_f32 v[182:183], v[182:183], v[228:229]
	v_pk_mul_f32 v[180:181], v[180:181], v[230:231]
	v_cndmask_b32_e64 v179, v249, v179, s[10:11]
	v_cndmask_b32_e64 v178, v248, v178, s[10:11]
	v_pk_mul_f32 v[176:177], v[60:61], v[176:177]
	v_pk_mul_f32 v[182:183], v[106:107], v[182:183]
	v_pk_mul_f32 v[180:181], v[104:105], v[180:181]
	v_pk_mul_f32 v[178:179], v[62:63], v[178:179]
	v_pk_fma_f32 v[176:177], v[36:37], v[56:57], v[176:177]
	v_cndmask_b32_e64 v229, v243, v239, s[8:9]
	v_cndmask_b32_e64 v228, v242, v237, s[8:9]
	v_cvt_pk_bf16_f32 v180, v180, v181
	v_cvt_pk_bf16_f32 v181, v182, v183
	v_pk_fma_f32 v[178:179], v[38:39], v[58:59], v[178:179]
	v_cndmask_b32_e64 v183, v245, v241, s[8:9]
	v_cndmask_b32_e64 v182, v244, v240, s[8:9]
	v_pk_fma_f32 v[176:177], v[48:49], v[228:229], v[176:177]
	v_pk_fma_f32 v[178:179], v[50:51], v[182:183], v[178:179]
	v_pk_add_f32 v[176:177], v[44:45], v[176:177]
	v_pk_add_f32 v[178:179], v[46:47], v[178:179]
	v_mul_f32_e32 v182, 0xbfb8aa3b, v176
	v_mul_f32_e32 v183, 0xbfb8aa3b, v177
	v_exp_f32_e32 v182, v182
	v_exp_f32_e32 v183, v183
	v_mul_f32_e32 v205, 0xbfb8aa3b, v178
	v_exp_f32_e32 v205, v205
	v_mul_f32_e32 v208, 0xbfb8aa3b, v179
	v_exp_f32_e32 v208, v208
	v_add_f32_e32 v182, 1.0, v182
	v_add_f32_e32 v183, 1.0, v183
	v_rcp_f32_e32 v182, v182
	v_rcp_f32_e32 v183, v183
	v_add_f32_e32 v205, 1.0, v205
	v_rcp_f32_e32 v228, v205
	v_add_f32_e32 v205, 1.0, v208
	v_rcp_f32_e32 v229, v205
	v_pk_mul_f32 v[176:177], v[176:177], v[182:183]
	v_add_u32_e32 v205, s27, v192
	v_pk_mul_f32 v[176:177], v[108:109], v[176:177]
	s_nop 0
	v_cvt_pk_bf16_f32 v182, v176, v177
	v_pk_mul_f32 v[176:177], v[178:179], v[228:229]
	s_nop 0
	v_pk_mul_f32 v[176:177], v[110:111], v[176:177]
	s_nop 0
	v_cvt_pk_bf16_f32 v183, v176, v177
	v_mad_i64_i32 v[176:177], s[40:41], v205, s38, v[172:173]
	global_store_dwordx4 v[176:177], v[180:183], off
; #define LAS __attribute__((address_space(3)))
;     __device__ __forceinline__ void operator()(const f32x4 (&acc_c)[2][2][4][2], const pg8::Unit& u, int wr, int wc, int fr, int fq) const {
;     ...
;         for (int ai = 0; ai < 2; ++ai)
; #pragma unroll
;             for (int m = 0; m < 4; ++m) { const int rl = ai * 128 + wr * 64 + m * 16 + fr;
;                 const float rstd = __builtin_amdgcn_rsqf(rsq[rl] * (1.0f / D_MODEL) + EPS);
; #pragma unroll
;                 for (int bj = 0; bj < 2; ++bj)
; #pragma unroll
;                     for (int n = 0; n < 2; ++n) acc[ai][bj][m][n] = acc[ai][bj][m][n] * rstd + *(const LAS f32x4*)(bias2 + bj * 128 + cl + 4 * n); }
;         f32x4 w0[2], w1[2], w2[2], cbv[2];
; #pragma unroll
;         for (int n = 0; n < 2; ++n) { w0[n] = *(const f32x4*)(cw + ch0 + 4 * n); w1[n] = *(const f32x4*)(cw + FFN + ch0 + 4 * n); w2[n] = *(const f32x4*)(cw + 2 * FFN + ch0 + 4 * n); cbv[n] = *(const f32x4*)(cb + ch0 + 4 * n); }
; #pragma unroll
;         for (int ai = 0; ai < 2; ++ai) { const int bi = 2 * ai + wr;
;             if (fr == 0) {
; #pragma unroll
;                 for (int n = 0; n < 2; ++n) *(LAS f32x4*)(X + (bi * 2 + 0) * 128 + cl + 4 * n) = acc[ai][0][0][n]; }
;             if (fr == 15) {
; #pragma unroll
;                 for (int n = 0; n < 2; ++n) *(LAS f32x4*)(X + (bi * 2 + 1) * 128 + cl + 4 * n) = acc[ai][0][3][n]; } }
;         asm volatile("s_waitcnt lgkmcnt(0)" ::: "memory"); __builtin_amdgcn_s_barrier(); asm volatile("" ::: "memory");
; #pragma unroll
;         for (int ai = 0; ai < 2; ++ai) { const int bi = 2 * ai + wr;
; #pragma unroll
;             for (int m = 0; m < 4; ++m) { u32x4 o;
; #pragma unroll
;                 for (int n = 0; n < 2; ++n) { const f32x4 cur = acc[ai][0][m][n];
;                     f32x4 pu, nd;
;                     if (m > 0) pu = ror1_4(acc[ai][0][m > 0 ? m - 1 : 0][n]); else pu = (bi > 0) ? *(const LAS f32x4*)(X + ((bi - 1) * 2 + 1) * 128 + cl + 4 * n) : (f32x4){0.f, 0.f, 0.f, 0.f};
;                     if (m < 3) nd = rol1_4(acc[ai][0][m < 3 ? m + 1 : 3][n]); else nd = (bi < 3) ? *(const LAS f32x4*)(X + ((bi + 1) * 2 + 0) * 128 + cl + 4 * n) : (f32x4){0.f, 0.f, 0.f, 0.f};
;                     const f32x4 ps = ror1_4(cur), ns = rol1_4(cur);
;                     const f32x4 prev = (fr > 0) ? ps : pu, next = (fr < 15) ? ns : nd;
.LBB0_843:
	s_or_b64 exec, exec, s[12:13]
	s_waitcnt lgkmcnt(0)
	v_pk_fma_f32 v[176:177], v[150:151], v[216:217], v[98:99]
	v_fmamk_f32 v150, v212, 0x3a000000, v224
	v_rsq_f32_e32 v178, v150
	v_pk_fma_f32 v[180:181], v[148:149], v[218:219], v[96:97]
	v_pk_fma_f32 v[182:183], v[146:147], v[216:217], v[94:95]
	v_pk_fma_f32 v[216:217], v[144:145], v[218:219], v[92:93]
	v_pk_fma_f32 v[144:145], v[154:155], v[178:179], v[122:123] op_sel_hi:[1,0,1]
	v_mov_b32_dpp v154, v40 row_ror:1 row_mask:0xf bank_mask:0xf
	v_mov_b32_dpp v155, v41 row_ror:1 row_mask:0xf bank_mask:0xf
	v_mov_b32_dpp v218, v214 row_ror:1 row_mask:0xf bank_mask:0xf
	v_mov_b32_dpp v219, v215 row_ror:1 row_mask:0xf bank_mask:0xf
	v_pk_fma_f32 v[148:149], v[158:159], v[178:179], v[126:127] op_sel_hi:[1,0,1]
	v_pk_fma_f32 v[150:151], v[156:157], v[178:179], v[124:125] op_sel_hi:[1,0,1]
	v_pk_fma_f32 v[146:147], v[152:153], v[178:179], v[120:121] op_sel_hi:[1,0,1]
	v_pk_fma_f32 v[142:143], v[142:143], v[178:179], v[98:99] op_sel_hi:[1,0,1]
	v_pk_fma_f32 v[140:141], v[140:141], v[178:179], v[96:97] op_sel_hi:[1,0,1]
	v_pk_fma_f32 v[138:139], v[138:139], v[178:179], v[94:95] op_sel_hi:[1,0,1]
	v_pk_fma_f32 v[136:137], v[136:137], v[178:179], v[92:93] op_sel_hi:[1,0,1]
	v_cndmask_b32_e64 v155, v219, v155, s[10:11]
	v_cndmask_b32_e64 v154, v218, v154, s[10:11]
	v_mov_b32_dpp v152, v42 row_ror:1 row_mask:0xf bank_mask:0xf
	v_mov_b32_dpp v153, v43 row_ror:1 row_mask:0xf bank_mask:0xf
	v_mov_b32_dpp v178, v150 row_ror:15 row_mask:0xf bank_mask:0xf
	v_mov_b32_dpp v179, v151 row_ror:15 row_mask:0xf bank_mask:0xf
	v_mov_b32_dpp v227, v174 row_ror:1 row_mask:0xf bank_mask:0xf
	v_mov_b32_dpp v228, v175 row_ror:1 row_mask:0xf bank_mask:0xf
	v_mov_b32_dpp v158, v214 row_ror:15 row_mask:0xf bank_mask:0xf
	v_mov_b32_dpp v159, v215 row_ror:15 row_mask:0xf bank_mask:0xf
	s_waitcnt vmcnt(0)
	v_pk_mul_f32 v[154:155], v[84:85], v[154:155]
	v_cndmask_b32_e64 v153, v228, v153, s[10:11]
	v_cndmask_b32_e64 v152, v227, v152, s[10:11]
	v_pk_fma_f32 v[154:155], v[214:215], v[76:77], v[154:155]
	v_cndmask_b32_e64 v159, v159, v179, s[8:9]
	v_cndmask_b32_e64 v158, v158, v178, s[8:9]
	v_mov_b32_dpp v208, v148 row_ror:15 row_mask:0xf bank_mask:0xf
	v_mov_b32_dpp v212, v149 row_ror:15 row_mask:0xf bank_mask:0xf
	v_mov_b32_dpp v156, v174 row_ror:15 row_mask:0xf bank_mask:0xf
	v_mov_b32_dpp v157, v175 row_ror:15 row_mask:0xf bank_mask:0xf
	v_pk_mul_f32 v[152:153], v[86:87], v[152:153]
	v_pk_fma_f32 v[154:155], v[72:73], v[158:159], v[154:155]
	v_pk_fma_f32 v[152:153], v[174:175], v[78:79], v[152:153]
	v_cndmask_b32_e64 v157, v157, v212, s[8:9]
	v_cndmask_b32_e64 v156, v156, v208, s[8:9]
	v_pk_add_f32 v[154:155], v[68:69], v[154:155]
	v_pk_fma_f32 v[152:153], v[74:75], v[156:157], v[152:153]
	v_mul_f32_e32 v156, 0xbfb8aa3b, v154
	v_exp_f32_e32 v158, v156
	v_mul_f32_e32 v156, 0xbfb8aa3b, v155
	v_exp_f32_e32 v159, v156
	v_pk_add_f32 v[156:157], v[70:71], v[152:153]
	v_add_f32_e32 v152, 1.0, v158
	v_mul_f32_e32 v158, 0xbfb8aa3b, v156
	v_add_f32_e32 v153, 1.0, v159
	v_mul_f32_e32 v159, 0xbfb8aa3b, v157
	v_exp_f32_e32 v158, v158
	v_exp_f32_e32 v159, v159
	v_rcp_f32_e32 v152, v152
	v_rcp_f32_e32 v153, v153
	v_add_f32_e32 v158, 1.0, v158
	v_add_f32_e32 v159, 1.0, v159
	v_rcp_f32_e32 v158, v158
	v_rcp_f32_e32 v159, v159
	v_mov_b32_dpp v229, v36 row_ror:1 row_mask:0xf bank_mask:0xf
	v_mov_b32_dpp v230, v37 row_ror:1 row_mask:0xf bank_mask:0xf
	v_mov_b32_dpp v237, v164 row_ror:1 row_mask:0xf bank_mask:0xf
	v_mov_b32_dpp v238, v165 row_ror:1 row_mask:0xf bank_mask:0xf
	v_pk_mul_f32 v[152:153], v[154:155], v[152:153]
	v_pk_mul_f32 v[154:155], v[156:157], v[158:159]
	v_cndmask_b32_e64 v157, v238, v230, s[10:11]
	v_cndmask_b32_e64 v156, v237, v229, s[10:11]
	v_mov_b32_dpp v231, v38 row_ror:1 row_mask:0xf bank_mask:0xf
	v_mov_b32_dpp v232, v39 row_ror:1 row_mask:0xf bank_mask:0xf
	v_mov_b32_dpp v233, v146 row_ror:15 row_mask:0xf bank_mask:0xf
	v_mov_b32_dpp v234, v147 row_ror:15 row_mask:0xf bank_mask:0xf
	v_mov_b32_dpp v239, v166 row_ror:1 row_mask:0xf bank_mask:0xf
	v_mov_b32_dpp v240, v167 row_ror:1 row_mask:0xf bank_mask:0xf
	v_mov_b32_dpp v241, v164 row_ror:15 row_mask:0xf bank_mask:0xf
	v_mov_b32_dpp v242, v165 row_ror:15 row_mask:0xf bank_mask:0xf
	v_pk_mul_f32 v[152:153], v[180:181], v[152:153]
	v_pk_mul_f32 v[154:155], v[176:177], v[154:155]
	v_pk_mul_f32 v[156:157], v[60:61], v[156:157]
	v_cvt_pk_bf16_f32 v152, v152, v153
	v_cvt_pk_bf16_f32 v153, v154, v155
	v_cndmask_b32_e64 v155, v240, v232, s[10:11]
	v_cndmask_b32_e64 v154, v239, v231, s[10:11]
	v_pk_fma_f32 v[156:157], v[164:165], v[56:57], v[156:157]
	v_cndmask_b32_e64 v165, v242, v234, s[8:9]
	v_cndmask_b32_e64 v164, v241, v233, s[8:9]
	v_mov_b32_dpp v235, v144 row_ror:15 row_mask:0xf bank_mask:0xf
	v_mov_b32_dpp v236, v145 row_ror:15 row_mask:0xf bank_mask:0xf
	v_mov_b32_dpp v243, v166 row_ror:15 row_mask:0xf bank_mask:0xf
	v_mov_b32_dpp v244, v167 row_ror:15 row_mask:0xf bank_mask:0xf
	v_pk_mul_f32 v[154:155], v[62:63], v[154:155]
	v_pk_fma_f32 v[156:157], v[48:49], v[164:165], v[156:157]
	v_pk_fma_f32 v[154:155], v[166:167], v[58:59], v[154:155]
	v_cndmask_b32_e64 v159, v244, v236, s[8:9]
	v_cndmask_b32_e64 v158, v243, v235, s[8:9]
	v_pk_add_f32 v[156:157], v[44:45], v[156:157]
	v_pk_fma_f32 v[154:155], v[50:51], v[158:159], v[154:155]
	v_mul_f32_e32 v158, 0xbfb8aa3b, v156
	v_exp_f32_e32 v164, v158
	v_mul_f32_e32 v158, 0xbfb8aa3b, v157
	v_exp_f32_e32 v165, v158
	v_pk_add_f32 v[158:159], v[46:47], v[154:155]
	v_add_f32_e32 v154, 1.0, v164
	v_mul_f32_e32 v164, 0xbfb8aa3b, v158
	v_add_f32_e32 v155, 1.0, v165
	v_mul_f32_e32 v165, 0xbfb8aa3b, v159
	v_exp_f32_e32 v164, v164
; #define LAS __attribute__((address_space(3)))
;     __device__ __forceinline__ void operator()(const f32x4 (&acc_c)[2][2][4][2], const pg8::Unit& u, int wr, int wc, int fr, int fq) const {
;     ...
;         for (int ai = 0; ai < 2; ++ai)
; #pragma unroll
;             for (int m = 0; m < 4; ++m) { const int rl = ai * 128 + wr * 64 + m * 16 + fr;
;                 const float rstd = __builtin_amdgcn_rsqf(rsq[rl] * (1.0f / D_MODEL) + EPS);
; #pragma unroll
;                 for (int bj = 0; bj < 2; ++bj)
; #pragma unroll
;                     for (int n = 0; n < 2; ++n) acc[ai][bj][m][n] = acc[ai][bj][m][n] * rstd + *(const LAS f32x4*)(bias2 + bj * 128 + cl + 4 * n); }
;         f32x4 w0[2], w1[2], w2[2], cbv[2];
; #pragma unroll
;         for (int n = 0; n < 2; ++n) { w0[n] = *(const f32x4*)(cw + ch0 + 4 * n); w1[n] = *(const f32x4*)(cw + FFN + ch0 + 4 * n); w2[n] = *(const f32x4*)(cw + 2 * FFN + ch0 + 4 * n); cbv[n] = *(const f32x4*)(cb + ch0 + 4 * n); }
; #pragma unroll
;         for (int ai = 0; ai < 2; ++ai) { const int bi = 2 * ai + wr;
;             if (fr == 0) {
; #pragma unroll
;                 for (int n = 0; n < 2; ++n) *(LAS f32x4*)(X + (bi * 2 + 0) * 128 + cl + 4 * n) = acc[ai][0][0][n]; }
;             if (fr == 15) {
; #pragma unroll
;                 for (int n = 0; n < 2; ++n) *(LAS f32x4*)(X + (bi * 2 + 1) * 128 + cl + 4 * n) = acc[ai][0][3][n]; } }
;         asm volatile("s_waitcnt lgkmcnt(0)" ::: "memory"); __builtin_amdgcn_s_barrier(); asm volatile("" ::: "memory");
; #pragma unroll
;         for (int ai = 0; ai < 2; ++ai) { const int bi = 2 * ai + wr;
; #pragma unroll
;             for (int m = 0; m < 4; ++m) { u32x4 o;
; #pragma unroll
;                 for (int n = 0; n < 2; ++n) { const f32x4 cur = acc[ai][0][m][n];
;                     f32x4 pu, nd;
;                     if (m > 0) pu = ror1_4(acc[ai][0][m > 0 ? m - 1 : 0][n]); else pu = (bi > 0) ? *(const LAS f32x4*)(X + ((bi - 1) * 2 + 1) * 128 + cl + 4 * n) : (f32x4){0.f, 0.f, 0.f, 0.f};
;                     if (m < 3) nd = rol1_4(acc[ai][0][m < 3 ? m + 1 : 3][n]); else nd = (bi < 3) ? *(const LAS f32x4*)(X + ((bi + 1) * 2 + 0) * 128 + cl + 4 * n) : (f32x4){0.f, 0.f, 0.f, 0.f};
;                     const f32x4 ps = ror1_4(cur), ns = rol1_4(cur);
;                     const f32x4 prev = (fr > 0) ? ps : pu, next = (fr < 15) ? ns : nd;
	v_exp_f32_e32 v165, v165
	v_rcp_f32_e32 v154, v154
	v_rcp_f32_e32 v155, v155
	v_add_f32_e32 v164, 1.0, v164
	v_add_f32_e32 v165, 1.0, v165
	v_rcp_f32_e32 v164, v164
	v_rcp_f32_e32 v165, v165
	v_pk_mul_f32 v[154:155], v[156:157], v[154:155]
	v_pk_mul_f32 v[154:155], v[216:217], v[154:155]
	v_pk_mul_f32 v[156:157], v[158:159], v[164:165]
	v_cvt_pk_bf16_f32 v154, v154, v155
	v_pk_mul_f32 v[156:157], v[182:183], v[156:157]
	v_cvt_pk_bf16_f32 v155, v156, v157
	v_or_b32_e32 v156, 16, v205
	v_mad_i64_i32 v[156:157], s[12:13], v156, s38, v[172:173]
	global_store_dwordx4 v[156:157], v[152:155], off
	s_nop 1
	v_mov_b32_dpp v153, v148 row_ror:1 row_mask:0xf bank_mask:0xf
	v_mov_b32_dpp v155, v149 row_ror:1 row_mask:0xf bank_mask:0xf
	v_mov_b32_dpp v152, v150 row_ror:1 row_mask:0xf bank_mask:0xf
	v_mov_b32_dpp v154, v151 row_ror:1 row_mask:0xf bank_mask:0xf
	v_cndmask_b32_e64 v157, v155, v228, s[10:11]
	v_cndmask_b32_e64 v156, v153, v227, s[10:11]
	v_mov_b32_dpp v166, v170 row_ror:15 row_mask:0xf bank_mask:0xf
	v_mov_b32_dpp v167, v171 row_ror:15 row_mask:0xf bank_mask:0xf
	v_cndmask_b32_e64 v159, v154, v219, s[10:11]
	v_cndmask_b32_e64 v158, v152, v218, s[10:11]
	v_pk_mul_f32 v[156:157], v[86:87], v[156:157]
	v_mov_b32_dpp v164, v168 row_ror:15 row_mask:0xf bank_mask:0xf
	v_mov_b32_dpp v165, v169 row_ror:15 row_mask:0xf bank_mask:0xf
	v_pk_mul_f32 v[158:159], v[84:85], v[158:159]
	v_pk_fma_f32 v[148:149], v[78:79], v[148:149], v[156:157]
	v_cndmask_b32_e64 v157, v212, v167, s[8:9]
	v_cndmask_b32_e64 v156, v208, v166, s[8:9]
	v_pk_fma_f32 v[150:151], v[76:77], v[150:151], v[158:159]
	v_cndmask_b32_e64 v159, v179, v165, s[8:9]
	v_cndmask_b32_e64 v158, v178, v164, s[8:9]
	v_pk_fma_f32 v[148:149], v[74:75], v[156:157], v[148:149]
	v_pk_fma_f32 v[150:151], v[72:73], v[158:159], v[150:151]
	v_pk_add_f32 v[148:149], v[70:71], v[148:149]
	v_pk_add_f32 v[150:151], v[68:69], v[150:151]
	v_mul_f32_e32 v158, 0xbfb8aa3b, v148
	v_mul_f32_e32 v159, 0xbfb8aa3b, v149
	v_mul_f32_e32 v156, 0xbfb8aa3b, v150
	v_mul_f32_e32 v157, 0xbfb8aa3b, v151
	v_exp_f32_e32 v158, v158
	v_exp_f32_e32 v159, v159
	v_exp_f32_e32 v156, v156
	v_exp_f32_e32 v157, v157
	v_add_f32_e32 v158, 1.0, v158
	v_add_f32_e32 v159, 1.0, v159
	v_add_f32_e32 v156, 1.0, v156
	v_add_f32_e32 v157, 1.0, v157
	v_rcp_f32_e32 v158, v158
	v_rcp_f32_e32 v159, v159
	v_rcp_f32_e32 v156, v156
	v_rcp_f32_e32 v157, v157
	v_pk_mul_f32 v[148:149], v[148:149], v[158:159]
	v_mov_b32_dpp v180, v146 row_ror:1 row_mask:0xf bank_mask:0xf
	v_mov_b32_dpp v181, v147 row_ror:1 row_mask:0xf bank_mask:0xf
	v_pk_mul_f32 v[150:151], v[150:151], v[156:157]
	v_pk_mul_f32 v[142:143], v[142:143], v[148:149]
	v_cndmask_b32_e64 v149, v181, v238, s[10:11]
	v_cndmask_b32_e64 v148, v180, v237, s[10:11]
	v_mov_b32_dpp v174, v160 row_ror:15 row_mask:0xf bank_mask:0xf
	v_mov_b32_dpp v175, v161 row_ror:15 row_mask:0xf bank_mask:0xf
	v_mov_b32_dpp v182, v144 row_ror:1 row_mask:0xf bank_mask:0xf
	v_mov_b32_dpp v183, v145 row_ror:1 row_mask:0xf bank_mask:0xf
	v_pk_mul_f32 v[140:141], v[140:141], v[150:151]
	v_pk_mul_f32 v[148:149], v[60:61], v[148:149]
	v_cvt_pk_bf16_f32 v140, v140, v141
	v_cvt_pk_bf16_f32 v141, v142, v143
	v_cndmask_b32_e64 v143, v183, v240, s[10:11]
	v_cndmask_b32_e64 v142, v182, v239, s[10:11]
	v_pk_fma_f32 v[148:149], v[146:147], v[56:57], v[148:149]
	v_cndmask_b32_e64 v157, v234, v175, s[8:9]
	v_cndmask_b32_e64 v156, v233, v174, s[8:9]
	v_mov_b32_dpp v176, v162 row_ror:15 row_mask:0xf bank_mask:0xf
	v_mov_b32_dpp v177, v163 row_ror:15 row_mask:0xf bank_mask:0xf
	v_pk_mul_f32 v[142:143], v[62:63], v[142:143]
	v_pk_fma_f32 v[148:149], v[48:49], v[156:157], v[148:149]
	v_pk_fma_f32 v[142:143], v[144:145], v[58:59], v[142:143]
	v_cndmask_b32_e64 v151, v236, v177, s[8:9]
	v_cndmask_b32_e64 v150, v235, v176, s[8:9]
	v_pk_add_f32 v[148:149], v[44:45], v[148:149]
	v_pk_fma_f32 v[142:143], v[50:51], v[150:151], v[142:143]
	v_mul_f32_e32 v150, 0xbfb8aa3b, v148
	v_exp_f32_e32 v156, v150
	v_mul_f32_e32 v150, 0xbfb8aa3b, v149
	v_exp_f32_e32 v157, v150
	v_pk_add_f32 v[150:151], v[46:47], v[142:143]
	v_add_f32_e32 v142, 1.0, v156
	v_mul_f32_e32 v156, 0xbfb8aa3b, v150
	v_add_f32_e32 v143, 1.0, v157
	v_mul_f32_e32 v157, 0xbfb8aa3b, v151
	v_exp_f32_e32 v156, v156
	v_exp_f32_e32 v157, v157
	v_rcp_f32_e32 v142, v142
	v_rcp_f32_e32 v143, v143
	v_add_f32_e32 v156, 1.0, v156
	v_add_f32_e32 v157, 1.0, v157
	v_rcp_f32_e32 v156, v156
	v_rcp_f32_e32 v157, v157
	v_pk_mul_f32 v[142:143], v[148:149], v[142:143]
	s_andn2_b64 vcc, exec, s[48:49]
	v_pk_mul_f32 v[136:137], v[136:137], v[142:143]
	s_nop 0
	v_cvt_pk_bf16_f32 v142, v136, v137
	v_pk_mul_f32 v[136:137], v[150:151], v[156:157]
	s_nop 0
	v_pk_mul_f32 v[136:137], v[138:139], v[136:137]
	s_nop 0
	v_cvt_pk_bf16_f32 v143, v136, v137
	v_or_b32_e32 v136, 32, v205
	v_mad_i64_i32 v[136:137], s[12:13], v136, s38, v[172:173]
	global_store_dwordx4 v[136:137], v[140:143], off
	v_cndmask_b32_e64 v137, 0, 1, s[48:49]
	v_mov_b32_e32 v136, 0
	v_cmp_ne_u32_e64 s[12:13], 1, v137
	v_mov_b32_e32 v140, 0
	v_mov_b32_e32 v141, 0
	v_mov_b32_e32 v142, 0
	v_mov_b32_e32 v143, 0
	s_cbranch_vccnz .LBB0_845
	ds_read_b128 v[140:143], v213 offset:1024
; #define LAS __attribute__((address_space(3)))
;     __device__ __forceinline__ void operator()(const f32x4 (&acc_c)[2][2][4][2], const pg8::Unit& u, int wr, int wc, int fr, int fq) const {
;     ...
;         for (int ai = 0; ai < 2; ++ai)
; #pragma unroll
;             for (int m = 0; m < 4; ++m) { const int rl = ai * 128 + wr * 64 + m * 16 + fr;
;                 const float rstd = __builtin_amdgcn_rsqf(rsq[rl] * (1.0f / D_MODEL) + EPS);
; #pragma unroll
;                 for (int bj = 0; bj < 2; ++bj)
; #pragma unroll
;                     for (int n = 0; n < 2; ++n) acc[ai][bj][m][n] = acc[ai][bj][m][n] * rstd + *(const LAS f32x4*)(bias2 + bj * 128 + cl + 4 * n); }
;         f32x4 w0[2], w1[2], w2[2], cbv[2];
; #pragma unroll
;         for (int n = 0; n < 2; ++n) { w0[n] = *(const f32x4*)(cw + ch0 + 4 * n); w1[n] = *(const f32x4*)(cw + FFN + ch0 + 4 * n); w2[n] = *(const f32x4*)(cw + 2 * FFN + ch0 + 4 * n); cbv[n] = *(const f32x4*)(cb + ch0 + 4 * n); }
; #pragma unroll
;         for (int ai = 0; ai < 2; ++ai) { const int bi = 2 * ai + wr;
;             if (fr == 0) {
; #pragma unroll
;                 for (int n = 0; n < 2; ++n) *(LAS f32x4*)(X + (bi * 2 + 0) * 128 + cl + 4 * n) = acc[ai][0][0][n]; }
;             if (fr == 15) {
; #pragma unroll
;                 for (int n = 0; n < 2; ++n) *(LAS f32x4*)(X + (bi * 2 + 1) * 128 + cl + 4 * n) = acc[ai][0][3][n]; } }
;         asm volatile("s_waitcnt lgkmcnt(0)" ::: "memory"); __builtin_amdgcn_s_barrier(); asm volatile("" ::: "memory");
; #pragma unroll
;         for (int ai = 0; ai < 2; ++ai) { const int bi = 2 * ai + wr;
; #pragma unroll
;             for (int m = 0; m < 4; ++m) { u32x4 o;
; #pragma unroll
;                 for (int n = 0; n < 2; ++n) { const f32x4 cur = acc[ai][0][m][n];
;                     f32x4 pu, nd;
;                     if (m > 0) pu = ror1_4(acc[ai][0][m > 0 ? m - 1 : 0][n]); else pu = (bi > 0) ? *(const LAS f32x4*)(X + ((bi - 1) * 2 + 1) * 128 + cl + 4 * n) : (f32x4){0.f, 0.f, 0.f, 0.f};
;                     if (m < 3) nd = rol1_4(acc[ai][0][m < 3 ? m + 1 : 3][n]); else nd = (bi < 3) ? *(const LAS f32x4*)(X + ((bi + 1) * 2 + 0) * 128 + cl + 4 * n) : (f32x4){0.f, 0.f, 0.f, 0.f};
;                     const f32x4 ps = ror1_4(cur), ns = rol1_4(cur);
;                     const f32x4 prev = (fr > 0) ? ps : pu, next = (fr < 15) ? ns : nd;
.LBB0_845:
	v_mov_b32_dpp v148, v146 row_ror:1 row_mask:0xf bank_mask:0xf
	v_mov_b32_dpp v146, v147 row_ror:1 row_mask:0xf bank_mask:0xf
	v_mov_b32_dpp v147, v144 row_ror:1 row_mask:0xf bank_mask:0xf
	v_mov_b32_dpp v174, v168 row_ror:1 row_mask:0xf bank_mask:0xf
	v_mov_b32_dpp v176, v169 row_ror:1 row_mask:0xf bank_mask:0xf
	v_mov_b32_dpp v175, v170 row_ror:1 row_mask:0xf bank_mask:0xf
	v_mov_b32_dpp v177, v171 row_ror:1 row_mask:0xf bank_mask:0xf
	v_mov_b32_dpp v164, v168 row_ror:15 row_mask:0xf bank_mask:0xf
	v_mov_b32_dpp v166, v169 row_ror:15 row_mask:0xf bank_mask:0xf
	v_mov_b32_dpp v165, v170 row_ror:15 row_mask:0xf bank_mask:0xf
	v_mov_b32_dpp v167, v171 row_ror:15 row_mask:0xf bank_mask:0xf
	v_mov_b32_dpp v144, v145 row_ror:1 row_mask:0xf bank_mask:0xf
	s_and_b64 vcc, exec, s[12:13]
	v_mov_b32_e32 v137, 0
	v_mov_b32_e32 v138, 0
	v_mov_b32_e32 v139, 0
	s_cbranch_vccnz .LBB0_847
	ds_read_b128 v[136:139], v213 offset:1040
.LBB0_847:
	s_movk_i32 s12, 0xcf
	v_mov_b32_dpp v156, v160 row_ror:1 row_mask:0xf bank_mask:0xf
	v_mov_b32_dpp v157, v161 row_ror:1 row_mask:0xf bank_mask:0xf
	v_mov_b32_dpp v158, v162 row_ror:1 row_mask:0xf bank_mask:0xf
	v_mov_b32_dpp v159, v163 row_ror:1 row_mask:0xf bank_mask:0xf
	v_mov_b32_dpp v145, v160 row_ror:15 row_mask:0xf bank_mask:0xf
	v_mov_b32_dpp v149, v161 row_ror:15 row_mask:0xf bank_mask:0xf
	v_mov_b32_dpp v150, v162 row_ror:15 row_mask:0xf bank_mask:0xf
	v_mov_b32_dpp v151, v163 row_ror:15 row_mask:0xf bank_mask:0xf
	v_cmp_ne_u32_e32 vcc, s12, v192
	s_and_saveexec_b64 s[12:13], vcc
	s_cbranch_execz .LBB0_849
	v_cndmask_b32_e64 v181, v176, v154, s[10:11]
	v_cndmask_b32_e64 v155, v177, v155, s[10:11]
	v_cndmask_b32_e64 v154, v175, v153, s[10:11]
	v_cndmask_b32_e64 v180, v174, v152, s[10:11]
	v_pk_mul_f32 v[152:153], v[86:87], v[154:155]
	s_waitcnt lgkmcnt(0)
	v_cndmask_b32_e64 v143, v167, v143, s[8:9]
	v_pk_fma_f32 v[152:153], v[78:79], v[170:171], v[152:153]
	v_cndmask_b32_e64 v142, v165, v142, s[8:9]
	v_pk_fma_f32 v[142:143], v[74:75], v[142:143], v[152:153]
	v_pk_mul_f32 v[154:155], v[84:85], v[180:181]
	v_pk_add_f32 v[142:143], v[70:71], v[142:143]
	v_pk_fma_f32 v[154:155], v[76:77], v[168:169], v[154:155]
	v_mul_f32_e32 v152, 0xbfb8aa3b, v143
	v_exp_f32_e32 v152, v152
	v_cndmask_b32_e64 v141, v166, v141, s[8:9]
	v_cndmask_b32_e64 v140, v164, v140, s[8:9]
	v_mov_b32_e32 v178, v210
	v_add_f32_e32 v152, 1.0, v152
	v_rcp_f32_e32 v153, v152
	v_mul_f32_e32 v152, 0xbfb8aa3b, v142
	v_exp_f32_e32 v152, v152
	v_mov_b32_e32 v179, v210
	v_pk_fma_f32 v[140:141], v[72:73], v[140:141], v[154:155]
	v_pk_fma_f32 v[118:119], v[118:119], v[178:179], v[98:99]
	v_add_f32_e32 v152, 1.0, v152
	v_rcp_f32_e32 v152, v152
	v_pk_add_f32 v[140:141], v[68:69], v[140:141]
	v_pk_fma_f32 v[116:117], v[116:117], v[210:211], v[96:97]
	v_cndmask_b32_e64 v139, v151, v139, s[8:9]
	v_pk_mul_f32 v[142:143], v[142:143], v[152:153]
	v_cndmask_b32_e64 v138, v150, v138, s[8:9]
	v_pk_mul_f32 v[118:119], v[118:119], v[142:143]
	v_mul_f32_e32 v142, 0xbfb8aa3b, v141
	v_exp_f32_e32 v142, v142
	v_cndmask_b32_e64 v137, v149, v137, s[8:9]
	v_cndmask_b32_e64 v136, v145, v136, s[8:9]
	v_pk_fma_f32 v[112:113], v[112:113], v[210:211], v[92:93]
	v_add_f32_e32 v142, 1.0, v142
	v_rcp_f32_e32 v143, v142
	v_mul_f32_e32 v142, 0xbfb8aa3b, v140
	v_exp_f32_e32 v142, v142
	v_pk_fma_f32 v[114:115], v[114:115], v[178:179], v[94:95]
	v_add_f32_e32 v142, 1.0, v142
	v_rcp_f32_e32 v142, v142
	s_nop 0
	v_pk_mul_f32 v[140:141], v[140:141], v[142:143]
	s_nop 0
	v_pk_mul_f32 v[116:117], v[116:117], v[140:141]
	v_cndmask_b32_e64 v141, v157, v146, s[10:11]
	v_cvt_pk_bf16_f32 v116, v116, v117
	v_cvt_pk_bf16_f32 v117, v118, v119
	v_cndmask_b32_e64 v119, v159, v144, s[10:11]
	v_cndmask_b32_e64 v118, v158, v147, s[10:11]
	v_cndmask_b32_e64 v140, v156, v148, s[10:11]
	v_pk_mul_f32 v[140:141], v[60:61], v[140:141]
	v_pk_mul_f32 v[118:119], v[62:63], v[118:119]
	v_pk_fma_f32 v[140:141], v[160:161], v[56:57], v[140:141]
	v_pk_fma_f32 v[118:119], v[162:163], v[58:59], v[118:119]
	v_pk_fma_f32 v[136:137], v[48:49], v[136:137], v[140:141]
	v_pk_fma_f32 v[118:119], v[50:51], v[138:139], v[118:119]
	s_nop 0
	v_pk_add_f32 v[138:139], v[46:47], v[118:119]
	v_pk_add_f32 v[118:119], v[44:45], v[136:137]
	s_nop 0
	v_mul_f32_e32 v136, 0xbfb8aa3b, v118
	v_mul_f32_e32 v137, 0xbfb8aa3b, v119
	v_exp_f32_e32 v136, v136
	v_exp_f32_e32 v137, v137
	v_add_f32_e32 v136, 1.0, v136
	v_add_f32_e32 v137, 1.0, v137
	v_rcp_f32_e32 v136, v136
	v_rcp_f32_e32 v137, v137
	s_nop 0
	v_pk_mul_f32 v[118:119], v[118:119], v[136:137]
	s_nop 0
	v_pk_mul_f32 v[112:113], v[112:113], v[118:119]
	s_nop 0
	v_cvt_pk_bf16_f32 v118, v112, v113
	v_mul_f32_e32 v112, 0xbfb8aa3b, v138
	v_mul_f32_e32 v113, 0xbfb8aa3b, v139
	v_exp_f32_e32 v112, v112
	v_exp_f32_e32 v113, v113
	v_add_f32_e32 v112, 1.0, v112
	v_add_f32_e32 v113, 1.0, v113
	v_rcp_f32_e32 v112, v112
	v_rcp_f32_e32 v113, v113
	s_nop 0
	v_pk_mul_f32 v[112:113], v[138:139], v[112:113]
	s_nop 0
	v_pk_mul_f32 v[112:113], v[114:115], v[112:113]
	s_nop 0
	v_cvt_pk_bf16_f32 v119, v112, v113
	v_or_b32_e32 v112, 48, v205
	v_mad_i64_i32 v[112:113], s[40:41], v112, s38, v[172:173]
	global_store_dwordx4 v[112:113], v[116:119], off

; #define LAS __attribute__((address_space(3)))
;     __device__ __forceinline__ void operator()(const f32x4 (&acc_c)[2][2][4][2], const pg8::Unit& u, int wr, int wc, int fr, int fq) const {
;     ...
;         for (int ai = 0; ai < 2; ++ai)
; #pragma unroll
;             for (int m = 0; m < 4; ++m) { const int rl = ai * 128 + wr * 64 + m * 16 + fr;
;                 const float rstd = __builtin_amdgcn_rsqf(rsq[rl] * (1.0f / D_MODEL) + EPS);
; #pragma unroll
;                 for (int bj = 0; bj < 2; ++bj)
; #pragma unroll
;                     for (int n = 0; n < 2; ++n) acc[ai][bj][m][n] = acc[ai][bj][m][n] * rstd + *(const LAS f32x4*)(bias2 + bj * 128 + cl + 4 * n); }
;         f32x4 w0[2], w1[2], w2[2], cbv[2];
; #pragma unroll
;         for (int n = 0; n < 2; ++n) { w0[n] = *(const f32x4*)(cw + ch0 + 4 * n); w1[n] = *(const f32x4*)(cw + FFN + ch0 + 4 * n); w2[n] = *(const f32x4*)(cw + 2 * FFN + ch0 + 4 * n); cbv[n] = *(const f32x4*)(cb + ch0 + 4 * n); }
; #pragma unroll
;         for (int ai = 0; ai < 2; ++ai) { const int bi = 2 * ai + wr;
;             if (fr == 0) {
; #pragma unroll
;                 for (int n = 0; n < 2; ++n) *(LAS f32x4*)(X + (bi * 2 + 0) * 128 + cl + 4 * n) = acc[ai][0][0][n]; }
;             if (fr == 15) {
; #pragma unroll
;                 for (int n = 0; n < 2; ++n) *(LAS f32x4*)(X + (bi * 2 + 1) * 128 + cl + 4 * n) = acc[ai][0][3][n]; } }
;         asm volatile("s_waitcnt lgkmcnt(0)" ::: "memory"); __builtin_amdgcn_s_barrier(); asm volatile("" ::: "memory");
; #pragma unroll
;         for (int ai = 0; ai < 2; ++ai) { const int bi = 2 * ai + wr;
; #pragma unroll
;             for (int m = 0; m < 4; ++m) { u32x4 o;
; #pragma unroll
;                 for (int n = 0; n < 2; ++n) { const f32x4 cur = acc[ai][0][m][n];
;                     f32x4 pu, nd;
;                     if (m > 0) pu = ror1_4(acc[ai][0][m > 0 ? m - 1 : 0][n]); else pu = (bi > 0) ? *(const LAS f32x4*)(X + ((bi - 1) * 2 + 1) * 128 + cl + 4 * n) : (f32x4){0.f, 0.f, 0.f, 0.f};
;                     if (m < 3) nd = rol1_4(acc[ai][0][m < 3 ? m + 1 : 3][n]); else nd = (bi < 3) ? *(const LAS f32x4*)(X + ((bi + 1) * 2 + 0) * 128 + cl + 4 * n) : (f32x4){0.f, 0.f, 0.f, 0.f};
;                     const f32x4 ps = ror1_4(cur), ns = rol1_4(cur);
;                     const f32x4 prev = (fr > 0) ? ps : pu, next = (fr < 15) ? ns : nd;
.LBB0_851:
	v_fmamk_f32 v113, v209, 0x3a000000, v224
	v_rsq_f32_e32 v136, v113
	s_nop 0
	v_pk_fma_f32 v[102:103], v[102:103], v[136:137], v[126:127] op_sel_hi:[1,0,1]
	v_pk_fma_f32 v[100:101], v[100:101], v[136:137], v[124:125] op_sel_hi:[1,0,1]
	s_nop 1
	v_mov_b32_dpp v152, v100 row_ror:15 row_mask:0xf bank_mask:0xf
	v_mov_b32_dpp v153, v101 row_ror:15 row_mask:0xf bank_mask:0xf
	v_mov_b32_dpp v154, v102 row_ror:15 row_mask:0xf bank_mask:0xf
	v_mov_b32_dpp v155, v103 row_ror:15 row_mask:0xf bank_mask:0xf
	v_mov_b32_dpp v160, v132 row_ror:1 row_mask:0xf bank_mask:0xf
	v_mov_b32_dpp v162, v133 row_ror:1 row_mask:0xf bank_mask:0xf
	v_mov_b32_dpp v161, v134 row_ror:1 row_mask:0xf bank_mask:0xf
	v_mov_b32_dpp v163, v135 row_ror:1 row_mask:0xf bank_mask:0xf
	v_mov_b32_dpp v156, v132 row_ror:15 row_mask:0xf bank_mask:0xf
	v_mov_b32_dpp v158, v133 row_ror:15 row_mask:0xf bank_mask:0xf
	v_mov_b32_dpp v157, v134 row_ror:15 row_mask:0xf bank_mask:0xf
	v_mov_b32_dpp v159, v135 row_ror:15 row_mask:0xf bank_mask:0xf
	s_and_b64 vcc, exec, s[12:13]
	v_mov_b32_e32 v113, 0
	v_mov_b32_e32 v114, 0
	v_mov_b32_e32 v115, 0
	s_cbranch_vccnz .LBB0_853
	ds_read_b128 v[112:115], v137 offset:16
.LBB0_853:
	v_mov_b32_e32 v137, v136
	v_mov_b32_e32 v138, v136
	v_mov_b32_e32 v139, v136
	v_pk_fma_f32 v[90:91], v[90:91], v[138:139], v[122:123]
	v_pk_fma_f32 v[88:89], v[88:89], v[136:137], v[120:121]
	s_movk_i32 s12, 0xff80
	s_nop 0
	v_mov_b32_dpp v140, v88 row_ror:15 row_mask:0xf bank_mask:0xf
	v_mov_b32_dpp v141, v89 row_ror:15 row_mask:0xf bank_mask:0xf
	v_mov_b32_dpp v142, v90 row_ror:15 row_mask:0xf bank_mask:0xf
	v_mov_b32_dpp v143, v91 row_ror:15 row_mask:0xf bank_mask:0xf
	v_mov_b32_dpp v148, v128 row_ror:1 row_mask:0xf bank_mask:0xf
	v_mov_b32_dpp v149, v129 row_ror:1 row_mask:0xf bank_mask:0xf
	v_mov_b32_dpp v150, v130 row_ror:1 row_mask:0xf bank_mask:0xf
	v_mov_b32_dpp v151, v131 row_ror:1 row_mask:0xf bank_mask:0xf
	v_mov_b32_dpp v144, v128 row_ror:15 row_mask:0xf bank_mask:0xf
	v_mov_b32_dpp v145, v129 row_ror:15 row_mask:0xf bank_mask:0xf
	v_mov_b32_dpp v146, v130 row_ror:15 row_mask:0xf bank_mask:0xf
	v_mov_b32_dpp v147, v131 row_ror:15 row_mask:0xf bank_mask:0xf
	v_cmp_ne_u32_e32 vcc, s12, v192
	s_and_saveexec_b64 s[12:13], vcc
	s_cbranch_execz .LBB0_855
	s_waitcnt lgkmcnt(0)
	v_cndmask_b32_e64 v119, v163, v119, s[10:11]
	v_cndmask_b32_e64 v118, v161, v118, s[10:11]
	v_pk_mul_f32 v[118:119], v[86:87], v[118:119]
	v_cndmask_b32_e64 v117, v162, v117, s[10:11]
	v_cndmask_b32_e64 v116, v160, v116, s[10:11]
	v_pk_fma_f32 v[118:119], v[78:79], v[134:135], v[118:119]
	v_cndmask_b32_e64 v155, v159, v155, s[8:9]
	v_cndmask_b32_e64 v154, v157, v154, s[8:9]
	v_pk_mul_f32 v[116:117], v[84:85], v[116:117]
	v_pk_fma_f32 v[118:119], v[74:75], v[154:155], v[118:119]
	v_pk_fma_f32 v[116:117], v[76:77], v[132:133], v[116:117]
	v_cndmask_b32_e64 v153, v158, v153, s[8:9]
	v_cndmask_b32_e64 v152, v156, v152, s[8:9]
	v_pk_add_f32 v[118:119], v[70:71], v[118:119]
	v_pk_fma_f32 v[116:117], v[72:73], v[152:153], v[116:117]
	v_mul_f32_e32 v152, 0xbfb8aa3b, v119
	v_exp_f32_e32 v152, v152
	v_mov_b32_e32 v164, v206
	v_mov_b32_e32 v165, v206
	v_pk_fma_f32 v[82:83], v[82:83], v[164:165], v[98:99]
	v_add_f32_e32 v152, 1.0, v152
	v_rcp_f32_e32 v153, v152
	v_mul_f32_e32 v152, 0xbfb8aa3b, v118
	v_exp_f32_e32 v152, v152
	v_pk_add_f32 v[116:117], v[68:69], v[116:117]
	v_pk_fma_f32 v[80:81], v[80:81], v[206:207], v[96:97]
	v_cndmask_b32_e64 v113, v149, v113, s[10:11]
	v_add_f32_e32 v152, 1.0, v152
	v_rcp_f32_e32 v152, v152
	v_cndmask_b32_e64 v112, v148, v112, s[10:11]
	v_pk_mul_f32 v[112:113], v[60:61], v[112:113]
	v_pk_fma_f32 v[32:33], v[32:33], v[206:207], v[92:93]
	v_pk_mul_f32 v[118:119], v[118:119], v[152:153]
	v_pk_fma_f32 v[112:113], v[128:129], v[56:57], v[112:113]
	v_pk_mul_f32 v[82:83], v[82:83], v[118:119]
	v_mul_f32_e32 v118, 0xbfb8aa3b, v117
	v_exp_f32_e32 v118, v118
	v_pk_fma_f32 v[34:35], v[34:35], v[164:165], v[94:95]
	v_add_f32_e32 v118, 1.0, v118
	v_rcp_f32_e32 v119, v118
	v_mul_f32_e32 v118, 0xbfb8aa3b, v116
	v_exp_f32_e32 v118, v118
	s_nop 0
	v_add_f32_e32 v118, 1.0, v118
	v_rcp_f32_e32 v118, v118
	s_nop 0
	v_pk_mul_f32 v[116:117], v[116:117], v[118:119]
	s_nop 0
	v_pk_mul_f32 v[80:81], v[80:81], v[116:117]
	v_cndmask_b32_e64 v117, v145, v141, s[8:9]
	v_cvt_pk_bf16_f32 v80, v80, v81
	v_cvt_pk_bf16_f32 v81, v82, v83
	v_cndmask_b32_e64 v83, v151, v115, s[10:11]
	v_cndmask_b32_e64 v82, v150, v114, s[10:11]
	v_pk_mul_f32 v[82:83], v[62:63], v[82:83]
	v_cndmask_b32_e64 v115, v147, v143, s[8:9]
	v_pk_fma_f32 v[82:83], v[130:131], v[58:59], v[82:83]
	v_cndmask_b32_e64 v114, v146, v142, s[8:9]
	v_cndmask_b32_e64 v116, v144, v140, s[8:9]
	v_pk_fma_f32 v[112:113], v[48:49], v[116:117], v[112:113]
	v_pk_fma_f32 v[82:83], v[50:51], v[114:115], v[82:83]
	s_nop 0
	v_pk_add_f32 v[114:115], v[46:47], v[82:83]
	v_pk_add_f32 v[82:83], v[44:45], v[112:113]
	s_nop 0
	v_mul_f32_e32 v112, 0xbfb8aa3b, v82
	v_mul_f32_e32 v113, 0xbfb8aa3b, v83
	v_exp_f32_e32 v112, v112
	v_exp_f32_e32 v113, v113
	v_add_f32_e32 v112, 1.0, v112
	v_add_f32_e32 v113, 1.0, v113
	v_rcp_f32_e32 v112, v112
	v_rcp_f32_e32 v113, v113
	s_nop 0
	v_pk_mul_f32 v[82:83], v[82:83], v[112:113]
	s_nop 0
	v_pk_mul_f32 v[32:33], v[32:33], v[82:83]
	s_nop 0
	v_cvt_pk_bf16_f32 v82, v32, v33
	v_mul_f32_e32 v32, 0xbfb8aa3b, v114
	v_mul_f32_e32 v33, 0xbfb8aa3b, v115
	v_exp_f32_e32 v32, v32
	v_exp_f32_e32 v33, v33
	v_add_f32_e32 v32, 1.0, v32
	v_add_f32_e32 v33, 1.0, v33
	v_rcp_f32_e32 v32, v32
	v_rcp_f32_e32 v33, v33
	s_nop 0
	v_pk_mul_f32 v[32:33], v[114:115], v[32:33]
	s_nop 0
	v_pk_mul_f32 v[32:33], v[34:35], v[32:33]
	s_nop 0
	v_cvt_pk_bf16_f32 v83, v32, v33
	v_add_u32_e32 v32, 0x80, v205
	v_mad_i64_i32 v[32:33], s[40:41], v32, s38, v[172:173]
	global_store_dwordx4 v[32:33], v[80:83], off
; #define LAS __attribute__((address_space(3)))
;     __device__ __forceinline__ void operator()(const f32x4 (&acc_c)[2][2][4][2], const pg8::Unit& u, int wr, int wc, int fr, int fq) const {
;     ...
;         for (int ai = 0; ai < 2; ++ai)
; #pragma unroll
;             for (int m = 0; m < 4; ++m) { const int rl = ai * 128 + wr * 64 + m * 16 + fr;
;                 const float rstd = __builtin_amdgcn_rsqf(rsq[rl] * (1.0f / D_MODEL) + EPS);
; #pragma unroll
;                 for (int bj = 0; bj < 2; ++bj)
; #pragma unroll
;                     for (int n = 0; n < 2; ++n) acc[ai][bj][m][n] = acc[ai][bj][m][n] * rstd + *(const LAS f32x4*)(bias2 + bj * 128 + cl + 4 * n); }
;         f32x4 w0[2], w1[2], w2[2], cbv[2];
; #pragma unroll
;         for (int n = 0; n < 2; ++n) { w0[n] = *(const f32x4*)(cw + ch0 + 4 * n); w1[n] = *(const f32x4*)(cw + FFN + ch0 + 4 * n); w2[n] = *(const f32x4*)(cw + 2 * FFN + ch0 + 4 * n); cbv[n] = *(const f32x4*)(cb + ch0 + 4 * n); }
; #pragma unroll
;         for (int ai = 0; ai < 2; ++ai) { const int bi = 2 * ai + wr;
;             if (fr == 0) {
; #pragma unroll
;                 for (int n = 0; n < 2; ++n) *(LAS f32x4*)(X + (bi * 2 + 0) * 128 + cl + 4 * n) = acc[ai][0][0][n]; }
;             if (fr == 15) {
; #pragma unroll
;                 for (int n = 0; n < 2; ++n) *(LAS f32x4*)(X + (bi * 2 + 1) * 128 + cl + 4 * n) = acc[ai][0][3][n]; } }
;         asm volatile("s_waitcnt lgkmcnt(0)" ::: "memory"); __builtin_amdgcn_s_barrier(); asm volatile("" ::: "memory");
; #pragma unroll
;         for (int ai = 0; ai < 2; ++ai) { const int bi = 2 * ai + wr;
; #pragma unroll
;             for (int m = 0; m < 4; ++m) { u32x4 o;
; #pragma unroll
;                 for (int n = 0; n < 2; ++n) { const f32x4 cur = acc[ai][0][m][n];
;                     f32x4 pu, nd;
;                     if (m > 0) pu = ror1_4(acc[ai][0][m > 0 ? m - 1 : 0][n]); else pu = (bi > 0) ? *(const LAS f32x4*)(X + ((bi - 1) * 2 + 1) * 128 + cl + 4 * n) : (f32x4){0.f, 0.f, 0.f, 0.f};
;                     if (m < 3) nd = rol1_4(acc[ai][0][m < 3 ? m + 1 : 3][n]); else nd = (bi < 3) ? *(const LAS f32x4*)(X + ((bi + 1) * 2 + 0) * 128 + cl + 4 * n) : (f32x4){0.f, 0.f, 0.f, 0.f};
;                     const f32x4 ps = ror1_4(cur), ns = rol1_4(cur);
;                     const f32x4 prev = (fr > 0) ? ps : pu, next = (fr < 15) ? ns : nd;
.LBB0_855:
	s_or_b64 exec, exec, s[12:13]
	v_fmamk_f32 v33, v204, 0x3a000000, v224
	v_rsq_f32_e32 v34, v33
	v_pk_fma_f32 v[82:83], v[16:17], v[136:137], v[92:93]
	s_waitcnt lgkmcnt(0)
	v_pk_fma_f32 v[16:17], v[26:27], v[34:35], v[122:123] op_sel_hi:[1,0,1]
	v_mov_b32_dpp v117, v102 row_ror:1 row_mask:0xf bank_mask:0xf
	v_mov_b32_dpp v26, v134 row_ror:1 row_mask:0xf bank_mask:0xf
	v_mov_b32_dpp v27, v135 row_ror:1 row_mask:0xf bank_mask:0xf
	v_mov_b32_dpp v118, v103 row_ror:1 row_mask:0xf bank_mask:0xf
	v_pk_fma_f32 v[80:81], v[18:19], v[138:139], v[94:95]
	v_pk_fma_f32 v[30:31], v[30:31], v[34:35], v[126:127] op_sel_hi:[1,0,1]
	v_pk_fma_f32 v[18:19], v[24:25], v[34:35], v[120:121] op_sel_hi:[1,0,1]
	v_cndmask_b32_e64 v27, v118, v27, s[10:11]
	v_cndmask_b32_e64 v26, v117, v26, s[10:11]
	v_mov_b32_dpp v113, v30 row_ror:15 row_mask:0xf bank_mask:0xf
	v_mov_b32_dpp v114, v31 row_ror:15 row_mask:0xf bank_mask:0xf
	v_mov_b32_dpp v120, v102 row_ror:15 row_mask:0xf bank_mask:0xf
	v_mov_b32_dpp v121, v103 row_ror:15 row_mask:0xf bank_mask:0xf
	v_pk_mul_f32 v[26:27], v[86:87], v[26:27]
	v_mov_b32_dpp v24, v132 row_ror:1 row_mask:0xf bank_mask:0xf
	v_mov_b32_dpp v25, v133 row_ror:1 row_mask:0xf bank_mask:0xf
	v_mov_b32_dpp v115, v100 row_ror:1 row_mask:0xf bank_mask:0xf
	v_mov_b32_dpp v116, v101 row_ror:1 row_mask:0xf bank_mask:0xf
	v_pk_fma_f32 v[26:27], v[78:79], v[102:103], v[26:27]
	v_cndmask_b32_e64 v103, v121, v114, s[8:9]
	v_cndmask_b32_e64 v102, v120, v113, s[8:9]
	v_pk_fma_f32 v[28:29], v[28:29], v[34:35], v[124:125] op_sel_hi:[1,0,1]
	v_pk_fma_f32 v[12:13], v[12:13], v[34:35], v[96:97] op_sel_hi:[1,0,1]
	v_pk_fma_f32 v[14:15], v[14:15], v[34:35], v[98:99] op_sel_hi:[1,0,1]
	v_pk_fma_f32 v[8:9], v[8:9], v[34:35], v[92:93] op_sel_hi:[1,0,1]
	v_cndmask_b32_e64 v25, v116, v25, s[10:11]
	v_cndmask_b32_e64 v24, v115, v24, s[10:11]
	v_pk_fma_f32 v[26:27], v[74:75], v[102:103], v[26:27]
	v_mov_b32_dpp v33, v28 row_ror:15 row_mask:0xf bank_mask:0xf
	v_mov_b32_dpp v112, v29 row_ror:15 row_mask:0xf bank_mask:0xf
	v_mov_b32_dpp v35, v100 row_ror:15 row_mask:0xf bank_mask:0xf
	v_mov_b32_dpp v119, v101 row_ror:15 row_mask:0xf bank_mask:0xf
	v_pk_mul_f32 v[24:25], v[84:85], v[24:25]
	v_pk_add_f32 v[26:27], v[70:71], v[26:27]
	v_pk_fma_f32 v[24:25], v[76:77], v[100:101], v[24:25]
	v_cndmask_b32_e64 v101, v119, v112, s[8:9]
	v_cndmask_b32_e64 v100, v35, v33, s[8:9]
	v_mul_f32_e32 v35, 0xbfb8aa3b, v27
	v_pk_fma_f32 v[24:25], v[72:73], v[100:101], v[24:25]
	v_exp_f32_e32 v35, v35
	v_mul_f32_e32 v100, 0xbfb8aa3b, v26
	v_exp_f32_e32 v100, v100
	v_pk_add_f32 v[24:25], v[68:69], v[24:25]
	v_add_f32_e32 v35, 1.0, v35
	v_rcp_f32_e32 v101, v35
	v_add_f32_e32 v35, 1.0, v100
	v_mul_f32_e32 v100, 0xbfb8aa3b, v25
	v_exp_f32_e32 v102, v100
	v_mul_f32_e32 v100, 0xbfb8aa3b, v24
	v_exp_f32_e32 v119, v100
	v_rcp_f32_e32 v100, v35
	v_add_f32_e32 v35, 1.0, v102
	v_rcp_f32_e32 v103, v35
	v_add_f32_e32 v35, 1.0, v119
	v_rcp_f32_e32 v102, v35
	v_pk_fma_f32 v[20:21], v[20:21], v[136:137], v[96:97]
	v_pk_fma_f32 v[22:23], v[22:23], v[138:139], v[98:99]
	v_pk_mul_f32 v[26:27], v[26:27], v[100:101]
	v_pk_mul_f32 v[24:25], v[24:25], v[102:103]
	v_pk_mul_f32 v[22:23], v[22:23], v[26:27]
	v_pk_mul_f32 v[20:21], v[20:21], v[24:25]
	v_cvt_pk_bf16_f32 v24, v20, v21
	s_nop 0
	v_mov_b32_dpp v20, v128 row_ror:1 row_mask:0xf bank_mask:0xf
	v_mov_b32_dpp v21, v129 row_ror:1 row_mask:0xf bank_mask:0xf
	v_mov_b32_dpp v25, v130 row_ror:1 row_mask:0xf bank_mask:0xf
	v_mov_b32_dpp v26, v131 row_ror:1 row_mask:0xf bank_mask:0xf
	v_mov_b32_dpp v119, v88 row_ror:1 row_mask:0xf bank_mask:0xf
	v_mov_b32_dpp v120, v89 row_ror:1 row_mask:0xf bank_mask:0xf
	v_mov_b32_dpp v121, v90 row_ror:1 row_mask:0xf bank_mask:0xf
	v_mov_b32_dpp v122, v91 row_ror:1 row_mask:0xf bank_mask:0xf
	v_cndmask_b32_e64 v21, v120, v21, s[10:11]
	v_cndmask_b32_e64 v20, v119, v20, s[10:11]
	v_cndmask_b32_e64 v27, v122, v26, s[10:11]
	v_cndmask_b32_e64 v26, v121, v25, s[10:11]
	v_pk_fma_f32 v[10:11], v[10:11], v[34:35], v[94:95] op_sel_hi:[1,0,1]
	v_mov_b32_dpp v102, v16 row_ror:15 row_mask:0xf bank_mask:0xf
	v_mov_b32_dpp v103, v17 row_ror:15 row_mask:0xf bank_mask:0xf
	v_mov_b32_dpp v123, v90 row_ror:15 row_mask:0xf bank_mask:0xf
	v_mov_b32_dpp v124, v91 row_ror:15 row_mask:0xf bank_mask:0xf
	v_pk_mul_f32 v[26:27], v[62:63], v[26:27]
	v_pk_mul_f32 v[20:21], v[60:61], v[20:21]
	v_mov_b32_dpp v34, v88 row_ror:15 row_mask:0xf bank_mask:0xf
	v_mov_b32_dpp v35, v89 row_ror:15 row_mask:0xf bank_mask:0xf
	v_pk_fma_f32 v[20:21], v[88:89], v[56:57], v[20:21]
	v_pk_fma_f32 v[26:27], v[90:91], v[58:59], v[26:27]
	v_cndmask_b32_e64 v89, v124, v103, s[8:9]
	v_cndmask_b32_e64 v88, v123, v102, s[8:9]
	v_pk_fma_f32 v[26:27], v[50:51], v[88:89], v[26:27]
	v_mov_b32_dpp v100, v18 row_ror:15 row_mask:0xf bank_mask:0xf
	v_mov_b32_dpp v101, v19 row_ror:15 row_mask:0xf bank_mask:0xf
	v_pk_add_f32 v[26:27], v[46:47], v[26:27]
	v_cndmask_b32_e64 v35, v35, v101, s[8:9]
	v_cndmask_b32_e64 v34, v34, v100, s[8:9]
	v_mul_f32_e32 v25, 0xbfb8aa3b, v27
	v_pk_fma_f32 v[20:21], v[48:49], v[34:35], v[20:21]
	v_exp_f32_e32 v25, v25
	v_mul_f32_e32 v34, 0xbfb8aa3b, v26
	v_exp_f32_e32 v34, v34
	v_pk_add_f32 v[20:21], v[44:45], v[20:21]
	v_add_f32_e32 v25, 1.0, v25
	v_rcp_f32_e32 v35, v25
	v_add_f32_e32 v25, 1.0, v34
	v_mul_f32_e32 v34, 0xbfb8aa3b, v21
	v_exp_f32_e32 v88, v34
	v_mul_f32_e32 v34, 0xbfb8aa3b, v20
	v_exp_f32_e32 v90, v34
	v_rcp_f32_e32 v34, v25
	v_add_f32_e32 v25, 1.0, v88
	v_rcp_f32_e32 v89, v25
	v_add_f32_e32 v25, 1.0, v90
	v_rcp_f32_e32 v88, v25
	v_cvt_pk_bf16_f32 v25, v22, v23
	v_pk_mul_f32 v[22:23], v[26:27], v[34:35]
	v_pk_mul_f32 v[20:21], v[20:21], v[88:89]
; #define LAS __attribute__((address_space(3)))
;     __device__ __forceinline__ void operator()(const f32x4 (&acc_c)[2][2][4][2], const pg8::Unit& u, int wr, int wc, int fr, int fq) const {
;     ...
;         for (int ai = 0; ai < 2; ++ai)
; #pragma unroll
;             for (int m = 0; m < 4; ++m) { const int rl = ai * 128 + wr * 64 + m * 16 + fr;
;                 const float rstd = __builtin_amdgcn_rsqf(rsq[rl] * (1.0f / D_MODEL) + EPS);
; #pragma unroll
;                 for (int bj = 0; bj < 2; ++bj)
; #pragma unroll
;                     for (int n = 0; n < 2; ++n) acc[ai][bj][m][n] = acc[ai][bj][m][n] * rstd + *(const LAS f32x4*)(bias2 + bj * 128 + cl + 4 * n); }
;         f32x4 w0[2], w1[2], w2[2], cbv[2];
; #pragma unroll
;         for (int n = 0; n < 2; ++n) { w0[n] = *(const f32x4*)(cw + ch0 + 4 * n); w1[n] = *(const f32x4*)(cw + FFN + ch0 + 4 * n); w2[n] = *(const f32x4*)(cw + 2 * FFN + ch0 + 4 * n); cbv[n] = *(const f32x4*)(cb + ch0 + 4 * n); }
; #pragma unroll
;         for (int ai = 0; ai < 2; ++ai) { const int bi = 2 * ai + wr;
;             if (fr == 0) {
; #pragma unroll
;                 for (int n = 0; n < 2; ++n) *(LAS f32x4*)(X + (bi * 2 + 0) * 128 + cl + 4 * n) = acc[ai][0][0][n]; }
;             if (fr == 15) {
; #pragma unroll
;                 for (int n = 0; n < 2; ++n) *(LAS f32x4*)(X + (bi * 2 + 1) * 128 + cl + 4 * n) = acc[ai][0][3][n]; } }
;         asm volatile("s_waitcnt lgkmcnt(0)" ::: "memory"); __builtin_amdgcn_s_barrier(); asm volatile("" ::: "memory");
; #pragma unroll
;         for (int ai = 0; ai < 2; ++ai) { const int bi = 2 * ai + wr;
; #pragma unroll
;             for (int m = 0; m < 4; ++m) { u32x4 o;
; #pragma unroll
;                 for (int n = 0; n < 2; ++n) { const f32x4 cur = acc[ai][0][m][n];
;                     f32x4 pu, nd;
;                     if (m > 0) pu = ror1_4(acc[ai][0][m > 0 ? m - 1 : 0][n]); else pu = (bi > 0) ? *(const LAS f32x4*)(X + ((bi - 1) * 2 + 1) * 128 + cl + 4 * n) : (f32x4){0.f, 0.f, 0.f, 0.f};
;                     if (m < 3) nd = rol1_4(acc[ai][0][m < 3 ? m + 1 : 3][n]); else nd = (bi < 3) ? *(const LAS f32x4*)(X + ((bi + 1) * 2 + 0) * 128 + cl + 4 * n) : (f32x4){0.f, 0.f, 0.f, 0.f};
;                     const f32x4 ps = ror1_4(cur), ns = rol1_4(cur);
;                     const f32x4 prev = (fr > 0) ? ps : pu, next = (fr < 15) ? ns : nd;
	v_pk_mul_f32 v[22:23], v[80:81], v[22:23]
	v_pk_mul_f32 v[20:21], v[82:83], v[20:21]
	v_cvt_pk_bf16_f32 v27, v22, v23
	v_cvt_pk_bf16_f32 v26, v20, v21
	v_add_u32_e32 v20, 0x90, v205
	v_mov_b32_dpp v21, v30 row_ror:1 row_mask:0xf bank_mask:0xf
	v_mov_b32_dpp v23, v31 row_ror:1 row_mask:0xf bank_mask:0xf
	v_cndmask_b32_e64 v83, v23, v118, s[10:11]
	v_cndmask_b32_e64 v82, v21, v117, s[10:11]
	v_mad_i64_i32 v[34:35], s[12:13], v20, s38, v[172:173]
	v_mov_b32_dpp v90, v66 row_ror:15 row_mask:0xf bank_mask:0xf
	v_mov_b32_dpp v91, v67 row_ror:15 row_mask:0xf bank_mask:0xf
	v_pk_mul_f32 v[82:83], v[86:87], v[82:83]
	v_mov_b32_dpp v20, v28 row_ror:1 row_mask:0xf bank_mask:0xf
	v_mov_b32_dpp v22, v29 row_ror:1 row_mask:0xf bank_mask:0xf
	v_pk_fma_f32 v[30:31], v[78:79], v[30:31], v[82:83]
	v_cndmask_b32_e64 v83, v114, v91, s[8:9]
	v_cndmask_b32_e64 v82, v113, v90, s[8:9]
	v_cndmask_b32_e64 v81, v22, v116, s[10:11]
	v_cndmask_b32_e64 v80, v20, v115, s[10:11]
	v_pk_fma_f32 v[30:31], v[74:75], v[82:83], v[30:31]
	v_mov_b32_dpp v88, v64 row_ror:15 row_mask:0xf bank_mask:0xf
	v_mov_b32_dpp v89, v65 row_ror:15 row_mask:0xf bank_mask:0xf
	v_pk_mul_f32 v[80:81], v[84:85], v[80:81]
	v_pk_add_f32 v[30:31], v[70:71], v[30:31]
	v_pk_fma_f32 v[28:29], v[76:77], v[28:29], v[80:81]
	v_cndmask_b32_e64 v81, v112, v89, s[8:9]
	v_cndmask_b32_e64 v80, v33, v88, s[8:9]
	v_mul_f32_e32 v33, 0xbfb8aa3b, v31
	v_pk_fma_f32 v[28:29], v[72:73], v[80:81], v[28:29]
	v_exp_f32_e32 v33, v33
	v_mul_f32_e32 v80, 0xbfb8aa3b, v30
	v_exp_f32_e32 v80, v80
	v_pk_add_f32 v[28:29], v[68:69], v[28:29]
	v_add_f32_e32 v33, 1.0, v33
	v_rcp_f32_e32 v81, v33
	v_add_f32_e32 v33, 1.0, v80
	v_mul_f32_e32 v80, 0xbfb8aa3b, v29
	v_exp_f32_e32 v82, v80
	v_mul_f32_e32 v80, 0xbfb8aa3b, v28
	v_exp_f32_e32 v88, v80
	v_rcp_f32_e32 v80, v33
	v_add_f32_e32 v33, 1.0, v82
	v_rcp_f32_e32 v83, v33
	v_add_f32_e32 v33, 1.0, v88
	v_rcp_f32_e32 v82, v33
	global_store_dwordx4 v[34:35], v[24:27], off
	v_lshl_add_u32 v32, v226, 2, s96
	s_andn2_b64 vcc, exec, s[52:53]
	v_pk_mul_f32 v[24:25], v[30:31], v[80:81]
	v_mov_b32_dpp v26, v16 row_ror:1 row_mask:0xf bank_mask:0xf
	v_mov_b32_dpp v27, v17 row_ror:1 row_mask:0xf bank_mask:0xf
	v_pk_mul_f32 v[14:15], v[14:15], v[24:25]
	v_pk_mul_f32 v[24:25], v[28:29], v[82:83]
	v_cndmask_b32_e64 v27, v27, v122, s[10:11]
	v_cndmask_b32_e64 v26, v26, v121, s[10:11]
	v_pk_mul_f32 v[12:13], v[12:13], v[24:25]
	v_mov_b32_dpp v30, v54 row_ror:15 row_mask:0xf bank_mask:0xf
	v_mov_b32_dpp v31, v55 row_ror:15 row_mask:0xf bank_mask:0xf
	v_pk_mul_f32 v[26:27], v[62:63], v[26:27]
	v_mov_b32_dpp v24, v18 row_ror:1 row_mask:0xf bank_mask:0xf
	v_mov_b32_dpp v25, v19 row_ror:1 row_mask:0xf bank_mask:0xf
	v_pk_fma_f32 v[26:27], v[58:59], v[16:17], v[26:27]
	v_cndmask_b32_e64 v31, v103, v31, s[8:9]
	v_cndmask_b32_e64 v30, v102, v30, s[8:9]
	v_cvt_pk_bf16_f32 v12, v12, v13
	v_cndmask_b32_e64 v25, v25, v120, s[10:11]
	v_cndmask_b32_e64 v24, v24, v119, s[10:11]
	v_pk_fma_f32 v[26:27], v[50:51], v[30:31], v[26:27]
	v_mov_b32_dpp v13, v52 row_ror:15 row_mask:0xf bank_mask:0xf
	v_mov_b32_dpp v28, v53 row_ror:15 row_mask:0xf bank_mask:0xf
	v_pk_mul_f32 v[24:25], v[60:61], v[24:25]
	v_pk_add_f32 v[26:27], v[46:47], v[26:27]
	v_pk_fma_f32 v[24:25], v[56:57], v[18:19], v[24:25]
	v_cndmask_b32_e64 v29, v101, v28, s[8:9]
	v_cndmask_b32_e64 v28, v100, v13, s[8:9]
	v_mul_f32_e32 v13, 0xbfb8aa3b, v27
	v_pk_fma_f32 v[24:25], v[48:49], v[28:29], v[24:25]
	v_exp_f32_e32 v13, v13
	v_mul_f32_e32 v28, 0xbfb8aa3b, v26
	v_exp_f32_e32 v28, v28
	v_pk_add_f32 v[24:25], v[44:45], v[24:25]
	v_add_f32_e32 v13, 1.0, v13
	v_rcp_f32_e32 v29, v13
	v_add_f32_e32 v13, 1.0, v28
	v_mul_f32_e32 v28, 0xbfb8aa3b, v25
	v_exp_f32_e32 v30, v28
	v_mul_f32_e32 v28, 0xbfb8aa3b, v24
	v_exp_f32_e32 v33, v28
	v_rcp_f32_e32 v28, v13
	v_add_f32_e32 v13, 1.0, v30
	v_rcp_f32_e32 v31, v13
	v_add_f32_e32 v13, 1.0, v33
	v_rcp_f32_e32 v30, v13
	v_cvt_pk_bf16_f32 v13, v14, v15
	v_pk_mul_f32 v[14:15], v[26:27], v[28:29]
	s_nop 0
	v_pk_mul_f32 v[10:11], v[10:11], v[14:15]
	v_pk_mul_f32 v[14:15], v[24:25], v[30:31]
	s_nop 0
	v_pk_mul_f32 v[8:9], v[8:9], v[14:15]
	v_cvt_pk_bf16_f32 v15, v10, v11
	v_cvt_pk_bf16_f32 v14, v8, v9
	v_add_u32_e32 v8, 0xa0, v205
	v_mad_i64_i32 v[8:9], s[12:13], v8, s38, v[172:173]
	global_store_dwordx4 v[8:9], v[12:15], off
	v_cndmask_b32_e64 v9, 0, 1, s[52:53]
	v_mov_b32_e32 v8, 0
	v_cmp_ne_u32_e64 s[12:13], 1, v9
	v_mov_b32_e32 v12, 0
	v_mov_b32_e32 v13, 0
	v_mov_b32_e32 v14, 0
	v_mov_b32_e32 v15, 0
	s_cbranch_vccnz .LBB0_857
	ds_read_b128 v[12:15], v32 offset:1024
; #define LAS __attribute__((address_space(3)))
;     __device__ __forceinline__ void operator()(const f32x4 (&acc_c)[2][2][4][2], const pg8::Unit& u, int wr, int wc, int fr, int fq) const {
;     ...
;         for (int ai = 0; ai < 2; ++ai)
; #pragma unroll
;             for (int m = 0; m < 4; ++m) { const int rl = ai * 128 + wr * 64 + m * 16 + fr;
;                 const float rstd = __builtin_amdgcn_rsqf(rsq[rl] * (1.0f / D_MODEL) + EPS);
; #pragma unroll
;                 for (int bj = 0; bj < 2; ++bj)
; #pragma unroll
;                     for (int n = 0; n < 2; ++n) acc[ai][bj][m][n] = acc[ai][bj][m][n] * rstd + *(const LAS f32x4*)(bias2 + bj * 128 + cl + 4 * n); }
;         f32x4 w0[2], w1[2], w2[2], cbv[2];
; #pragma unroll
;         for (int n = 0; n < 2; ++n) { w0[n] = *(const f32x4*)(cw + ch0 + 4 * n); w1[n] = *(const f32x4*)(cw + FFN + ch0 + 4 * n); w2[n] = *(const f32x4*)(cw + 2 * FFN + ch0 + 4 * n); cbv[n] = *(const f32x4*)(cb + ch0 + 4 * n); }
; #pragma unroll
;         for (int ai = 0; ai < 2; ++ai) { const int bi = 2 * ai + wr;
;             if (fr == 0) {
; #pragma unroll
;                 for (int n = 0; n < 2; ++n) *(LAS f32x4*)(X + (bi * 2 + 0) * 128 + cl + 4 * n) = acc[ai][0][0][n]; }
;             if (fr == 15) {
; #pragma unroll
;                 for (int n = 0; n < 2; ++n) *(LAS f32x4*)(X + (bi * 2 + 1) * 128 + cl + 4 * n) = acc[ai][0][3][n]; } }
;         asm volatile("s_waitcnt lgkmcnt(0)" ::: "memory"); __builtin_amdgcn_s_barrier(); asm volatile("" ::: "memory");
; #pragma unroll
;         for (int ai = 0; ai < 2; ++ai) { const int bi = 2 * ai + wr;
; #pragma unroll
;             for (int m = 0; m < 4; ++m) { u32x4 o;
; #pragma unroll
;                 for (int n = 0; n < 2; ++n) { const f32x4 cur = acc[ai][0][m][n];
;                     f32x4 pu, nd;
;                     if (m > 0) pu = ror1_4(acc[ai][0][m > 0 ? m - 1 : 0][n]); else pu = (bi > 0) ? *(const LAS f32x4*)(X + ((bi - 1) * 2 + 1) * 128 + cl + 4 * n) : (f32x4){0.f, 0.f, 0.f, 0.f};
;                     if (m < 3) nd = rol1_4(acc[ai][0][m < 3 ? m + 1 : 3][n]); else nd = (bi < 3) ? *(const LAS f32x4*)(X + ((bi + 1) * 2 + 0) * 128 + cl + 4 * n) : (f32x4){0.f, 0.f, 0.f, 0.f};
;                     const f32x4 ps = ror1_4(cur), ns = rol1_4(cur);
;                     const f32x4 prev = (fr > 0) ? ps : pu, next = (fr < 15) ? ns : nd;
.LBB0_857:
	v_mov_b32_dpp v24, v18 row_ror:1 row_mask:0xf bank_mask:0xf
	v_mov_b32_dpp v18, v19 row_ror:1 row_mask:0xf bank_mask:0xf
	v_mov_b32_dpp v19, v16 row_ror:1 row_mask:0xf bank_mask:0xf
	v_mov_b32_dpp v34, v64 row_ror:1 row_mask:0xf bank_mask:0xf
	v_mov_b32_dpp v81, v65 row_ror:1 row_mask:0xf bank_mask:0xf
	v_mov_b32_dpp v35, v66 row_ror:1 row_mask:0xf bank_mask:0xf
	v_mov_b32_dpp v82, v67 row_ror:1 row_mask:0xf bank_mask:0xf
	v_mov_b32_dpp v26, v64 row_ror:15 row_mask:0xf bank_mask:0xf
	v_mov_b32_dpp v29, v65 row_ror:15 row_mask:0xf bank_mask:0xf
	v_mov_b32_dpp v27, v66 row_ror:15 row_mask:0xf bank_mask:0xf
	v_mov_b32_dpp v30, v67 row_ror:15 row_mask:0xf bank_mask:0xf
	v_mov_b32_dpp v16, v17 row_ror:1 row_mask:0xf bank_mask:0xf
	s_and_b64 vcc, exec, s[12:13]
	v_mov_b32_e32 v9, 0
	v_mov_b32_e32 v10, 0
	v_mov_b32_e32 v11, 0
	s_cbranch_vccnz .LBB0_859
	ds_read_b128 v[8:11], v32 offset:1040
.LBB0_859:
	v_mov_b32_e32 v32, v202
	v_mov_b32_e32 v33, v202
	v_pk_fma_f32 v[6:7], v[6:7], v[32:33], v[98:99]
	v_pk_fma_f32 v[2:3], v[2:3], v[32:33], v[94:95]
	s_movk_i32 s12, 0x4f
	v_pk_fma_f32 v[4:5], v[4:5], v[202:203], v[96:97]
	v_pk_fma_f32 v[0:1], v[0:1], v[202:203], v[92:93]
	v_mov_b32_dpp v32, v52 row_ror:1 row_mask:0xf bank_mask:0xf
	v_mov_b32_dpp v33, v53 row_ror:1 row_mask:0xf bank_mask:0xf
	v_mov_b32_dpp v80, v54 row_ror:1 row_mask:0xf bank_mask:0xf
	v_mov_b32_dpp v83, v55 row_ror:1 row_mask:0xf bank_mask:0xf
	v_mov_b32_dpp v17, v52 row_ror:15 row_mask:0xf bank_mask:0xf
	v_mov_b32_dpp v25, v53 row_ror:15 row_mask:0xf bank_mask:0xf
	v_mov_b32_dpp v28, v54 row_ror:15 row_mask:0xf bank_mask:0xf
	v_mov_b32_dpp v31, v55 row_ror:15 row_mask:0xf bank_mask:0xf
	v_cmp_ne_u32_e32 vcc, s12, v192
	s_and_saveexec_b64 s[12:13], vcc
	s_cbranch_execz .LBB0_861
	v_cndmask_b32_e64 v89, v81, v22, s[10:11]
	v_cndmask_b32_e64 v23, v82, v23, s[10:11]
	v_cndmask_b32_e64 v22, v35, v21, s[10:11]
	v_cndmask_b32_e64 v88, v34, v20, s[10:11]
	v_pk_mul_f32 v[20:21], v[86:87], v[22:23]
	s_waitcnt lgkmcnt(0)
	v_cndmask_b32_e64 v15, v30, v15, s[8:9]
	v_pk_fma_f32 v[20:21], v[78:79], v[66:67], v[20:21]
	v_cndmask_b32_e64 v14, v27, v14, s[8:9]
	v_pk_fma_f32 v[14:15], v[74:75], v[14:15], v[20:21]
	v_pk_mul_f32 v[22:23], v[84:85], v[88:89]
	v_pk_add_f32 v[14:15], v[70:71], v[14:15]
	v_pk_fma_f32 v[22:23], v[76:77], v[64:65], v[22:23]
	v_mul_f32_e32 v20, 0xbfb8aa3b, v15
	v_cndmask_b32_e64 v13, v29, v13, s[8:9]
	v_cndmask_b32_e64 v12, v26, v12, s[8:9]
	v_exp_f32_e32 v20, v20
	v_mul_f32_e32 v21, 0xbfb8aa3b, v14
	v_pk_fma_f32 v[12:13], v[72:73], v[12:13], v[22:23]
	v_exp_f32_e32 v22, v21
	v_pk_add_f32 v[12:13], v[68:69], v[12:13]
	v_add_f32_e32 v20, 1.0, v20
	v_rcp_f32_e32 v21, v20
	v_add_f32_e32 v20, 1.0, v22
	v_mul_f32_e32 v22, 0xbfb8aa3b, v13
	v_exp_f32_e32 v22, v22
	v_mul_f32_e32 v23, 0xbfb8aa3b, v12
	v_exp_f32_e32 v26, v23
	v_rcp_f32_e32 v20, v20
	v_add_f32_e32 v22, 1.0, v22
	v_rcp_f32_e32 v23, v22
	v_add_f32_e32 v22, 1.0, v26
	v_rcp_f32_e32 v22, v22
	v_pk_mul_f32 v[14:15], v[14:15], v[20:21]
	v_cndmask_b32_e64 v9, v25, v9, s[8:9]
	v_pk_mul_f32 v[14:15], v[6:7], v[14:15]
	v_pk_mul_f32 v[12:13], v[12:13], v[22:23]
	v_cndmask_b32_e64 v8, v17, v8, s[8:9]
	v_pk_mul_f32 v[12:13], v[4:5], v[12:13]
	v_cndmask_b32_e64 v11, v31, v11, s[8:9]
	v_cvt_pk_bf16_f32 v12, v12, v13
	v_cvt_pk_bf16_f32 v13, v14, v15
	v_cndmask_b32_e64 v14, v80, v19, s[10:11]
	v_cndmask_b32_e64 v19, v33, v18, s[10:11]
	v_cndmask_b32_e64 v18, v32, v24, s[10:11]
	v_pk_mul_f32 v[18:19], v[60:61], v[18:19]
	v_cndmask_b32_e64 v15, v83, v16, s[10:11]
	v_pk_fma_f32 v[18:19], v[56:57], v[52:53], v[18:19]
	v_pk_mul_f32 v[14:15], v[62:63], v[14:15]
	v_pk_fma_f32 v[8:9], v[48:49], v[8:9], v[18:19]
	v_pk_fma_f32 v[14:15], v[58:59], v[54:55], v[14:15]
	v_cndmask_b32_e64 v10, v28, v10, s[8:9]
	v_pk_add_f32 v[8:9], v[44:45], v[8:9]
	v_pk_fma_f32 v[10:11], v[50:51], v[10:11], v[14:15]
	v_mul_f32_e32 v14, 0xbfb8aa3b, v8
	v_mul_f32_e32 v15, 0xbfb8aa3b, v9
	v_exp_f32_e32 v14, v14
	v_exp_f32_e32 v15, v15
	v_pk_add_f32 v[10:11], v[46:47], v[10:11]
	v_add_f32_e32 v14, 1.0, v14
	v_mul_f32_e32 v16, 0xbfb8aa3b, v10
	v_mul_f32_e32 v17, 0xbfb8aa3b, v11
	v_exp_f32_e32 v16, v16
	v_exp_f32_e32 v17, v17
	v_add_f32_e32 v15, 1.0, v15
	v_rcp_f32_e32 v14, v14
	v_rcp_f32_e32 v15, v15
	v_add_f32_e32 v16, 1.0, v16
	v_add_f32_e32 v17, 1.0, v17
	v_rcp_f32_e32 v16, v16
	v_rcp_f32_e32 v17, v17
	v_pk_mul_f32 v[8:9], v[8:9], v[14:15]
	s_nop 0
	v_pk_mul_f32 v[8:9], v[0:1], v[8:9]
	s_nop 0
	v_cvt_pk_bf16_f32 v14, v8, v9
	v_pk_mul_f32 v[8:9], v[10:11], v[16:17]
	s_nop 0
	v_pk_mul_f32 v[8:9], v[2:3], v[8:9]
	s_nop 0
	v_cvt_pk_bf16_f32 v15, v8, v9
	v_add_u32_e32 v8, 0xb0, v205
	v_mad_i64_i32 v[8:9], s[40:41], v8, s38, v[172:173]
	global_store_dwordx4 v[8:9], v[12:15], off

;     __device__ __forceinline__ void operator()(const f32x4 (&acc_c)[2][2][4][2], const pg8::Unit& u, int wr, int wc, int fr, int fq) const {
;     ...
; #pragma unroll
;         for (int m = 0; m < 4; ++m) { const int rl = half * 128 + wr * 64 + m * 16 + fr;
;             const float rstd = __builtin_amdgcn_rsqf(rsq[rl] * (1.0f / D_MODEL) + EPS);
; #pragma unroll
;             for (int bj = 0; bj < 2; ++bj)
; #pragma unroll
;                 for (int n = 0; n < 2; ++n) acc[0][bj][m][n] = acc[0][bj][m][n] * rstd + *(const LAS f32x4*)(bias2 + bj * 128 + cl + 4 * n); }
;         f32x4 w0[2], w1[2], w2[2], cbv[2];
; #pragma unroll
;         for (int n = 0; n < 2; ++n) { w0[n] = *(const f32x4*)(cw + ch0 + 4 * n); w1[n] = *(const f32x4*)(cw + FFN + ch0 + 4 * n); w2[n] = *(const f32x4*)(cw + 2 * FFN + ch0 + 4 * n); cbv[n] = *(const f32x4*)(cb + ch0 + 4 * n); }
;         { const int bi = wr;
;             if (fr == 0) {
; #pragma unroll
;                 for (int n = 0; n < 2; ++n) *(LAS f32x4*)(X + (bi * 2 + 0) * 128 + cl + 4 * n) = acc[0][0][0][n]; }
;             if (fr == 15) {
; #pragma unroll
;                 for (int n = 0; n < 2; ++n) *(LAS f32x4*)(X + (bi * 2 + 1) * 128 + cl + 4 * n) = acc[0][0][3][n]; } }
;         asm volatile("s_waitcnt lgkmcnt(0)" ::: "memory"); __builtin_amdgcn_s_barrier(); asm volatile("" ::: "memory");
;         { const int bi = wr;
; #pragma unroll
;             for (int m = 0; m < 4; ++m) { u32x4 o;
; #pragma unroll
;                 for (int n = 0; n < 2; ++n) { const f32x4 cur = acc[0][0][m][n];
;                     f32x4 pu, nd;
;                     if (m > 0) pu = ror1_4(acc[0][0][m > 0 ? m - 1 : 0][n]); else pu = (bi > 0) ? *(const LAS f32x4*)(X + ((bi - 1) * 2 + 1) * 128 + cl + 4 * n) : (f32x4){0.f, 0.f, 0.f, 0.f};
;                     if (m < 3) nd = rol1_4(acc[0][0][m < 3 ? m + 1 : 3][n]); else nd = (bi < 1) ? *(const LAS f32x4*)(X + ((bi + 1) * 2 + 0) * 128 + cl + 4 * n) : (f32x4){0.f, 0.f, 0.f, 0.f};
;                     const f32x4 ps = ror1_4(cur), ns = rol1_4(cur);
;                     const f32x4 prev = (fr > 0) ? ps : pu, next = (fr < 15) ? ns : nd;
;                     const f32x4 uu = w0[n] * prev + w1[n] * cur + w2[n] * next + cbv[n]; const f32x4 gt = acc[0][1][m][n];
;                     f32x4 r; r.x = siluf_(uu.x) * gt.x; r.y = siluf_(uu.y) * gt.y; r.z = siluf_(uu.z) * gt.z; r.w = siluf_(uu.w) * gt.w;
.LBB0_899:
	v_mov_b32_e32 v146, v128
	v_mov_b32_e32 v147, v128
	v_pk_fma_f32 v[40:41], v[40:41], v[128:129], v[92:93]
	v_pk_fma_f32 v[48:49], v[48:49], v[128:129], v[88:89]
	v_mov_b32_e32 v128, v130
	v_mov_b32_e32 v129, v130
	v_pk_fma_f32 v[42:43], v[42:43], v[146:147], v[94:95]
	v_or_b32_e32 v127, s13, v132
	v_lshl_add_u64 v[100:101], v[120:121], 1, s[14:15]
	s_mov_b64 s[10:11], 0x14342000
	v_pk_fma_f32 v[50:51], v[50:51], v[146:147], v[90:91]
	v_pk_fma_f32 v[98:99], v[98:99], v[128:129], v[106:107]
	v_pk_fma_f32 v[128:129], v[96:97], v[130:131], v[104:105]
	s_lshl_b32 s13, s3, 7
	v_lshl_add_u64 v[100:101], v[100:101], 0, s[10:11]
	v_mov_b32_dpp v96, v128 row_ror:15 row_mask:0xf bank_mask:0xf
	v_mov_b32_dpp v146, v129 row_ror:15 row_mask:0xf bank_mask:0xf
	v_mov_b32_dpp v147, v98 row_ror:15 row_mask:0xf bank_mask:0xf
	v_mov_b32_dpp v148, v99 row_ror:15 row_mask:0xf bank_mask:0xf
	v_mov_b32_dpp v152, v16 row_ror:1 row_mask:0xf bank_mask:0xf
	v_mov_b32_dpp v153, v17 row_ror:1 row_mask:0xf bank_mask:0xf
	v_mov_b32_dpp v154, v18 row_ror:1 row_mask:0xf bank_mask:0xf
	v_mov_b32_dpp v155, v19 row_ror:1 row_mask:0xf bank_mask:0xf
	v_mov_b32_dpp v149, v16 row_ror:15 row_mask:0xf bank_mask:0xf
	v_mov_b32_dpp v150, v17 row_ror:15 row_mask:0xf bank_mask:0xf
	v_mov_b32_dpp v151, v18 row_ror:15 row_mask:0xf bank_mask:0xf
	v_mov_b32_dpp v97, v19 row_ror:15 row_mask:0xf bank_mask:0xf
	v_cmp_ne_u32_e32 vcc, 0, v127
	s_and_saveexec_b64 s[10:11], vcc
	s_xor_b64 s[10:11], exec, s[10:11]
	s_cbranch_execz .LBB0_901
	s_waitcnt lgkmcnt(0)
	v_cndmask_b32_e64 v119, v145, v119, s[8:9]
	v_cndmask_b32_e64 v118, v143, v118, s[8:9]
	s_waitcnt vmcnt(0)
	v_pk_mul_f32 v[118:119], v[58:59], v[118:119]
	v_cndmask_b32_e64 v143, v140, v136, s[6:7]
	v_pk_fma_f32 v[118:119], v[22:23], v[66:67], v[118:119]
	v_cndmask_b32_e64 v137, v141, v137, s[6:7]
	v_cndmask_b32_e64 v136, v139, v135, s[6:7]
	v_pk_fma_f32 v[118:119], v[54:55], v[136:137], v[118:119]
	v_cndmask_b32_e64 v116, v142, v116, s[8:9]
	v_pk_add_f32 v[118:119], v[46:47], v[118:119]
	v_cndmask_b32_e64 v142, v138, v134, s[6:7]
	v_mul_f32_e32 v134, 0xbfb8aa3b, v119
	v_cndmask_b32_e64 v117, v144, v117, s[8:9]
	v_exp_f32_e32 v134, v134
	v_mul_f32_e32 v135, 0xbfb8aa3b, v118
	v_pk_mul_f32 v[116:117], v[56:57], v[116:117]
	v_exp_f32_e32 v136, v135
	v_pk_fma_f32 v[116:117], v[20:21], v[64:65], v[116:117]
	v_add_f32_e32 v134, 1.0, v134
	v_pk_fma_f32 v[116:117], v[52:53], v[142:143], v[116:117]
	v_rcp_f32_e32 v135, v134
	v_pk_add_f32 v[116:117], v[44:45], v[116:117]
	v_add_f32_e32 v134, 1.0, v136
	v_mul_f32_e32 v136, 0xbfb8aa3b, v117
	v_exp_f32_e32 v136, v136
	v_mul_f32_e32 v137, 0xbfb8aa3b, v116
	v_exp_f32_e32 v138, v137
	v_rcp_f32_e32 v134, v134
	v_add_f32_e32 v136, 1.0, v136
	v_rcp_f32_e32 v137, v136
	v_add_f32_e32 v136, 1.0, v138
	v_rcp_f32_e32 v136, v136
	v_pk_mul_f32 v[118:119], v[118:119], v[134:135]
	v_cndmask_b32_e64 v113, v153, v113, s[8:9]
	v_cndmask_b32_e64 v112, v152, v112, s[8:9]
	v_pk_mul_f32 v[116:117], v[116:117], v[136:137]
	v_pk_mul_f32 v[118:119], v[42:43], v[118:119]
	v_pk_mul_f32 v[116:117], v[40:41], v[116:117]
	v_cndmask_b32_e64 v115, v155, v115, s[8:9]
	v_cndmask_b32_e64 v114, v154, v114, s[8:9]
	v_pk_mul_f32 v[112:113], v[32:33], v[112:113]
	v_cvt_pk_bf16_f32 v116, v116, v117
	v_cvt_pk_bf16_f32 v117, v118, v119
	v_pk_mul_f32 v[114:115], v[34:35], v[114:115]
	v_pk_fma_f32 v[112:113], v[16:17], v[36:37], v[112:113]
	v_cndmask_b32_e64 v119, v97, v148, s[6:7]
	v_cndmask_b32_e64 v97, v150, v146, s[6:7]
	v_cndmask_b32_e64 v96, v149, v96, s[6:7]
	v_pk_fma_f32 v[114:115], v[18:19], v[38:39], v[114:115]
	v_cndmask_b32_e64 v118, v151, v147, s[6:7]
	v_pk_fma_f32 v[96:97], v[28:29], v[96:97], v[112:113]
	v_pk_fma_f32 v[112:113], v[30:31], v[118:119], v[114:115]
	v_pk_add_f32 v[96:97], v[24:25], v[96:97]
	v_pk_add_f32 v[112:113], v[26:27], v[112:113]
	v_mul_f32_e32 v114, 0xbfb8aa3b, v96
	v_mul_f32_e32 v115, 0xbfb8aa3b, v97
	v_exp_f32_e32 v114, v114
	v_exp_f32_e32 v115, v115
	v_mul_f32_e32 v118, 0xbfb8aa3b, v112
	v_exp_f32_e32 v118, v118
	v_mul_f32_e32 v119, 0xbfb8aa3b, v113
	v_exp_f32_e32 v119, v119
	v_add_f32_e32 v114, 1.0, v114
	v_add_f32_e32 v115, 1.0, v115
	v_rcp_f32_e32 v114, v114
	v_rcp_f32_e32 v115, v115
	v_add_f32_e32 v118, 1.0, v118
	v_rcp_f32_e32 v134, v118
	v_add_f32_e32 v118, 1.0, v119
	v_rcp_f32_e32 v135, v118
	v_pk_mul_f32 v[96:97], v[96:97], v[114:115]
	s_lshl_b32 s17, s12, 8
	v_pk_mul_f32 v[96:97], v[48:49], v[96:97]
	s_or_b32 s17, s17, s13
	v_cvt_pk_bf16_f32 v118, v96, v97
	v_pk_mul_f32 v[96:97], v[112:113], v[134:135]
	s_movk_i32 s18, 0x2c00
	v_pk_mul_f32 v[96:97], v[50:51], v[96:97]
	s_nop 0
	v_cvt_pk_bf16_f32 v119, v96, v97
	v_add_u32_e32 v96, s17, v127
	v_mad_i64_i32 v[96:97], s[18:19], v96, s18, v[100:101]
	global_store_dwordx4 v[96:97], v[116:119], off
;     __host__ __device__ bool next(int i, Unit& u) const { const long L = (long)i * G + c; if (L >= maxL) return false; return unit_of(L, u); }
; #define LAS __attribute__((address_space(3)))
; __device__ __forceinline__ unsigned pk2(float lo, float hi) { const f32x2_t v = {lo, hi}; const bf16x2_t b = __builtin_convertvector(v, bf16x2_t); return __builtin_bit_cast(unsigned, b); }
; __device__ __forceinline__ float siluf_(float x) { return x * __builtin_amdgcn_rcpf(1.0f + __expf(-x)); }
;     __device__ bool next(int i, pg8::Unit& u) const { if (!pg8::StaticOrder::next(i >> 1, u)) return false; u.br = i & 1; return true; }
; __device__ __forceinline__ f32x4 ror1_4(const f32x4 v) { return (f32x4){dpp_ror1(v.x), dpp_ror1(v.y), dpp_ror1(v.z), dpp_ror1(v.w)}; }
; __device__ __forceinline__ f32x4 rol1_4(const f32x4 v) { return (f32x4){dpp_rol1(v.x), dpp_rol1(v.y), dpp_rol1(v.z), dpp_rol1(v.w)}; }
;     __device__ __forceinline__ void operator()(const f32x4 (&acc_c)[2][2][4][2], const pg8::Unit& u, int wr, int wc, int fr, int fq) const {
;     ...
;             for (int m = 0; m < 4; ++m) { u32x4 o;
; #pragma unroll
;                 for (int n = 0; n < 2; ++n) { const f32x4 cur = acc[0][0][m][n];
;                     f32x4 pu, nd;
;                     if (m > 0) pu = ror1_4(acc[0][0][m > 0 ? m - 1 : 0][n]); else pu = (bi > 0) ? *(const LAS f32x4*)(X + ((bi - 1) * 2 + 1) * 128 + cl + 4 * n) : (f32x4){0.f, 0.f, 0.f, 0.f};
;                     if (m < 3) nd = rol1_4(acc[0][0][m < 3 ? m + 1 : 3][n]); else nd = (bi < 1) ? *(const LAS f32x4*)(X + ((bi + 1) * 2 + 0) * 128 + cl + 4 * n) : (f32x4){0.f, 0.f, 0.f, 0.f};
;                     const f32x4 ps = ror1_4(cur), ns = rol1_4(cur);
;                     const f32x4 prev = (fr > 0) ? ps : pu, next = (fr < 15) ? ns : nd;
;                     const f32x4 uu = w0[n] * prev + w1[n] * cur + w2[n] * next + cbv[n]; const f32x4 gt = acc[0][1][m][n];
;                     f32x4 r; r.x = siluf_(uu.x) * gt.x; r.y = siluf_(uu.y) * gt.y; r.z = siluf_(uu.z) * gt.z; r.w = siluf_(uu.w) * gt.w;
;                     if (n == 0) { o.x = pk2(r.x, r.y); o.y = pk2(r.z, r.w); } else { o.z = pk2(r.x, r.y); o.w = pk2(r.z, r.w); } }
;                 const int rh = wr * 64 + m * 16 + fr;
;                 if (rh != 0 && rh != 127) *(u32x4*)(ACT + (size_t)(u.pm * 256 + half * 128 + rh) * FFN + ch0) = o; } }
.LBB0_901:
	s_or_saveexec_b64 s[10:11], s[10:11]
	s_add_i32 s16, s16, 0x20000
	s_waitcnt lgkmcnt(0)
	v_mov_b32_e32 v112, s17
	s_xor_b64 exec, exec, s[10:11]
	s_lshl_b32 s17, s12, 8
	s_or_b32 s13, s13, s17
	v_mov_b32_e32 v112, s13
	s_or_b64 exec, exec, s[10:11]
	v_mov_b32_e32 v114, v130
	v_mov_b32_e32 v115, v130
	v_pk_fma_f32 v[116:117], v[78:79], v[114:115], v[94:95]
	v_mov_b32_e32 v78, 0x358637bd
	v_fmac_f32_e32 v78, 0x3a000000, v126
	v_rsq_f32_e32 v118, v78
	v_pk_fma_f32 v[134:135], v[76:77], v[130:131], v[92:93]
	v_pk_fma_f32 v[130:131], v[72:73], v[130:131], v[88:89]
	v_pk_fma_f32 v[114:115], v[74:75], v[114:115], v[90:91]
	v_pk_fma_f32 v[78:79], v[84:85], v[118:119], v[108:109] op_sel_hi:[1,0,1]
	v_pk_fma_f32 v[72:73], v[82:83], v[118:119], v[106:107] op_sel_hi:[1,0,1]
	v_mov_b32_dpp v82, v20 row_ror:1 row_mask:0xf bank_mask:0xf
	v_mov_b32_dpp v83, v21 row_ror:1 row_mask:0xf bank_mask:0xf
	v_mov_b32_dpp v107, v124 row_ror:1 row_mask:0xf bank_mask:0xf
	v_mov_b32_dpp v108, v125 row_ror:1 row_mask:0xf bank_mask:0xf
	v_pk_fma_f32 v[76:77], v[86:87], v[118:119], v[110:111] op_sel_hi:[1,0,1]
	v_pk_fma_f32 v[74:75], v[80:81], v[118:119], v[104:105] op_sel_hi:[1,0,1]
	v_cndmask_b32_e64 v83, v108, v83, s[8:9]
	v_cndmask_b32_e64 v82, v107, v82, s[8:9]
	v_mov_b32_dpp v80, v22 row_ror:1 row_mask:0xf bank_mask:0xf
	v_mov_b32_dpp v81, v23 row_ror:1 row_mask:0xf bank_mask:0xf
	v_mov_b32_dpp v97, v78 row_ror:15 row_mask:0xf bank_mask:0xf
	v_mov_b32_dpp v104, v79 row_ror:15 row_mask:0xf bank_mask:0xf
	v_mov_b32_dpp v109, v102 row_ror:1 row_mask:0xf bank_mask:0xf
	v_mov_b32_dpp v110, v103 row_ror:1 row_mask:0xf bank_mask:0xf
	v_mov_b32_dpp v86, v124 row_ror:15 row_mask:0xf bank_mask:0xf
	v_mov_b32_dpp v87, v125 row_ror:15 row_mask:0xf bank_mask:0xf
	s_waitcnt vmcnt(0)
	v_pk_mul_f32 v[82:83], v[56:57], v[82:83]
	v_cndmask_b32_e64 v81, v110, v81, s[8:9]
	v_cndmask_b32_e64 v80, v109, v80, s[8:9]
	v_pk_fma_f32 v[82:83], v[64:65], v[124:125], v[82:83]
	v_cndmask_b32_e64 v87, v87, v104, s[6:7]
	v_cndmask_b32_e64 v86, v86, v97, s[6:7]
	v_mov_b32_dpp v105, v76 row_ror:15 row_mask:0xf bank_mask:0xf
	v_mov_b32_dpp v106, v77 row_ror:15 row_mask:0xf bank_mask:0xf
	v_mov_b32_dpp v84, v102 row_ror:15 row_mask:0xf bank_mask:0xf
	v_mov_b32_dpp v85, v103 row_ror:15 row_mask:0xf bank_mask:0xf
	v_pk_mul_f32 v[80:81], v[58:59], v[80:81]
	v_pk_fma_f32 v[82:83], v[52:53], v[86:87], v[82:83]
	v_pk_fma_f32 v[80:81], v[66:67], v[102:103], v[80:81]
	v_cndmask_b32_e64 v85, v85, v106, s[6:7]
	v_cndmask_b32_e64 v84, v84, v105, s[6:7]
	v_pk_add_f32 v[82:83], v[44:45], v[82:83]
	v_pk_fma_f32 v[80:81], v[54:55], v[84:85], v[80:81]
	v_mul_f32_e32 v84, 0xbfb8aa3b, v82
	v_exp_f32_e32 v86, v84
	v_mul_f32_e32 v84, 0xbfb8aa3b, v83
	v_exp_f32_e32 v87, v84
	v_pk_add_f32 v[84:85], v[46:47], v[80:81]
	v_add_f32_e32 v80, 1.0, v86
	v_mul_f32_e32 v86, 0xbfb8aa3b, v84
	v_add_f32_e32 v81, 1.0, v87
	v_mul_f32_e32 v87, 0xbfb8aa3b, v85
	v_exp_f32_e32 v86, v86
	v_exp_f32_e32 v87, v87
	v_rcp_f32_e32 v80, v80
	v_rcp_f32_e32 v81, v81
	v_add_f32_e32 v86, 1.0, v86
	v_add_f32_e32 v87, 1.0, v87
	v_rcp_f32_e32 v86, v86
	v_rcp_f32_e32 v87, v87
	v_lshl_add_u32 v113, v123, 2, s16
	v_pk_fma_f32 v[70:71], v[70:71], v[118:119], v[94:95] op_sel_hi:[1,0,1]
	v_pk_fma_f32 v[68:69], v[68:69], v[118:119], v[92:93] op_sel_hi:[1,0,1]
	v_pk_fma_f32 v[62:63], v[62:63], v[118:119], v[90:91] op_sel_hi:[1,0,1]
	v_pk_fma_f32 v[60:61], v[60:61], v[118:119], v[88:89] op_sel_hi:[1,0,1]
	v_pk_mul_f32 v[80:81], v[82:83], v[80:81]
	v_pk_mul_f32 v[82:83], v[84:85], v[86:87]
	v_mov_b32_dpp v111, v16 row_ror:1 row_mask:0xf bank_mask:0xf
	v_mov_b32_dpp v118, v17 row_ror:1 row_mask:0xf bank_mask:0xf
	v_mov_b32_dpp v119, v18 row_ror:1 row_mask:0xf bank_mask:0xf
	v_mov_b32_dpp v123, v19 row_ror:1 row_mask:0xf bank_mask:0xf
	v_mov_b32_dpp v139, v128 row_ror:1 row_mask:0xf bank_mask:0xf
	v_mov_b32_dpp v140, v129 row_ror:1 row_mask:0xf bank_mask:0xf
	v_mov_b32_dpp v141, v98 row_ror:1 row_mask:0xf bank_mask:0xf
	v_mov_b32_dpp v142, v99 row_ror:1 row_mask:0xf bank_mask:0xf
	v_pk_mul_f32 v[80:81], v[134:135], v[80:81]
	v_pk_mul_f32 v[82:83], v[116:117], v[82:83]
	v_cvt_pk_bf16_f32 v80, v80, v81
	v_cvt_pk_bf16_f32 v81, v82, v83
	v_cndmask_b32_e64 v83, v142, v123, s[8:9]
	v_cndmask_b32_e64 v82, v141, v119, s[8:9]
	v_cndmask_b32_e64 v85, v140, v118, s[8:9]
	v_cndmask_b32_e64 v84, v139, v111, s[8:9]
	v_mov_b32_dpp v126, v74 row_ror:15 row_mask:0xf bank_mask:0xf
	v_mov_b32_dpp v136, v75 row_ror:15 row_mask:0xf bank_mask:0xf
	v_mov_b32_dpp v143, v128 row_ror:15 row_mask:0xf bank_mask:0xf
	v_mov_b32_dpp v144, v129 row_ror:15 row_mask:0xf bank_mask:0xf
	v_pk_mul_f32 v[84:85], v[32:33], v[84:85]
	v_pk_mul_f32 v[82:83], v[34:35], v[82:83]
	v_mov_b32_dpp v145, v98 row_ror:15 row_mask:0xf bank_mask:0xf
	v_mov_b32_dpp v146, v99 row_ror:15 row_mask:0xf bank_mask:0xf
	v_pk_fma_f32 v[82:83], v[98:99], v[38:39], v[82:83]
	v_pk_fma_f32 v[84:85], v[128:129], v[36:37], v[84:85]
	v_cndmask_b32_e64 v99, v144, v136, s[6:7]
	v_cndmask_b32_e64 v98, v143, v126, s[6:7]
	v_mov_b32_dpp v137, v72 row_ror:15 row_mask:0xf bank_mask:0xf
	v_mov_b32_dpp v138, v73 row_ror:15 row_mask:0xf bank_mask:0xf
	v_pk_fma_f32 v[84:85], v[28:29], v[98:99], v[84:85]
	v_cndmask_b32_e64 v87, v146, v138, s[6:7]
;     __host__ __device__ bool next(int i, Unit& u) const { const long L = (long)i * G + c; if (L >= maxL) return false; return unit_of(L, u); }
; #define LAS __attribute__((address_space(3)))
; __device__ __forceinline__ unsigned pk2(float lo, float hi) { const f32x2_t v = {lo, hi}; const bf16x2_t b = __builtin_convertvector(v, bf16x2_t); return __builtin_bit_cast(unsigned, b); }
; __device__ __forceinline__ float siluf_(float x) { return x * __builtin_amdgcn_rcpf(1.0f + __expf(-x)); }
;     __device__ bool next(int i, pg8::Unit& u) const { if (!pg8::StaticOrder::next(i >> 1, u)) return false; u.br = i & 1; return true; }
; __device__ __forceinline__ f32x4 ror1_4(const f32x4 v) { return (f32x4){dpp_ror1(v.x), dpp_ror1(v.y), dpp_ror1(v.z), dpp_ror1(v.w)}; }
; __device__ __forceinline__ f32x4 rol1_4(const f32x4 v) { return (f32x4){dpp_rol1(v.x), dpp_rol1(v.y), dpp_rol1(v.z), dpp_rol1(v.w)}; }
;     __device__ __forceinline__ void operator()(const f32x4 (&acc_c)[2][2][4][2], const pg8::Unit& u, int wr, int wc, int fr, int fq) const {
;     ...
;             for (int m = 0; m < 4; ++m) { u32x4 o;
; #pragma unroll
;                 for (int n = 0; n < 2; ++n) { const f32x4 cur = acc[0][0][m][n];
;                     f32x4 pu, nd;
;                     if (m > 0) pu = ror1_4(acc[0][0][m > 0 ? m - 1 : 0][n]); else pu = (bi > 0) ? *(const LAS f32x4*)(X + ((bi - 1) * 2 + 1) * 128 + cl + 4 * n) : (f32x4){0.f, 0.f, 0.f, 0.f};
;                     if (m < 3) nd = rol1_4(acc[0][0][m < 3 ? m + 1 : 3][n]); else nd = (bi < 1) ? *(const LAS f32x4*)(X + ((bi + 1) * 2 + 0) * 128 + cl + 4 * n) : (f32x4){0.f, 0.f, 0.f, 0.f};
;                     const f32x4 ps = ror1_4(cur), ns = rol1_4(cur);
;                     const f32x4 prev = (fr > 0) ? ps : pu, next = (fr < 15) ? ns : nd;
;                     const f32x4 uu = w0[n] * prev + w1[n] * cur + w2[n] * next + cbv[n]; const f32x4 gt = acc[0][1][m][n];
;                     f32x4 r; r.x = siluf_(uu.x) * gt.x; r.y = siluf_(uu.y) * gt.y; r.z = siluf_(uu.z) * gt.z; r.w = siluf_(uu.w) * gt.w;
;                     if (n == 0) { o.x = pk2(r.x, r.y); o.y = pk2(r.z, r.w); } else { o.z = pk2(r.x, r.y); o.w = pk2(r.z, r.w); } }
;                 const int rh = wr * 64 + m * 16 + fr;
;                 if (rh != 0 && rh != 127) *(u32x4*)(ACT + (size_t)(u.pm * 256 + half * 128 + rh) * FFN + ch0) = o; } }
	v_cndmask_b32_e64 v86, v145, v137, s[6:7]
	v_pk_add_f32 v[84:85], v[24:25], v[84:85]
	v_pk_fma_f32 v[82:83], v[30:31], v[86:87], v[82:83]
	v_mul_f32_e32 v86, 0xbfb8aa3b, v84
	v_exp_f32_e32 v98, v86
	v_mul_f32_e32 v86, 0xbfb8aa3b, v85
	v_exp_f32_e32 v99, v86
	v_pk_add_f32 v[86:87], v[26:27], v[82:83]
	v_add_f32_e32 v82, 1.0, v98
	v_mul_f32_e32 v98, 0xbfb8aa3b, v86
	v_add_f32_e32 v83, 1.0, v99
	v_mul_f32_e32 v99, 0xbfb8aa3b, v87
	v_exp_f32_e32 v98, v98
	v_exp_f32_e32 v99, v99
	v_rcp_f32_e32 v82, v82
	v_rcp_f32_e32 v83, v83
	v_add_f32_e32 v98, 1.0, v98
	v_add_f32_e32 v99, 1.0, v99
	v_rcp_f32_e32 v98, v98
	v_rcp_f32_e32 v99, v99
	v_pk_mul_f32 v[82:83], v[84:85], v[82:83]
	s_movk_i32 s13, 0x2c00
	v_pk_mul_f32 v[82:83], v[130:131], v[82:83]
	v_pk_mul_f32 v[84:85], v[86:87], v[98:99]
	v_add_u32_e32 v98, v112, v127
	v_pk_mul_f32 v[84:85], v[114:115], v[84:85]
	v_cvt_pk_bf16_f32 v82, v82, v83
	v_cvt_pk_bf16_f32 v83, v84, v85
	v_add_u32_e32 v84, 16, v98
	v_mad_i64_i32 v[84:85], s[16:17], v84, s13, v[100:101]
	global_store_dwordx4 v[84:85], v[80:83], off
	s_nop 1
	v_mov_b32_dpp v81, v76 row_ror:1 row_mask:0xf bank_mask:0xf
	v_mov_b32_dpp v83, v77 row_ror:1 row_mask:0xf bank_mask:0xf
	v_mov_b32_dpp v80, v78 row_ror:1 row_mask:0xf bank_mask:0xf
	v_mov_b32_dpp v82, v79 row_ror:1 row_mask:0xf bank_mask:0xf
	v_cndmask_b32_e64 v85, v83, v110, s[8:9]
	v_cndmask_b32_e64 v84, v81, v109, s[8:9]
	v_mov_b32_dpp v103, v14 row_ror:15 row_mask:0xf bank_mask:0xf
	v_mov_b32_dpp v111, v15 row_ror:15 row_mask:0xf bank_mask:0xf
	v_cndmask_b32_e64 v87, v82, v108, s[8:9]
	v_cndmask_b32_e64 v86, v80, v107, s[8:9]
	v_pk_mul_f32 v[84:85], v[58:59], v[84:85]
	v_mov_b32_dpp v99, v12 row_ror:15 row_mask:0xf bank_mask:0xf
	v_mov_b32_dpp v102, v13 row_ror:15 row_mask:0xf bank_mask:0xf
	v_pk_mul_f32 v[86:87], v[56:57], v[86:87]
	v_pk_fma_f32 v[76:77], v[66:67], v[76:77], v[84:85]
	v_cndmask_b32_e64 v85, v106, v111, s[6:7]
	v_cndmask_b32_e64 v84, v105, v103, s[6:7]
	v_pk_fma_f32 v[78:79], v[64:65], v[78:79], v[86:87]
	v_cndmask_b32_e64 v87, v104, v102, s[6:7]
	v_cndmask_b32_e64 v86, v97, v99, s[6:7]
	v_pk_fma_f32 v[76:77], v[54:55], v[84:85], v[76:77]
	v_pk_fma_f32 v[78:79], v[52:53], v[86:87], v[78:79]
	v_pk_add_f32 v[76:77], v[46:47], v[76:77]
	v_pk_add_f32 v[78:79], v[44:45], v[78:79]
	v_mul_f32_e32 v86, 0xbfb8aa3b, v76
	v_mul_f32_e32 v87, 0xbfb8aa3b, v77
	v_mul_f32_e32 v84, 0xbfb8aa3b, v78
	v_mul_f32_e32 v85, 0xbfb8aa3b, v79
	v_exp_f32_e32 v86, v86
	v_exp_f32_e32 v87, v87
	v_exp_f32_e32 v84, v84
	v_exp_f32_e32 v85, v85
	v_add_f32_e32 v86, 1.0, v86
	v_add_f32_e32 v87, 1.0, v87
	v_add_f32_e32 v84, 1.0, v84
	v_add_f32_e32 v85, 1.0, v85
	v_rcp_f32_e32 v86, v86
	v_rcp_f32_e32 v87, v87
	v_rcp_f32_e32 v84, v84
	v_rcp_f32_e32 v85, v85
	v_pk_mul_f32 v[76:77], v[76:77], v[86:87]
	v_mov_b32_dpp v118, v74 row_ror:1 row_mask:0xf bank_mask:0xf
	v_mov_b32_dpp v119, v75 row_ror:1 row_mask:0xf bank_mask:0xf
	v_pk_mul_f32 v[78:79], v[78:79], v[84:85]
	v_pk_mul_f32 v[70:71], v[70:71], v[76:77]
	v_cndmask_b32_e64 v77, v119, v140, s[8:9]
	v_cndmask_b32_e64 v76, v118, v139, s[8:9]
	v_mov_b32_dpp v114, v8 row_ror:15 row_mask:0xf bank_mask:0xf
	v_mov_b32_dpp v115, v9 row_ror:15 row_mask:0xf bank_mask:0xf
	v_mov_b32_dpp v123, v72 row_ror:1 row_mask:0xf bank_mask:0xf
	v_mov_b32_dpp v124, v73 row_ror:1 row_mask:0xf bank_mask:0xf
	v_pk_mul_f32 v[68:69], v[68:69], v[78:79]
	v_pk_mul_f32 v[76:77], v[32:33], v[76:77]
	v_cvt_pk_bf16_f32 v68, v68, v69
	v_cvt_pk_bf16_f32 v69, v70, v71
	v_cndmask_b32_e64 v71, v124, v142, s[8:9]
	v_cndmask_b32_e64 v70, v123, v141, s[8:9]
	v_pk_fma_f32 v[76:77], v[36:37], v[74:75], v[76:77]
	v_cndmask_b32_e64 v85, v136, v115, s[6:7]
	v_cndmask_b32_e64 v84, v126, v114, s[6:7]
	v_mov_b32_dpp v116, v10 row_ror:15 row_mask:0xf bank_mask:0xf
	v_mov_b32_dpp v117, v11 row_ror:15 row_mask:0xf bank_mask:0xf
	v_pk_mul_f32 v[70:71], v[34:35], v[70:71]
	v_pk_fma_f32 v[76:77], v[28:29], v[84:85], v[76:77]
	v_pk_fma_f32 v[70:71], v[38:39], v[72:73], v[70:71]
	v_cndmask_b32_e64 v79, v138, v117, s[6:7]
	v_cndmask_b32_e64 v78, v137, v116, s[6:7]
	v_pk_add_f32 v[76:77], v[24:25], v[76:77]
	v_pk_fma_f32 v[70:71], v[30:31], v[78:79], v[70:71]
	v_mul_f32_e32 v78, 0xbfb8aa3b, v76
	v_exp_f32_e32 v84, v78
	v_mul_f32_e32 v78, 0xbfb8aa3b, v77
	v_exp_f32_e32 v85, v78
	v_pk_add_f32 v[78:79], v[26:27], v[70:71]
	v_add_f32_e32 v70, 1.0, v84
	v_mul_f32_e32 v84, 0xbfb8aa3b, v78
	v_add_f32_e32 v71, 1.0, v85
	v_mul_f32_e32 v85, 0xbfb8aa3b, v79
	v_exp_f32_e32 v84, v84
	v_exp_f32_e32 v85, v85
	v_rcp_f32_e32 v70, v70
	v_rcp_f32_e32 v71, v71
	v_add_f32_e32 v84, 1.0, v84
	v_add_f32_e32 v85, 1.0, v85
	v_rcp_f32_e32 v84, v84
	v_rcp_f32_e32 v85, v85
	v_pk_mul_f32 v[70:71], v[76:77], v[70:71]
	s_cmp_lt_i32 s4, 1
	v_pk_mul_f32 v[60:61], v[60:61], v[70:71]
	s_cselect_b64 s[10:11], -1, 0
	v_cvt_pk_bf16_f32 v70, v60, v61
	v_pk_mul_f32 v[60:61], v[78:79], v[84:85]
	v_mov_b32_e32 v96, 0
	v_pk_mul_f32 v[60:61], v[62:63], v[60:61]
	s_cmp_gt_i32 s4, 0
	v_cvt_pk_bf16_f32 v71, v60, v61
	v_add_u32_e32 v60, 32, v98
	v_mad_i64_i32 v[60:61], s[16:17], v60, s13, v[100:101]
	global_store_dwordx4 v[60:61], v[68:71], off
	v_mov_b32_e32 v60, 0
	v_mov_b32_e32 v61, 0
	v_mov_b32_e32 v62, 0
	v_mov_b32_e32 v63, 0
	s_cbranch_scc1 .LBB0_905
	ds_read_b128 v[60:63], v113 offset:1024

;     __host__ __device__ bool next(int i, Unit& u) const { const long L = (long)i * G + c; if (L >= maxL) return false; return unit_of(L, u); }
; #define LAS __attribute__((address_space(3)))
; __device__ __forceinline__ unsigned pk2(float lo, float hi) { const f32x2_t v = {lo, hi}; const bf16x2_t b = __builtin_convertvector(v, bf16x2_t); return __builtin_bit_cast(unsigned, b); }
; __device__ __forceinline__ float siluf_(float x) { return x * __builtin_amdgcn_rcpf(1.0f + __expf(-x)); }
;     __device__ bool next(int i, pg8::Unit& u) const { if (!pg8::StaticOrder::next(i >> 1, u)) return false; u.br = i & 1; return true; }
; __device__ __forceinline__ f32x4 ror1_4(const f32x4 v) { return (f32x4){dpp_ror1(v.x), dpp_ror1(v.y), dpp_ror1(v.z), dpp_ror1(v.w)}; }
; __device__ __forceinline__ f32x4 rol1_4(const f32x4 v) { return (f32x4){dpp_rol1(v.x), dpp_rol1(v.y), dpp_rol1(v.z), dpp_rol1(v.w)}; }
;     __device__ __forceinline__ void operator()(const f32x4 (&acc_c)[2][2][4][2], const pg8::Unit& u, int wr, int wc, int fr, int fq) const {
;     ...
;             for (int m = 0; m < 4; ++m) { u32x4 o;
; #pragma unroll
;                 for (int n = 0; n < 2; ++n) { const f32x4 cur = acc[0][0][m][n];
;                     f32x4 pu, nd;
;                     if (m > 0) pu = ror1_4(acc[0][0][m > 0 ? m - 1 : 0][n]); else pu = (bi > 0) ? *(const LAS f32x4*)(X + ((bi - 1) * 2 + 1) * 128 + cl + 4 * n) : (f32x4){0.f, 0.f, 0.f, 0.f};
;                     if (m < 3) nd = rol1_4(acc[0][0][m < 3 ? m + 1 : 3][n]); else nd = (bi < 1) ? *(const LAS f32x4*)(X + ((bi + 1) * 2 + 0) * 128 + cl + 4 * n) : (f32x4){0.f, 0.f, 0.f, 0.f};
;                     const f32x4 ps = ror1_4(cur), ns = rol1_4(cur);
;                     const f32x4 prev = (fr > 0) ? ps : pu, next = (fr < 15) ? ns : nd;
;                     const f32x4 uu = w0[n] * prev + w1[n] * cur + w2[n] * next + cbv[n]; const f32x4 gt = acc[0][1][m][n];
;                     f32x4 r; r.x = siluf_(uu.x) * gt.x; r.y = siluf_(uu.y) * gt.y; r.z = siluf_(uu.z) * gt.z; r.w = siluf_(uu.w) * gt.w;
;                     if (n == 0) { o.x = pk2(r.x, r.y); o.y = pk2(r.z, r.w); } else { o.z = pk2(r.x, r.y); o.w = pk2(r.z, r.w); } }
;                 const int rh = wr * 64 + m * 16 + fr;
;                 if (rh != 0 && rh != 127) *(u32x4*)(ACT + (size_t)(u.pm * 256 + half * 128 + rh) * FFN + ch0) = o; } }
.LBB0_907:
	v_mov_b32_e32 v72, v122
	v_mov_b32_e32 v73, v122
	v_pk_fma_f32 v[6:7], v[6:7], v[72:73], v[94:95]
	v_pk_fma_f32 v[2:3], v[2:3], v[72:73], v[90:91]
	v_pk_fma_f32 v[0:1], v[0:1], v[122:123], v[88:89]
	s_movk_i32 s10, 0x4f
	v_pk_fma_f32 v[4:5], v[4:5], v[122:123], v[92:93]
	v_mov_b32_dpp v84, v8 row_ror:1 row_mask:0xf bank_mask:0xf
	v_mov_b32_dpp v87, v9 row_ror:1 row_mask:0xf bank_mask:0xf
	v_mov_b32_dpp v88, v10 row_ror:1 row_mask:0xf bank_mask:0xf
	v_mov_b32_dpp v89, v11 row_ror:1 row_mask:0xf bank_mask:0xf
	v_mov_b32_dpp v73, v8 row_ror:15 row_mask:0xf bank_mask:0xf
	v_mov_b32_dpp v74, v9 row_ror:15 row_mask:0xf bank_mask:0xf
	v_mov_b32_dpp v75, v10 row_ror:15 row_mask:0xf bank_mask:0xf
	v_mov_b32_dpp v72, v11 row_ror:15 row_mask:0xf bank_mask:0xf
	v_cmp_ne_u32_e32 vcc, s10, v127
	s_and_saveexec_b64 s[10:11], vcc
	s_cbranch_execz .LBB0_909
	v_cndmask_b32_e64 v91, v102, v82, s[8:9]
	v_cndmask_b32_e64 v83, v103, v83, s[8:9]
	v_cndmask_b32_e64 v82, v86, v81, s[8:9]
	v_pk_mul_f32 v[58:59], v[58:59], v[82:83]
	s_waitcnt lgkmcnt(0)
	v_cndmask_b32_e64 v63, v79, v63, s[6:7]
	v_pk_fma_f32 v[58:59], v[66:67], v[14:15], v[58:59]
	v_cndmask_b32_e64 v62, v77, v62, s[6:7]
	v_pk_fma_f32 v[54:55], v[54:55], v[62:63], v[58:59]
	v_cndmask_b32_e64 v90, v85, v80, s[8:9]
	v_pk_add_f32 v[46:47], v[46:47], v[54:55]
	v_pk_mul_f32 v[56:57], v[56:57], v[90:91]
	v_mul_f32_e32 v54, 0xbfb8aa3b, v47
	v_exp_f32_e32 v54, v54
	v_mul_f32_e32 v55, 0xbfb8aa3b, v46
	v_pk_fma_f32 v[56:57], v[64:65], v[12:13], v[56:57]
	v_cndmask_b32_e64 v61, v78, v61, s[6:7]
	v_cndmask_b32_e64 v60, v76, v60, s[6:7]
	v_exp_f32_e32 v55, v55
	v_pk_fma_f32 v[52:53], v[52:53], v[60:61], v[56:57]
	s_nop 0
	v_pk_add_f32 v[44:45], v[44:45], v[52:53]
	v_add_f32_e32 v52, 1.0, v54
	v_mul_f32_e32 v54, 0xbfb8aa3b, v45
	v_rcp_f32_e32 v53, v52
	v_add_f32_e32 v52, 1.0, v55
	v_exp_f32_e32 v54, v54
	v_mul_f32_e32 v55, 0xbfb8aa3b, v44
	v_exp_f32_e32 v56, v55
	v_rcp_f32_e32 v52, v52
	v_add_f32_e32 v54, 1.0, v54
	v_rcp_f32_e32 v55, v54
	v_add_f32_e32 v54, 1.0, v56
	v_rcp_f32_e32 v54, v54
	v_pk_mul_f32 v[46:47], v[46:47], v[52:53]
	v_cndmask_b32_e64 v53, v87, v69, s[8:9]
	v_pk_mul_f32 v[46:47], v[6:7], v[46:47]
	v_pk_mul_f32 v[44:45], v[44:45], v[54:55]
	v_cndmask_b32_e64 v52, v84, v68, s[8:9]
	v_pk_mul_f32 v[44:45], v[4:5], v[44:45]
	v_pk_mul_f32 v[32:33], v[32:33], v[52:53]
	v_cvt_pk_bf16_f32 v44, v44, v45
	v_cvt_pk_bf16_f32 v45, v46, v47
	v_cndmask_b32_e64 v47, v89, v71, s[8:9]
	v_cndmask_b32_e64 v46, v88, v70, s[8:9]
	v_pk_mul_f32 v[34:35], v[34:35], v[46:47]
	v_pk_fma_f32 v[32:33], v[36:37], v[8:9], v[32:33]
	v_pk_fma_f32 v[34:35], v[38:39], v[10:11], v[34:35]
	v_cndmask_b32_e64 v39, v74, v97, s[6:7]
	v_cndmask_b32_e64 v38, v73, v96, s[6:7]
	v_pk_fma_f32 v[28:29], v[28:29], v[38:39], v[32:33]
	v_cndmask_b32_e64 v37, v72, v99, s[6:7]
	v_cndmask_b32_e64 v36, v75, v98, s[6:7]
	v_pk_add_f32 v[24:25], v[24:25], v[28:29]
	v_pk_fma_f32 v[30:31], v[30:31], v[36:37], v[34:35]
	v_mul_f32_e32 v28, 0xbfb8aa3b, v24
	v_mul_f32_e32 v29, 0xbfb8aa3b, v25
	v_exp_f32_e32 v28, v28
	v_exp_f32_e32 v29, v29
	v_pk_add_f32 v[26:27], v[26:27], v[30:31]
	v_add_f32_e32 v28, 1.0, v28
	v_mul_f32_e32 v30, 0xbfb8aa3b, v26
	v_mul_f32_e32 v31, 0xbfb8aa3b, v27
	v_exp_f32_e32 v30, v30
	v_exp_f32_e32 v31, v31
	v_add_f32_e32 v29, 1.0, v29
	v_rcp_f32_e32 v28, v28
	v_rcp_f32_e32 v29, v29
	v_add_f32_e32 v30, 1.0, v30
	v_add_f32_e32 v31, 1.0, v31
	v_rcp_f32_e32 v30, v30
	v_rcp_f32_e32 v31, v31
	v_pk_mul_f32 v[24:25], v[24:25], v[28:29]
	s_nop 0
	v_pk_mul_f32 v[24:25], v[0:1], v[24:25]
	s_nop 0
	v_cvt_pk_bf16_f32 v46, v24, v25
	v_pk_mul_f32 v[24:25], v[26:27], v[30:31]
	s_nop 0
	v_pk_mul_f32 v[24:25], v[2:3], v[24:25]
	s_nop 0
	v_cvt_pk_bf16_f32 v47, v24, v25
	v_add3_u32 v24, v112, v127, 48
	v_mad_i64_i32 v[24:25], s[16:17], v24, s13, v[100:101]
	global_store_dwordx4 v[24:25], v[44:47], off

; __global__ void __launch_bounds__(NTHREADS, 2) mega_fwd(Params p_in) {
;     const int wave_id = __builtin_amdgcn_readfirstlane((int)(threadIdx.x >> 6));
;     extern __shared__ __attribute__((aligned(16))) unsigned char lds_raw[];
	.amdhsa_kernel _Z8mega_fwd6Params
		.amdhsa_group_segment_fixed_size 0
		.amdhsa_private_segment_fixed_size 0
		.amdhsa_kernarg_size 456
		.amdhsa_user_sgpr_count 2
		.amdhsa_user_sgpr_dispatch_ptr 0
		.amdhsa_user_sgpr_queue_ptr 0
		.amdhsa_user_sgpr_kernarg_segment_ptr 1
		.amdhsa_user_sgpr_dispatch_id 0
		.amdhsa_user_sgpr_kernarg_preload_length 0
		.amdhsa_user_sgpr_kernarg_preload_offset 0
		.amdhsa_user_sgpr_private_segment_size 0
		.amdhsa_uses_dynamic_stack 0
		.amdhsa_enable_private_segment 0
		.amdhsa_system_sgpr_workgroup_id_x 1
		.amdhsa_system_sgpr_workgroup_id_y 0
		.amdhsa_system_sgpr_workgroup_id_z 0
		.amdhsa_system_sgpr_workgroup_info 0
		.amdhsa_system_vgpr_workitem_id 0
		.amdhsa_next_free_vgpr 251
		.amdhsa_next_free_sgpr 102
		.amdhsa_accum_offset 252
		.amdhsa_reserve_vcc 1
		.amdhsa_float_round_mode_32 0
		.amdhsa_float_round_mode_16_64 0
		.amdhsa_float_denorm_mode_32 3
		.amdhsa_float_denorm_mode_16_64 3
		.amdhsa_dx10_clamp 1
		.amdhsa_ieee_mode 1
		.amdhsa_fp16_overflow 0
		.amdhsa_tg_split 0
		.amdhsa_exception_fp_ieee_invalid_op 0
		.amdhsa_exception_fp_denorm_src 0
		.amdhsa_exception_fp_ieee_div_zero 0
		.amdhsa_exception_fp_ieee_overflow 0
		.amdhsa_exception_fp_ieee_underflow 0
		.amdhsa_exception_fp_ieee_inexact 0
		.amdhsa_exception_int_div_zero 0
	.end_amdhsa_kernel

; __global__ void __launch_bounds__(NTHREADS, 2) mega_fwd(Params p_in) {
amdhsa.kernels:
  - .agpr_count:     0
    .args:
      - .offset:         0
        .size:           200
        .value_kind:     by_value
      - .offset:         200
        .size:           4
        .value_kind:     hidden_block_count_x
      - .offset:         204
        .size:           4
        .value_kind:     hidden_block_count_y
      - .offset:         208
        .size:           4
        .value_kind:     hidden_block_count_z
      - .offset:         212
        .size:           2
        .value_kind:     hidden_group_size_x
      - .offset:         214
        .size:           2
        .value_kind:     hidden_group_size_y
      - .offset:         216
        .size:           2
        .value_kind:     hidden_group_size_z
      - .offset:         218
        .size:           2
        .value_kind:     hidden_remainder_x
      - .offset:         220
        .size:           2
        .value_kind:     hidden_remainder_y
      - .offset:         222
        .size:           2
        .value_kind:     hidden_remainder_z
      - .offset:         240
        .size:           8
        .value_kind:     hidden_global_offset_x
      - .offset:         248
        .size:           8
        .value_kind:     hidden_global_offset_y
      - .offset:         256
        .size:           8
        .value_kind:     hidden_global_offset_z
      - .offset:         264
        .size:           2
        .value_kind:     hidden_grid_dims
      - .offset:         320
        .size:           4
        .value_kind:     hidden_dynamic_lds_size
    .group_segment_fixed_size: 0
    .kernarg_segment_align: 8
    .kernarg_segment_size: 456
    .language:       OpenCL C
    .language_version:
      - 2
      - 0
    .max_flat_workgroup_size: 512
    .name:           _Z8mega_fwd6Params
    .private_segment_fixed_size: 0
    .sgpr_count:     108
    .sgpr_spill_count: 14
    .symbol:         _Z8mega_fwd6Params.kd
    .uniform_work_group_size: 1
    .uses_dynamic_stack: false
    .vgpr_count:     251
    .vgpr_spill_count: 0
    .wavefront_size: 64
